# causal attention loop: sink AGPR->VGPR copies of O and S into the rare rescale/mask blocks, relax over-strict vmcnt waits to the true 2-tile prefetch distance
# speedup vs baseline: 1.2843x; 1.2843x over previous
; DI int crow(int reg, int h) { return (reg & 3) + 8 * (reg >> 2) + 4 * h; }
; template <int DQK>
; DI void attn_item_c(const u16* __restrict__ Qp, int ldq, const u16* __restrict__ Kp, const u16* __restrict__ Vtp, int ldv,
;                     int nkt, int q0, float c, u16* Yp, int ldy, char* smem, bool dry) {
;     ...
;   auto body = [&](int kt, u32x4* wk, u32x4* wv, f32x16& s0, f32x16& s1, f32x16& n0, f32x16& n1) {
;     const u16* Ks = L0 + (kt & 1) * BUFE;
;     const u16* Vs = Ks + 64 * KLD;
;     u16* Ln = L0 + ((kt + 1) & 1) * BUFE;
;     const bool active = !(kt * 64 > qmin + 31);
;     if (kt * 64 + 63 > qmin) {
; #pragma unroll
;       for (int e = 0; e < 16; ++e) {
;         int key = kt * 64 + crow(e, h);
;         if (key > qi) s0[e] = -INFINITY;
;         if (key + 32 > qi) s1[e] = -INFINITY;
;       }
;     }
.LBB0_208:
	s_lshl_b32 s45, s44, 6
	s_or_b32 s0, s45, 63
	v_cmp_gt_i32_e32 vcc, s0, v233
	s_and_saveexec_b64 s[46:47], vcc
	s_cbranch_execz .LBB0_212
	v_accvgpr_read_b32 v32, a64
	v_accvgpr_read_b32 v0, a80
	v_accvgpr_read_b32 v33, a65
	v_accvgpr_read_b32 v34, a66
	v_accvgpr_read_b32 v35, a67
	v_accvgpr_read_b32 v36, a68
	v_accvgpr_read_b32 v37, a69
	v_accvgpr_read_b32 v38, a70
	v_accvgpr_read_b32 v39, a71
	v_accvgpr_read_b32 v40, a72
	v_accvgpr_read_b32 v41, a73
	v_accvgpr_read_b32 v42, a74
	v_accvgpr_read_b32 v43, a75
	v_accvgpr_read_b32 v44, a76
	v_accvgpr_read_b32 v45, a77
	v_accvgpr_read_b32 v46, a78
	v_accvgpr_read_b32 v47, a79
	v_accvgpr_read_b32 v1, a81
	v_accvgpr_read_b32 v2, a82
	v_accvgpr_read_b32 v3, a83
	v_accvgpr_read_b32 v4, a84
	v_accvgpr_read_b32 v5, a85
	v_accvgpr_read_b32 v6, a86
	v_accvgpr_read_b32 v7, a87
	v_accvgpr_read_b32 v8, a88
	v_accvgpr_read_b32 v9, a89
	v_accvgpr_read_b32 v10, a90
	v_accvgpr_read_b32 v11, a91
	v_accvgpr_read_b32 v12, a92
	v_accvgpr_read_b32 v13, a93
	v_accvgpr_read_b32 v14, a94
	v_accvgpr_read_b32 v15, a95
	v_accvgpr_read_b32 v129, a237
	v_or_b32_e32 v129, s45, v129
	v_or_b32_e32 v146, 32, v129
	v_cmp_le_i32_e64 s[0:1], v146, v212
	v_or_b32_e32 v146, 33, v129
	v_mov_b32_e32 v147, 0xff800000
	v_cmp_le_i32_e64 s[6:7], v146, v212
	v_or_b32_e32 v146, 2, v129
	v_cmp_le_i32_e32 vcc, v129, v212
	v_cndmask_b32_e64 v33, v147, v33, s[6:7]
	v_cmp_le_i32_e64 s[6:7], v146, v212
	v_or_b32_e32 v146, 34, v129
	v_cmp_le_i32_e64 s[8:9], v146, v212
	v_or_b32_e32 v146, 3, v129
	v_cndmask_b32_e64 v32, v147, v32, s[0:1]
	v_cndmask_b32_e64 v34, v147, v34, s[8:9]
	v_cmp_le_i32_e64 s[8:9], v146, v212
	v_or_b32_e32 v146, 35, v129
	v_cmp_le_i32_e64 s[10:11], v146, v212
	v_or_b32_e32 v146, 8, v129
	v_cmp_lt_i32_e64 s[0:1], v129, v212
	v_cndmask_b32_e64 v35, v147, v35, s[10:11]
	v_cmp_le_i32_e64 s[10:11], v146, v212
	v_or_b32_e32 v146, 40, v129
	v_cmp_le_i32_e64 s[12:13], v146, v212
	v_or_b32_e32 v146, 9, v129
	s_nop 0
	v_cndmask_b32_e64 v36, v147, v36, s[12:13]
	v_cmp_le_i32_e64 s[12:13], v146, v212
	v_or_b32_e32 v146, 41, v129
	v_cmp_le_i32_e64 s[14:15], v146, v212
	v_or_b32_e32 v146, 10, v129
	s_nop 0
	v_cndmask_b32_e64 v37, v147, v37, s[14:15]
	v_cmp_le_i32_e64 s[14:15], v146, v212
	v_or_b32_e32 v146, 42, v129
	v_cmp_le_i32_e64 s[16:17], v146, v212
	v_or_b32_e32 v146, 11, v129
	s_nop 0
	v_cndmask_b32_e64 v38, v147, v38, s[16:17]
	v_cmp_le_i32_e64 s[16:17], v146, v212
	v_or_b32_e32 v146, 43, v129
	v_cmp_le_i32_e64 s[18:19], v146, v212
	v_or_b32_e32 v146, 16, v129
	s_nop 0
	v_cndmask_b32_e64 v39, v147, v39, s[18:19]
	v_cmp_le_i32_e64 s[18:19], v146, v212
	v_or_b32_e32 v146, 48, v129
	v_cmp_le_i32_e64 s[22:23], v146, v212
	v_or_b32_e32 v146, 17, v129
	s_nop 0
	v_cndmask_b32_e64 v40, v147, v40, s[22:23]
	v_cmp_le_i32_e64 s[22:23], v146, v212
	v_or_b32_e32 v146, 49, v129
	v_cmp_le_i32_e64 s[24:25], v146, v212
	v_or_b32_e32 v146, 18, v129
	s_nop 0
	v_cndmask_b32_e64 v41, v147, v41, s[24:25]
	v_cmp_le_i32_e64 s[24:25], v146, v212
	v_or_b32_e32 v146, 50, v129
	v_cmp_le_i32_e64 s[26:27], v146, v212
	v_or_b32_e32 v146, 19, v129
	s_nop 0
	v_cndmask_b32_e64 v42, v147, v42, s[26:27]
	v_cmp_le_i32_e64 s[26:27], v146, v212
	v_or_b32_e32 v146, 51, v129
	v_cmp_le_i32_e64 s[28:29], v146, v212
	v_or_b32_e32 v146, 24, v129
	s_nop 0
	v_cndmask_b32_e64 v43, v147, v43, s[28:29]
	v_cmp_le_i32_e64 s[28:29], v146, v212
	v_or_b32_e32 v146, 56, v129
	v_cmp_le_i32_e64 s[30:31], v146, v212
	v_or_b32_e32 v146, 25, v129
	s_nop 0
	v_cndmask_b32_e64 v44, v147, v44, s[30:31]
	v_cmp_le_i32_e64 s[30:31], v146, v212
	v_or_b32_e32 v146, 57, v129
	v_cmp_le_i32_e64 s[34:35], v146, v212
	v_or_b32_e32 v146, 26, v129
	s_nop 0
	v_cndmask_b32_e64 v45, v147, v45, s[34:35]
	v_cmp_le_i32_e64 s[34:35], v146, v212
	v_or_b32_e32 v146, 58, v129
	v_cmp_le_i32_e64 s[36:37], v146, v212
	v_or_b32_e32 v146, 27, v129
	v_or_b32_e32 v129, 59, v129
	v_cndmask_b32_e64 v46, v147, v46, s[36:37]
	v_cmp_le_i32_e64 s[36:37], v146, v212
	v_cmp_gt_i32_e64 s[40:41], v129, v212
	s_and_saveexec_b64 s[48:49], s[40:41]
	v_mov_b32_e32 v47, s65
	s_or_b64 exec, exec, s[48:49]
	v_accvgpr_write_b32 a79, v47
	v_accvgpr_write_b32 a78, v46
	v_accvgpr_write_b32 a77, v45
	v_accvgpr_write_b32 a76, v44
	v_accvgpr_write_b32 a75, v43
	v_accvgpr_write_b32 a74, v42
	v_accvgpr_write_b32 a73, v41
	v_accvgpr_write_b32 a72, v40
	v_accvgpr_write_b32 a71, v39
	v_accvgpr_write_b32 a70, v38
	v_accvgpr_write_b32 a69, v37
	v_accvgpr_write_b32 a68, v36
	v_accvgpr_write_b32 a67, v35
	v_accvgpr_write_b32 a66, v34
	v_accvgpr_write_b32 a65, v33
	v_accvgpr_write_b32 a64, v32
	v_mov_b32_e32 v32, 0xff800000
	v_cndmask_b32_e64 v1, v32, v1, s[0:1]
	v_cndmask_b32_e32 v0, v32, v0, vcc
	v_cndmask_b32_e64 v2, v32, v2, s[6:7]
	v_cndmask_b32_e64 v3, v32, v3, s[8:9]
	v_cndmask_b32_e64 v4, v32, v4, s[10:11]
	v_cndmask_b32_e64 v5, v32, v5, s[12:13]
	v_cndmask_b32_e64 v6, v32, v6, s[14:15]
	v_cndmask_b32_e64 v7, v32, v7, s[16:17]
	v_cndmask_b32_e64 v8, v32, v8, s[18:19]
	v_cndmask_b32_e64 v9, v32, v9, s[22:23]
	v_cndmask_b32_e64 v10, v32, v10, s[24:25]
	v_cndmask_b32_e64 v11, v32, v11, s[26:27]
	v_cndmask_b32_e64 v12, v32, v12, s[28:29]
	v_cndmask_b32_e64 v13, v32, v13, s[30:31]
	v_cndmask_b32_e64 v14, v32, v14, s[34:35]
	v_cndmask_b32_e64 v15, v32, v15, s[36:37]
	v_accvgpr_write_b32 a80, v0
	v_accvgpr_write_b32 a81, v1
	v_accvgpr_write_b32 a82, v2
	v_accvgpr_write_b32 a83, v3
	v_accvgpr_write_b32 a84, v4
	v_accvgpr_write_b32 a85, v5
	v_accvgpr_write_b32 a86, v6
	v_accvgpr_write_b32 a87, v7
	v_accvgpr_write_b32 a88, v8
	v_accvgpr_write_b32 a89, v9
	v_accvgpr_write_b32 a90, v10
	v_accvgpr_write_b32 a91, v11
	v_accvgpr_write_b32 a92, v12
	v_accvgpr_write_b32 a93, v13
	v_accvgpr_write_b32 a94, v14
	v_accvgpr_write_b32 a95, v15
	s_mov_b64 s[40:41], s[70:71]
; DI float ex2(float x) { return __builtin_amdgcn_exp2f(x); }
; template <int DQK>
; DI void attn_item_c(const u16* __restrict__ Qp, int ldq, const u16* __restrict__ Kp, const u16* __restrict__ Vtp, int ldv,
;                     int nkt, int q0, float c, u16* Yp, int ldy, char* smem, bool dry) {
;     ...
;     float mx = fmaxf(s0[0], s1[0]);
; #pragma unroll
;     for (int e = 1; e < 16; ++e) mx = fmaxf(fmaxf(mx, s0[e]), s1[e]);
;     mx = fmaxf(mx, __shfl_xor(mx, 32));
;     if (__builtin_amdgcn_ballot_w64((mx - m) * c > 8.f) != 0ull) {
;       const float mn = fmaxf(m, mx);
;       const float alpha = ex2((m - mn) * c);
;       m = mn;
;       l *= alpha;
; #pragma unroll
;       for (int dt = 0; dt < 4; ++dt)
; #pragma unroll
;         for (int e = 0; e < 16; ++e) o[dt][e] *= alpha;
;     }
.LBB0_212:
	s_or_b64 exec, exec, s[46:47]
	v_accvgpr_read_b32 v32, a80
	v_accvgpr_read_b32 v0, a64
	v_max_f32_e32 v129, v0, v0
	v_max_f32_e32 v146, v32, v32
	v_accvgpr_read_b32 v33, a81
	v_accvgpr_read_b32 v1, a65
	v_max_f32_e32 v129, v146, v129
	v_accvgpr_read_b32 v34, a82
	v_accvgpr_read_b32 v2, a66
	v_max3_f32 v129, v129, v33, v1
	v_accvgpr_read_b32 v35, a83
	v_accvgpr_read_b32 v3, a67
	v_max3_f32 v129, v129, v34, v2
	v_accvgpr_read_b32 v36, a84
	v_accvgpr_read_b32 v4, a68
	v_max3_f32 v129, v129, v35, v3
	v_accvgpr_read_b32 v37, a85
	v_accvgpr_read_b32 v5, a69
	v_max3_f32 v129, v129, v36, v4
	v_accvgpr_read_b32 v38, a86
	v_accvgpr_read_b32 v6, a70
	v_max3_f32 v129, v129, v37, v5
	v_accvgpr_read_b32 v39, a87
	v_accvgpr_read_b32 v7, a71
	v_max3_f32 v129, v129, v38, v6
	v_accvgpr_read_b32 v40, a88
	v_accvgpr_read_b32 v8, a72
	v_max3_f32 v129, v129, v39, v7
	v_accvgpr_read_b32 v41, a89
	v_accvgpr_read_b32 v9, a73
	v_max3_f32 v129, v129, v40, v8
	v_accvgpr_read_b32 v42, a90
	v_accvgpr_read_b32 v10, a74
	v_max3_f32 v129, v129, v41, v9
	v_accvgpr_read_b32 v43, a91
	v_accvgpr_read_b32 v11, a75
	v_max3_f32 v129, v129, v42, v10
	v_accvgpr_read_b32 v44, a92
	v_accvgpr_read_b32 v12, a76
	v_max3_f32 v129, v129, v43, v11
	v_accvgpr_read_b32 v45, a93
	v_accvgpr_read_b32 v13, a77
	v_max3_f32 v129, v129, v44, v12
	v_accvgpr_read_b32 v46, a94
	v_accvgpr_read_b32 v14, a78
	v_max3_f32 v129, v129, v45, v13
	v_accvgpr_read_b32 v47, a95
	v_accvgpr_read_b32 v15, a79
	v_max3_f32 v129, v129, v46, v14
	v_max3_f32 v129, v129, v47, v15
	ds_bpermute_b32 v146, v232, v129
	s_waitcnt lgkmcnt(0)
	v_max_f32_e32 v146, v146, v146
	v_max_f32_e32 v129, v129, v146
	v_sub_f32_e32 v146, v129, v216
	v_mul_f32_e32 v146, 0x3dd53b94, v146
	v_cmp_lt_f32_e32 vcc, s33, v146
	s_cbranch_vccz .LBB0_214
	v_accvgpr_read_b32 v16, a48
	v_accvgpr_read_b32 v63, a47
	v_accvgpr_read_b32 v79, a31
	v_accvgpr_read_b32 v95, a15
	v_accvgpr_read_b32 v17, a49
	v_accvgpr_read_b32 v18, a50
	v_accvgpr_read_b32 v19, a51
	v_accvgpr_read_b32 v20, a52
	v_accvgpr_read_b32 v21, a53
	v_accvgpr_read_b32 v22, a54
	v_accvgpr_read_b32 v23, a55
	v_accvgpr_read_b32 v24, a56
	v_accvgpr_read_b32 v25, a57
	v_accvgpr_read_b32 v26, a58
	v_accvgpr_read_b32 v27, a59
	v_accvgpr_read_b32 v28, a60
	v_accvgpr_read_b32 v29, a61
	v_accvgpr_read_b32 v30, a62
	v_accvgpr_read_b32 v31, a63
	v_accvgpr_read_b32 v62, a46
	v_accvgpr_read_b32 v61, a45
	v_accvgpr_read_b32 v60, a44
	v_accvgpr_read_b32 v59, a43
	v_accvgpr_read_b32 v58, a42
	v_accvgpr_read_b32 v57, a41
	v_accvgpr_read_b32 v56, a40
	v_accvgpr_read_b32 v55, a39
	v_accvgpr_read_b32 v54, a38
	v_accvgpr_read_b32 v53, a37
	v_accvgpr_read_b32 v52, a36
	v_accvgpr_read_b32 v51, a35
	v_accvgpr_read_b32 v50, a34
	v_accvgpr_read_b32 v49, a33
	v_accvgpr_read_b32 v48, a32
	v_accvgpr_read_b32 v78, a30
	v_accvgpr_read_b32 v77, a29
	v_accvgpr_read_b32 v76, a28
	v_accvgpr_read_b32 v75, a27
	v_accvgpr_read_b32 v74, a26
	v_accvgpr_read_b32 v73, a25
	v_accvgpr_read_b32 v72, a24
	v_accvgpr_read_b32 v71, a23
	v_accvgpr_read_b32 v70, a22
	v_accvgpr_read_b32 v69, a21
	v_accvgpr_read_b32 v68, a20
	v_accvgpr_read_b32 v67, a19
	v_accvgpr_read_b32 v66, a18
	v_accvgpr_read_b32 v65, a17
	v_accvgpr_read_b32 v64, a16
	v_accvgpr_read_b32 v94, a14
	v_accvgpr_read_b32 v93, a13
	v_accvgpr_read_b32 v92, a12
	v_accvgpr_read_b32 v91, a11
	v_accvgpr_read_b32 v90, a10
	v_accvgpr_read_b32 v89, a9
	v_accvgpr_read_b32 v88, a8
	v_accvgpr_read_b32 v87, a7
	v_accvgpr_read_b32 v86, a6
	v_accvgpr_read_b32 v85, a5
	v_accvgpr_read_b32 v84, a4
	v_accvgpr_read_b32 v83, a3
	v_accvgpr_read_b32 v82, a2
	v_accvgpr_read_b32 v81, a1
	v_accvgpr_read_b32 v80, a0
	v_max_f32_e32 v129, v129, v129
	v_max_f32_e32 v146, v216, v216
	v_max_f32_e32 v129, v146, v129
	v_sub_f32_e32 v146, v216, v129
	v_mul_f32_e32 v146, 0x3dd53b94, v146
	v_exp_f32_e32 v146, v146
	v_mov_b32_e32 v216, v129
	v_pk_mul_f32 v[80:81], v[80:81], v[146:147] op_sel_hi:[1,0]
	v_pk_mul_f32 v[64:65], v[64:65], v[146:147] op_sel_hi:[1,0]
	v_pk_mul_f32 v[48:49], v[48:49], v[146:147] op_sel_hi:[1,0]
	v_pk_mul_f32 v[30:31], v[30:31], v[146:147] op_sel_hi:[1,0]
	v_pk_mul_f32 v[94:95], v[94:95], v[146:147] op_sel_hi:[1,0]
	v_pk_mul_f32 v[92:93], v[92:93], v[146:147] op_sel_hi:[1,0]
	v_pk_mul_f32 v[90:91], v[90:91], v[146:147] op_sel_hi:[1,0]
	v_pk_mul_f32 v[88:89], v[88:89], v[146:147] op_sel_hi:[1,0]
	v_pk_mul_f32 v[86:87], v[86:87], v[146:147] op_sel_hi:[1,0]
	v_pk_mul_f32 v[84:85], v[84:85], v[146:147] op_sel_hi:[1,0]
	v_pk_mul_f32 v[82:83], v[82:83], v[146:147] op_sel_hi:[1,0]
	v_pk_mul_f32 v[78:79], v[78:79], v[146:147] op_sel_hi:[1,0]
	v_accvgpr_write_b32 a0, v80
	v_pk_mul_f32 v[76:77], v[76:77], v[146:147] op_sel_hi:[1,0]
	v_pk_mul_f32 v[74:75], v[74:75], v[146:147] op_sel_hi:[1,0]
	v_pk_mul_f32 v[72:73], v[72:73], v[146:147] op_sel_hi:[1,0]
	v_pk_mul_f32 v[70:71], v[70:71], v[146:147] op_sel_hi:[1,0]
	v_pk_mul_f32 v[68:69], v[68:69], v[146:147] op_sel_hi:[1,0]
	v_pk_mul_f32 v[66:67], v[66:67], v[146:147] op_sel_hi:[1,0]
	v_pk_mul_f32 v[62:63], v[62:63], v[146:147] op_sel_hi:[1,0]
	v_accvgpr_write_b32 a16, v64
	v_pk_mul_f32 v[60:61], v[60:61], v[146:147] op_sel_hi:[1,0]
	v_pk_mul_f32 v[58:59], v[58:59], v[146:147] op_sel_hi:[1,0]
	v_pk_mul_f32 v[56:57], v[56:57], v[146:147] op_sel_hi:[1,0]
	v_pk_mul_f32 v[54:55], v[54:55], v[146:147] op_sel_hi:[1,0]
	v_pk_mul_f32 v[52:53], v[52:53], v[146:147] op_sel_hi:[1,0]
	v_pk_mul_f32 v[50:51], v[50:51], v[146:147] op_sel_hi:[1,0]
	v_pk_mul_f32 v[28:29], v[28:29], v[146:147] op_sel_hi:[1,0]
	v_accvgpr_write_b32 a32, v48
	v_pk_mul_f32 v[26:27], v[26:27], v[146:147] op_sel_hi:[1,0]
	v_pk_mul_f32 v[24:25], v[24:25], v[146:147] op_sel_hi:[1,0]
; #define MFMA32(a, b, c) __builtin_amdgcn_mfma_f32_32x32x16_bf16((a), (b), (c), 0, 0, 0)
; DI float ex2(float x) { return __builtin_amdgcn_exp2f(x); }
; template <int DQK>
; DI void attn_item_c(const u16* __restrict__ Qp, int ldq, const u16* __restrict__ Kp, const u16* __restrict__ Vtp, int ldv,
;                     int nkt, int q0, float c, u16* Yp, int ldy, char* smem, bool dry) {
;     ...
;       const float mn = fmaxf(m, mx);
;       const float alpha = ex2((m - mn) * c);
;       m = mn;
;       l *= alpha;
; #pragma unroll
;       for (int dt = 0; dt < 4; ++dt)
; #pragma unroll
;         for (int e = 0; e < 16; ++e) o[dt][e] *= alpha;
;     }
;     ...
; #pragma unroll
;     for (int ks = 0; ks < NKS; ++ks) {
;       if (ks + 2 < NKS) {
;         ka[(ks + 2) % 3][0] = *(const bf16x8*)(k0 + 16 * (ks + 2));
;         ka[(ks + 2) % 3][1] = *(const bf16x8*)(k0 + 32 * KLD + 16 * (ks + 2));
;       }
;       __builtin_amdgcn_sched_barrier(0);
;       n0 = MFMA32(ka[ks % 3][0], qf[ks], n0); n1 = MFMA32(ka[ks % 3][1], qf[ks], n1);
;       {
;         constexpr int dummy0 = 0; (void)dummy0;
;         const int e_lo = (32 * ks) / NKS, e_hi = (32 * (ks + 1)) / NKS;
; #pragma unroll
;         for (int q = 0; q < 3; ++q) {
;           const int e = e_lo + q;
;           if (e < e_hi) {
;             if (e < 16) { s0[e & 15] = ex2(fmaf(s0[e & 15], c, -mc)); ps += s0[e & 15]; }
;             else        { s1[e & 15] = ex2(fmaf(s1[e & 15], c, -mc)); ps += s1[e & 15]; }
;           }
;         }
;       }
	v_pk_mul_f32 v[22:23], v[22:23], v[146:147] op_sel_hi:[1,0]
	v_pk_mul_f32 v[20:21], v[20:21], v[146:147] op_sel_hi:[1,0]
	v_pk_mul_f32 v[18:19], v[18:19], v[146:147] op_sel_hi:[1,0]
	v_pk_mul_f32 v[16:17], v[16:17], v[146:147] op_sel_hi:[1,0]
	v_mul_f32_e32 v190, v190, v146
	v_accvgpr_write_b32 a63, v31
	v_accvgpr_write_b32 a1, v81
	v_accvgpr_write_b32 a2, v82
	v_accvgpr_write_b32 a3, v83
	v_accvgpr_write_b32 a4, v84
	v_accvgpr_write_b32 a5, v85
	v_accvgpr_write_b32 a6, v86
	v_accvgpr_write_b32 a7, v87
	v_accvgpr_write_b32 a8, v88
	v_accvgpr_write_b32 a9, v89
	v_accvgpr_write_b32 a10, v90
	v_accvgpr_write_b32 a11, v91
	v_accvgpr_write_b32 a12, v92
	v_accvgpr_write_b32 a13, v93
	v_accvgpr_write_b32 a14, v94
	v_accvgpr_write_b32 a15, v95
	v_accvgpr_write_b32 a17, v65
	v_accvgpr_write_b32 a18, v66
	v_accvgpr_write_b32 a19, v67
	v_accvgpr_write_b32 a20, v68
	v_accvgpr_write_b32 a21, v69
	v_accvgpr_write_b32 a22, v70
	v_accvgpr_write_b32 a23, v71
	v_accvgpr_write_b32 a24, v72
	v_accvgpr_write_b32 a25, v73
	v_accvgpr_write_b32 a26, v74
	v_accvgpr_write_b32 a27, v75
	v_accvgpr_write_b32 a28, v76
	v_accvgpr_write_b32 a29, v77
	v_accvgpr_write_b32 a30, v78
	v_accvgpr_write_b32 a31, v79
	v_accvgpr_write_b32 a33, v49
	v_accvgpr_write_b32 a34, v50
	v_accvgpr_write_b32 a35, v51
	v_accvgpr_write_b32 a36, v52
	v_accvgpr_write_b32 a37, v53
	v_accvgpr_write_b32 a38, v54
	v_accvgpr_write_b32 a39, v55
	v_accvgpr_write_b32 a40, v56
	v_accvgpr_write_b32 a41, v57
	v_accvgpr_write_b32 a42, v58
	v_accvgpr_write_b32 a43, v59
	v_accvgpr_write_b32 a44, v60
	v_accvgpr_write_b32 a45, v61
	v_accvgpr_write_b32 a46, v62
	v_accvgpr_write_b32 a47, v63
	v_accvgpr_write_b32 a62, v30
	v_accvgpr_write_b32 a61, v29
	v_accvgpr_write_b32 a60, v28
	v_accvgpr_write_b32 a59, v27
	v_accvgpr_write_b32 a58, v26
	v_accvgpr_write_b32 a57, v25
	v_accvgpr_write_b32 a56, v24
	v_accvgpr_write_b32 a55, v23
	v_accvgpr_write_b32 a54, v22
	v_accvgpr_write_b32 a53, v21
	v_accvgpr_write_b32 a52, v20
	v_accvgpr_write_b32 a51, v19
	v_accvgpr_write_b32 a50, v18
	v_accvgpr_write_b32 a49, v17
	v_accvgpr_write_b32 a48, v16
.LBB0_214:
	ds_read_b128 v[16:19], v219
	ds_read_b128 v[20:23], v219 offset:32
	ds_read_b128 v[24:27], v219 offset:12800
	ds_read_b128 v[28:31], v219 offset:64
	ds_read_b128 v[48:51], v219 offset:12832
	ds_read_b128 v[52:55], v219 offset:12864
	v_accvgpr_read_b32 v56, a238
	v_mul_f32_e32 v249, 0xbdd53b94, v216
	v_cmp_le_i32_e32 vcc, s45, v56
	s_waitcnt lgkmcnt(5)
	v_mfma_f32_32x32x16_bf16 a[80:95], v[16:19], v[96:99], 0
	v_fmamk_f32 v16, v32, 0x3dd53b94, v249
	v_exp_f32_e32 v191, v16
	v_fmamk_f32 v16, v33, 0x3dd53b94, v249
	v_exp_f32_e32 v192, v16
	s_waitcnt lgkmcnt(3)
	v_mfma_f32_32x32x16_bf16 a[64:79], v[24:27], v[96:99], 0
	ds_read_b128 v[16:19], v219 offset:96
	ds_read_b128 v[24:27], v219 offset:12896
	v_mfma_f32_32x32x16_bf16 a[80:95], v[20:23], v[100:103], a[80:95]
	v_fmamk_f32 v20, v34, 0x3dd53b94, v249
	v_exp_f32_e32 v193, v20
	v_fmamk_f32 v20, v35, 0x3dd53b94, v249
	v_exp_f32_e32 v198, v20
	v_fmamk_f32 v20, v36, 0x3dd53b94, v249
	v_exp_f32_e32 v199, v20
	s_waitcnt lgkmcnt(3)
	v_mfma_f32_32x32x16_bf16 a[64:79], v[48:51], v[100:103], a[64:79]
	ds_read_b128 v[20:23], v219 offset:128
	ds_read_b128 v[32:35], v219 offset:12928
	v_mfma_f32_32x32x16_bf16 a[80:95], v[28:31], v[104:107], a[80:95]
	v_fmamk_f32 v28, v37, 0x3dd53b94, v249
	v_exp_f32_e32 v200, v28
	v_fmamk_f32 v28, v38, 0x3dd53b94, v249
	v_exp_f32_e32 v201, v28
	v_fmamk_f32 v28, v39, 0x3dd53b94, v249
	v_exp_f32_e32 v202, v28
	s_waitcnt lgkmcnt(4)
	v_mfma_f32_32x32x16_bf16 a[64:79], v[52:55], v[104:107], a[64:79]
	ds_read_b128 v[28:31], v219 offset:160
	ds_read_b128 v[36:39], v219 offset:12960
	s_waitcnt lgkmcnt(5)
	v_mfma_f32_32x32x16_bf16 a[80:95], v[16:19], v[108:111], a[80:95]
	v_fmamk_f32 v16, v40, 0x3dd53b94, v249
	v_exp_f32_e32 v203, v16
	v_fmamk_f32 v16, v41, 0x3dd53b94, v249
	v_exp_f32_e32 v204, v16
	s_waitcnt lgkmcnt(4)
	v_mfma_f32_32x32x16_bf16 a[64:79], v[24:27], v[108:111], a[64:79]
	ds_read_b128 v[16:19], v219 offset:192
	ds_read_b128 v[24:27], v219 offset:12992
	s_waitcnt lgkmcnt(5)
	v_mfma_f32_32x32x16_bf16 a[80:95], v[20:23], v[112:115], a[80:95]
	v_fmamk_f32 v20, v42, 0x3dd53b94, v249
	v_exp_f32_e32 v205, v20
	v_fmamk_f32 v20, v43, 0x3dd53b94, v249
	v_exp_f32_e32 v206, v20
	v_fmamk_f32 v20, v44, 0x3dd53b94, v249
	v_exp_f32_e32 v207, v20
	s_waitcnt lgkmcnt(4)
	v_mfma_f32_32x32x16_bf16 a[64:79], v[32:35], v[112:115], a[64:79]
	ds_read_b128 v[20:23], v219 offset:224
	ds_read_b128 v[32:35], v219 offset:13024
	s_waitcnt lgkmcnt(5)
	v_mfma_f32_32x32x16_bf16 a[80:95], v[28:31], v[116:119], a[80:95]
	v_fmamk_f32 v28, v45, 0x3dd53b94, v249
	v_exp_f32_e32 v208, v28
	v_fmamk_f32 v28, v46, 0x3dd53b94, v249
	v_exp_f32_e32 v209, v28
	v_fmamk_f32 v28, v47, 0x3dd53b94, v249
	v_exp_f32_e32 v248, v28
	s_waitcnt lgkmcnt(4)
	v_mfma_f32_32x32x16_bf16 a[64:79], v[36:39], v[116:119], a[64:79]
	ds_read_b128 v[28:31], v219 offset:256
	ds_read_b128 v[36:39], v219 offset:13056
	s_waitcnt lgkmcnt(5)
	v_mfma_f32_32x32x16_bf16 a[80:95], v[16:19], v[120:123], a[80:95]
	v_fmamk_f32 v0, v0, 0x3dd53b94, v249
	v_exp_f32_e32 v213, v0
	v_fmamk_f32 v0, v1, 0x3dd53b94, v249
	v_exp_f32_e32 v214, v0
	s_waitcnt lgkmcnt(4)
	v_mfma_f32_32x32x16_bf16 a[64:79], v[24:27], v[120:123], a[64:79]
	ds_read_b128 v[16:19], v219 offset:288
	ds_read_b128 v[24:27], v219 offset:13088
	s_waitcnt lgkmcnt(5)
	v_mfma_f32_32x32x16_bf16 a[80:95], v[20:23], v[124:127], a[80:95]
	v_fmamk_f32 v0, v2, 0x3dd53b94, v249
	v_exp_f32_e32 v129, v0
	v_fmamk_f32 v0, v3, 0x3dd53b94, v249
	v_exp_f32_e32 v215, v0
	v_fmamk_f32 v0, v4, 0x3dd53b94, v249
	v_exp_f32_e32 v227, v0
	s_waitcnt lgkmcnt(4)
; template <int DQK>
; DI void attn_item_c(const u16* __restrict__ Qp, int ldq, const u16* __restrict__ Kp, const u16* __restrict__ Vtp, int ldv,
;                     int nkt, int q0, float c, u16* Yp, int ldy, char* smem, bool dry) {
;     ...
; #pragma unroll
;     for (int ks = 0; ks < NKS; ++ks) {
;       if (ks + 2 < NKS) {
;         ka[(ks + 2) % 3][0] = *(const bf16x8*)(k0 + 16 * (ks + 2));
;         ka[(ks + 2) % 3][1] = *(const bf16x8*)(k0 + 32 * KLD + 16 * (ks + 2));
;       }
;       __builtin_amdgcn_sched_barrier(0);
;       n0 = MFMA32(ka[ks % 3][0], qf[ks], n0); n1 = MFMA32(ka[ks % 3][1], qf[ks], n1);
;       {
;         constexpr int dummy0 = 0; (void)dummy0;
;         const int e_lo = (32 * ks) / NKS, e_hi = (32 * (ks + 1)) / NKS;
; #pragma unroll
;         for (int q = 0; q < 3; ++q) {
;           const int e = e_lo + q;
;           if (e < e_hi) {
;             if (e < 16) { s0[e & 15] = ex2(fmaf(s0[e & 15], c, -mc)); ps += s0[e & 15]; }
;             else        { s1[e & 15] = ex2(fmaf(s1[e & 15], c, -mc)); ps += s1[e & 15]; }
;           }
;         }
;       }
;       if (ks == 3)  { pk[0].x = pack2(s0[0], s0[1]);  pk[0].y = pack2(s0[2], s0[3]);   pk[0].z = pack2(s0[4], s0[5]);   pk[0].w = pack2(s0[6], s0[7]); }
;       if (ks == 6)  { pk[1].x = pack2(s0[8], s0[9]);  pk[1].y = pack2(s0[10], s0[11]); pk[1].z = pack2(s0[12], s0[13]); pk[1].w = pack2(s0[14], s0[15]); }
;       if (ks == 9)  { pk[2].x = pack2(s1[0], s1[1]);  pk[2].y = pack2(s1[2], s1[3]);   pk[2].z = pack2(s1[4], s1[5]);   pk[2].w = pack2(s1[6], s1[7]); }
;       if (ks == NKS - 1) { pk[3].x = pack2(s1[8], s1[9]);  pk[3].y = pack2(s1[10], s1[11]); pk[3].z = pack2(s1[12], s1[13]); pk[3].w = pack2(s1[14], s1[15]); }
;       __builtin_amdgcn_sched_barrier(0);
;     }
;     l += ps;
; #pragma unroll
;     for (int i = 0; i < 4; ++i) pf[i] = __builtin_bit_cast(bf16x8, pk[i]);
;     if (active) {
;       const u16* v0 = Vs + r * 72 + 8 * h;
;       bf16x8 va[2][4];
; #pragma unroll
;       for (int dt = 0; dt < 4; ++dt) va[0][dt] = *(const bf16x8*)(v0 + (32 * dt) * 72);
; #pragma unroll
;       for (int kk = 0; kk < 4; ++kk) {
;         if (kk < 3) {
; #pragma unroll
;           for (int dt = 0; dt < 4; ++dt) va[(kk + 1) & 1][dt] = *(const bf16x8*)(v0 + (32 * dt) * 72 + 16 * (kk + 1));
;         }
;         __builtin_amdgcn_sched_barrier(0);
; #pragma unroll
	v_mfma_f32_32x32x16_bf16 a[64:79], v[32:35], v[124:127], a[64:79]
	ds_read_b128 v[0:3], v219 offset:320
	ds_read_b128 v[20:23], v219 offset:13120
	s_waitcnt lgkmcnt(5)
	v_mfma_f32_32x32x16_bf16 a[80:95], v[28:31], v[130:133], a[80:95]
	v_fmamk_f32 v4, v5, 0x3dd53b94, v249
	v_exp_f32_e32 v228, v4
	v_fmamk_f32 v4, v6, 0x3dd53b94, v249
	v_exp_f32_e32 v229, v4
	v_fmamk_f32 v4, v7, 0x3dd53b94, v249
	v_exp_f32_e32 v230, v4
	s_waitcnt lgkmcnt(4)
	v_mfma_f32_32x32x16_bf16 a[64:79], v[36:39], v[130:133], a[64:79]
	ds_read_b128 v[4:7], v219 offset:352
	ds_read_b128 v[28:31], v219 offset:13152
	s_waitcnt lgkmcnt(5)
	v_mfma_f32_32x32x16_bf16 a[80:95], v[16:19], v[134:137], a[80:95]
	v_fmamk_f32 v8, v8, 0x3dd53b94, v249
	v_exp_f32_e32 v149, v8
	v_fmamk_f32 v8, v9, 0x3dd53b94, v249
	v_exp_f32_e32 v231, v8
	s_waitcnt lgkmcnt(4)
	v_mfma_f32_32x32x16_bf16 a[64:79], v[24:27], v[134:137], a[64:79]
	s_waitcnt lgkmcnt(3)
	v_mfma_f32_32x32x16_bf16 a[80:95], v[0:3], v[138:141], a[80:95]
	v_fmamk_f32 v0, v10, 0x3dd53b94, v249
	v_exp_f32_e32 v218, v0
	v_fmamk_f32 v0, v11, 0x3dd53b94, v249
	v_exp_f32_e32 v234, v0
	v_fmamk_f32 v0, v12, 0x3dd53b94, v249
	v_exp_f32_e32 v244, v0
	s_waitcnt lgkmcnt(2)
	v_mfma_f32_32x32x16_bf16 a[64:79], v[20:23], v[138:141], a[64:79]
	s_waitcnt lgkmcnt(1)
	v_mfma_f32_32x32x16_bf16 a[80:95], v[4:7], v[142:145], a[80:95]
	v_fmamk_f32 v0, v13, 0x3dd53b94, v249
	v_exp_f32_e32 v146, v0
	v_fmamk_f32 v0, v14, 0x3dd53b94, v249
	v_exp_f32_e32 v147, v0
	v_fmamk_f32 v0, v15, 0x3dd53b94, v249
	v_exp_f32_e32 v148, v0
	s_waitcnt lgkmcnt(0)
	v_mfma_f32_32x32x16_bf16 a[64:79], v[28:31], v[142:145], a[64:79]
	v_add_u32_e32 v211, 0x1000, v220
	v_add_u32_e32 v251, 0x2000, v220
	v_add_u32_e32 v210, 0x3000, v220
	s_and_saveexec_b64 s[0:1], vcc
	s_xor_b64 s[0:1], exec, s[0:1]
	s_cbranch_execz .LBB0_216
	ds_read_b128 v[16:19], v128 offset:25600
	ds_read_b128 v[20:23], v128 offset:25632
	ds_read_b128 v[24:27], v128 offset:30208
	ds_read_b128 v[28:31], v128 offset:30240
	ds_read_b128 v[32:35], v128 offset:34816
	ds_read_b128 v[36:39], v128 offset:34848
	ds_read_b128 v[40:43], v128 offset:39424
	ds_read_b128 v[44:47], v128 offset:39456
	s_or_b32 s20, s44, 3
	s_add_i32 s8, s44, 4
	v_cvt_pk_bf16_f32 v0, v149, v231
	v_cvt_pk_bf16_f32 v1, v218, v234
	v_cvt_pk_bf16_f32 v2, v244, v146
	v_cvt_pk_bf16_f32 v3, v147, v148
	v_cvt_pk_bf16_f32 v4, v213, v214
	v_cvt_pk_bf16_f32 v5, v129, v215
	v_cvt_pk_bf16_f32 v6, v227, v228
	v_cvt_pk_bf16_f32 v7, v229, v230
	v_cvt_pk_bf16_f32 v8, v203, v204
	v_cvt_pk_bf16_f32 v9, v205, v206
	v_cvt_pk_bf16_f32 v10, v207, v208
	v_cvt_pk_bf16_f32 v11, v209, v248
	v_cvt_pk_bf16_f32 v12, v191, v192
	v_cvt_pk_bf16_f32 v13, v193, v198
	v_cvt_pk_bf16_f32 v14, v199, v200
	v_cvt_pk_bf16_f32 v15, v201, v202
	s_lshl_b64 s[6:7], s[20:21], 14
	s_mul_hi_u32 s9, s8, 0x6000
	s_mulk_i32 s8, 0x6000
	s_waitcnt lgkmcnt(7)
	v_mfma_f32_32x32x16_bf16 a[0:15], v[16:19], v[12:15], a[0:15]
	s_waitcnt vmcnt(10)
	ds_write_b128 v221, a[96:99] offset:44032
	ds_write_b128 v222, a[100:103] offset:44032
	ds_write_b128 v223, a[104:107] offset:44032
	ds_write_b128 v224, a[108:111] offset:44032
	ds_write_b128 v225, a[112:115] offset:44032
	ds_write_b128 v226, a[116:119] offset:44032
	s_waitcnt lgkmcnt(11)
	v_mfma_f32_32x32x16_bf16 a[16:31], v[24:27], v[12:15], a[16:31]
	s_waitcnt lgkmcnt(9)
	v_mfma_f32_32x32x16_bf16 a[32:47], v[32:35], v[12:15], a[32:47]
	s_waitcnt lgkmcnt(7)
	v_mfma_f32_32x32x16_bf16 a[48:63], v[40:43], v[12:15], a[48:63]
	ds_read_b128 v[12:15], v128 offset:25664
	ds_read_b128 v[16:19], v128 offset:30272
	ds_read_b128 v[24:27], v128 offset:34880
	ds_read_b128 v[32:35], v128 offset:39488
	v_mfma_f32_32x32x16_bf16 a[0:15], v[20:23], v[8:11], a[0:15]
	v_accvgpr_read_b32 v20, a240
	v_accvgpr_read_b32 v21, a241
	v_accvgpr_read_b32 v22, a242
	v_accvgpr_read_b32 v23, a243
	ds_write2_b64 v220, v[20:21], v[22:23] offset1:2
	ds_write2_b64 v211, v[150:151], v[152:153] offset0:64 offset1:66
	ds_write2_b64 v251, v[154:155], v[156:157] offset0:128 offset1:130
	ds_write2_b64 v210, v[158:159], v[160:161] offset0:192 offset1:194
	v_mfma_f32_32x32x16_bf16 a[16:31], v[28:31], v[8:11], a[16:31]
	v_mfma_f32_32x32x16_bf16 a[32:47], v[36:39], v[8:11], a[32:47]
	s_waitcnt lgkmcnt(14)
	v_mfma_f32_32x32x16_bf16 a[48:63], v[44:47], v[8:11], a[48:63]
	ds_read_b128 v[8:11], v128 offset:25696
	ds_read_b128 v[20:23], v128 offset:30304
	ds_read_b128 v[28:31], v128 offset:34912
	ds_read_b128 v[36:39], v128 offset:39520
	s_add_u32 s8, s94, s8
	s_addc_u32 s9, s95, s9
	s_waitcnt lgkmcnt(11)
	v_mfma_f32_32x32x16_bf16 a[0:15], v[12:15], v[4:7], a[0:15]
	v_lshl_add_u64 v[12:13], s[8:9], 0, v[236:237]
	v_lshl_add_u64 v[14:15], s[8:9], 0, v[238:239]
	global_load_dwordx4 a[148:151], v[12:13], off
	global_load_dwordx4 a[152:155], v[14:15], off
	v_lshl_add_u64 v[12:13], s[8:9], 0, v[240:241]
	v_lshl_add_u64 v[14:15], s[8:9], 0, v[242:243]
	global_load_dwordx4 a[160:163], v[12:13], off
	global_load_dwordx4 a[168:171], v[14:15], off
	v_accvgpr_read_b32 v12, a230
	v_accvgpr_read_b32 v13, a231
	v_accvgpr_read_b32 v14, a232
	v_lshl_add_u64 v[12:13], s[8:9], 0, v[12:13]
	v_accvgpr_read_b32 v15, a233
	v_lshl_add_u64 v[14:15], s[8:9], 0, v[14:15]
	global_load_dwordx4 a[176:179], v[12:13], off
	global_load_dwordx4 a[184:187], v[14:15], off
	s_waitcnt lgkmcnt(10)
	v_mfma_f32_32x32x16_bf16 a[16:31], v[16:19], v[4:7], a[16:31]
	s_waitcnt lgkmcnt(9)
	v_mfma_f32_32x32x16_bf16 a[32:47], v[24:27], v[4:7], a[32:47]
	s_waitcnt lgkmcnt(8)
	v_mfma_f32_32x32x16_bf16 a[48:63], v[32:35], v[4:7], a[48:63]
	s_add_u32 s6, s60, s6
	s_addc_u32 s7, s61, s7
	s_waitcnt lgkmcnt(3)
	v_mfma_f32_32x32x16_bf16 a[0:15], v[8:11], v[0:3], a[0:15]
	s_waitcnt lgkmcnt(2)
	v_mfma_f32_32x32x16_bf16 a[16:31], v[20:23], v[0:3], a[16:31]
	s_waitcnt lgkmcnt(1)
	v_mfma_f32_32x32x16_bf16 a[32:47], v[28:31], v[0:3], a[32:47]
	s_waitcnt lgkmcnt(0)
	v_mfma_f32_32x32x16_bf16 a[48:63], v[36:39], v[0:3], a[48:63]
	v_lshl_add_u64 v[0:1], s[6:7], 0, v[236:237]
	global_load_dwordx4 v[178:181], v[0:1], off
	v_lshl_add_u64 v[0:1], s[6:7], 0, v[238:239]
	global_load_dwordx4 v[186:189], v[0:1], off
	v_lshl_add_u64 v[0:1], s[6:7], 0, v[240:241]
	global_load_dwordx4 v[182:185], v[0:1], off
	v_lshl_add_u64 v[0:1], s[6:7], 0, v[242:243]
	global_load_dwordx4 v[194:197], v[0:1], off
; DI int crow(int reg, int h) { return (reg & 3) + 8 * (reg >> 2) + 4 * h; }
; template <int DQK>
; DI void attn_item_c(const u16* __restrict__ Qp, int ldq, const u16* __restrict__ Kp, const u16* __restrict__ Vtp, int ldv,
;                     int nkt, int q0, float c, u16* Yp, int ldy, char* smem, bool dry) {
;     ...
;   auto body = [&](int kt, u32x4* wk, u32x4* wv, f32x16& s0, f32x16& s1, f32x16& n0, f32x16& n1) {
;     const u16* Ks = L0 + (kt & 1) * BUFE;
;     const u16* Vs = Ks + 64 * KLD;
;     u16* Ln = L0 + ((kt + 1) & 1) * BUFE;
;     const bool active = !(kt * 64 > qmin + 31);
;     if (kt * 64 + 63 > qmin) {
; #pragma unroll
;       for (int e = 0; e < 16; ++e) {
;         int key = kt * 64 + crow(e, h);
;         if (key > qi) s0[e] = -INFINITY;
;         if (key + 32 > qi) s1[e] = -INFINITY;
;       }
;     }
;     ...
;     } else {
;       lstore(wk, wv, Ln);
;       gload(wk, wv, kt + 3);
;     }
;     __syncthreads();
.LBB0_216:
	s_andn2_saveexec_b64 s[0:1], s[0:1]
	s_cbranch_execz .LBB0_218
	s_add_i32 s6, s44, 4
	s_or_b32 s20, s44, 3
	s_mul_hi_u32 s7, s6, 0x6000
	s_mulk_i32 s6, 0x6000
	v_accvgpr_read_b32 v0, a240
	s_add_u32 s6, s94, s6
	v_accvgpr_read_b32 v1, a241
	v_accvgpr_read_b32 v2, a242
	v_accvgpr_read_b32 v3, a243
	s_addc_u32 s7, s95, s7
	s_waitcnt vmcnt(10)
	ds_write_b128 v221, a[96:99] offset:44032
	ds_write_b128 v222, a[100:103] offset:44032
	ds_write_b128 v223, a[104:107] offset:44032
	ds_write_b128 v224, a[108:111] offset:44032
	ds_write_b128 v225, a[112:115] offset:44032
	ds_write_b128 v226, a[116:119] offset:44032
	ds_write2_b64 v220, v[0:1], v[2:3] offset1:2
	ds_write2_b64 v211, v[150:151], v[152:153] offset0:64 offset1:66
	ds_write2_b64 v251, v[154:155], v[156:157] offset0:128 offset1:130
	ds_write2_b64 v210, v[158:159], v[160:161] offset0:192 offset1:194
	v_lshl_add_u64 v[0:1], s[6:7], 0, v[236:237]
	global_load_dwordx4 a[148:151], v[0:1], off
	v_lshl_add_u64 v[0:1], s[6:7], 0, v[238:239]
	global_load_dwordx4 a[152:155], v[0:1], off
	v_lshl_add_u64 v[0:1], s[6:7], 0, v[240:241]
	global_load_dwordx4 a[160:163], v[0:1], off
	v_lshl_add_u64 v[0:1], s[6:7], 0, v[242:243]
	global_load_dwordx4 a[168:171], v[0:1], off
	v_accvgpr_read_b32 v0, a230
	v_accvgpr_read_b32 v1, a231
	v_lshl_add_u64 v[0:1], s[6:7], 0, v[0:1]
	global_load_dwordx4 a[176:179], v[0:1], off
	v_accvgpr_read_b32 v0, a232
	v_accvgpr_read_b32 v1, a233
	v_lshl_add_u64 v[0:1], s[6:7], 0, v[0:1]
	s_lshl_b64 s[6:7], s[20:21], 14
	s_add_u32 s6, s60, s6
	s_addc_u32 s7, s61, s7
	global_load_dwordx4 a[184:187], v[0:1], off
	v_lshl_add_u64 v[0:1], s[6:7], 0, v[236:237]
	global_load_dwordx4 v[178:181], v[0:1], off
	v_lshl_add_u64 v[0:1], s[6:7], 0, v[238:239]
	global_load_dwordx4 v[186:189], v[0:1], off
	v_lshl_add_u64 v[0:1], s[6:7], 0, v[240:241]
	global_load_dwordx4 v[182:185], v[0:1], off
	v_lshl_add_u64 v[0:1], s[6:7], 0, v[242:243]
	global_load_dwordx4 v[194:197], v[0:1], off
.LBB0_218:
	s_or_b64 exec, exec, s[0:1]
	s_nop 0
	s_or_b32 s0, s45, 0x7f
	s_or_b32 s20, s45, 64
	v_cmp_gt_i32_e32 vcc, s0, v233
	s_waitcnt lgkmcnt(0)
	s_barrier
	s_and_saveexec_b64 s[46:47], vcc
	s_cbranch_execz .LBB0_222
	v_accvgpr_read_b32 v0, a80
	v_accvgpr_read_b32 v32, a64
	v_accvgpr_read_b32 v1, a81
	v_accvgpr_read_b32 v2, a82
	v_accvgpr_read_b32 v3, a83
	v_accvgpr_read_b32 v4, a84
	v_accvgpr_read_b32 v5, a85
	v_accvgpr_read_b32 v6, a86
	v_accvgpr_read_b32 v7, a87
	v_accvgpr_read_b32 v8, a88
	v_accvgpr_read_b32 v9, a89
	v_accvgpr_read_b32 v10, a90
	v_accvgpr_read_b32 v11, a91
	v_accvgpr_read_b32 v12, a92
	v_accvgpr_read_b32 v13, a93
	v_accvgpr_read_b32 v14, a94
	v_accvgpr_read_b32 v15, a95
	v_accvgpr_read_b32 v33, a65
	v_accvgpr_read_b32 v34, a66
	v_accvgpr_read_b32 v35, a67
	v_accvgpr_read_b32 v36, a68
	v_accvgpr_read_b32 v37, a69
	v_accvgpr_read_b32 v38, a70
	v_accvgpr_read_b32 v39, a71
	v_accvgpr_read_b32 v40, a72
	v_accvgpr_read_b32 v41, a73
	v_accvgpr_read_b32 v42, a74
	v_accvgpr_read_b32 v43, a75
	v_accvgpr_read_b32 v44, a76
	v_accvgpr_read_b32 v45, a77
	v_accvgpr_read_b32 v46, a78
	v_accvgpr_read_b32 v47, a79
	v_accvgpr_read_b32 v150, a237
	v_or_b32_e32 v150, s20, v150
	v_or_b32_e32 v151, 32, v150
	v_cmp_le_i32_e64 s[0:1], v151, v212
	v_or_b32_e32 v151, 33, v150
	v_mov_b32_e32 v152, 0xff800000
	v_cmp_le_i32_e64 s[6:7], v151, v212
	v_or_b32_e32 v151, 2, v150
	v_cmp_le_i32_e32 vcc, v150, v212
	v_cndmask_b32_e64 v33, v152, v33, s[6:7]
	v_cmp_le_i32_e64 s[6:7], v151, v212
	v_or_b32_e32 v151, 34, v150
	v_cmp_le_i32_e64 s[8:9], v151, v212
	v_or_b32_e32 v151, 3, v150
	v_cndmask_b32_e64 v32, v152, v32, s[0:1]
	v_cndmask_b32_e64 v34, v152, v34, s[8:9]
	v_cmp_le_i32_e64 s[8:9], v151, v212
	v_or_b32_e32 v151, 35, v150
	v_cmp_le_i32_e64 s[10:11], v151, v212
	v_or_b32_e32 v151, 8, v150
	v_cmp_lt_i32_e64 s[0:1], v150, v212
	v_cndmask_b32_e64 v35, v152, v35, s[10:11]
	v_cmp_le_i32_e64 s[10:11], v151, v212
	v_or_b32_e32 v151, 40, v150
	v_cmp_le_i32_e64 s[12:13], v151, v212
	v_or_b32_e32 v151, 9, v150
	s_nop 0
	v_cndmask_b32_e64 v36, v152, v36, s[12:13]
	v_cmp_le_i32_e64 s[12:13], v151, v212
	v_or_b32_e32 v151, 41, v150
	v_cmp_le_i32_e64 s[14:15], v151, v212
	v_or_b32_e32 v151, 10, v150
	s_nop 0
	v_cndmask_b32_e64 v37, v152, v37, s[14:15]
	v_cmp_le_i32_e64 s[14:15], v151, v212
	v_or_b32_e32 v151, 42, v150
	v_cmp_le_i32_e64 s[16:17], v151, v212
	v_or_b32_e32 v151, 11, v150
	s_nop 0
	v_cndmask_b32_e64 v38, v152, v38, s[16:17]
	v_cmp_le_i32_e64 s[16:17], v151, v212
	v_or_b32_e32 v151, 43, v150
	v_cmp_le_i32_e64 s[18:19], v151, v212
	v_or_b32_e32 v151, 16, v150
	s_nop 0
	v_cndmask_b32_e64 v39, v152, v39, s[18:19]
	v_cmp_le_i32_e64 s[18:19], v151, v212
	v_or_b32_e32 v151, 48, v150
	v_cmp_le_i32_e64 s[22:23], v151, v212
	v_or_b32_e32 v151, 17, v150
	s_nop 0
	v_cndmask_b32_e64 v40, v152, v40, s[22:23]
	v_cmp_le_i32_e64 s[22:23], v151, v212
	v_or_b32_e32 v151, 49, v150
	v_cmp_le_i32_e64 s[24:25], v151, v212
	v_or_b32_e32 v151, 18, v150
	s_nop 0
	v_cndmask_b32_e64 v41, v152, v41, s[24:25]
	v_cmp_le_i32_e64 s[24:25], v151, v212
	v_or_b32_e32 v151, 50, v150
	v_cmp_le_i32_e64 s[26:27], v151, v212
	v_or_b32_e32 v151, 19, v150
	s_nop 0
	v_cndmask_b32_e64 v42, v152, v42, s[26:27]
	v_cmp_le_i32_e64 s[26:27], v151, v212
	v_or_b32_e32 v151, 51, v150
	v_cmp_le_i32_e64 s[28:29], v151, v212
	v_or_b32_e32 v151, 24, v150
	s_nop 0
	v_cndmask_b32_e64 v43, v152, v43, s[28:29]
	v_cmp_le_i32_e64 s[28:29], v151, v212
	v_or_b32_e32 v151, 56, v150
	v_cmp_le_i32_e64 s[30:31], v151, v212
	v_or_b32_e32 v151, 25, v150
	s_nop 0
	v_cndmask_b32_e64 v44, v152, v44, s[30:31]
	v_cmp_le_i32_e64 s[30:31], v151, v212
	v_or_b32_e32 v151, 57, v150
; DI float ex2(float x) { return __builtin_amdgcn_exp2f(x); }
; DI int crow(int reg, int h) { return (reg & 3) + 8 * (reg >> 2) + 4 * h; }
; template <int DQK>
; DI void attn_item_c(const u16* __restrict__ Qp, int ldq, const u16* __restrict__ Kp, const u16* __restrict__ Vtp, int ldv,
;                     int nkt, int q0, float c, u16* Yp, int ldy, char* smem, bool dry) {
;     ...
;     const bool active = !(kt * 64 > qmin + 31);
;     if (kt * 64 + 63 > qmin) {
; #pragma unroll
;       for (int e = 0; e < 16; ++e) {
;         int key = kt * 64 + crow(e, h);
;         if (key > qi) s0[e] = -INFINITY;
;         if (key + 32 > qi) s1[e] = -INFINITY;
;       }
;     }
;     float mx = fmaxf(s0[0], s1[0]);
; #pragma unroll
;     for (int e = 1; e < 16; ++e) mx = fmaxf(fmaxf(mx, s0[e]), s1[e]);
;     mx = fmaxf(mx, __shfl_xor(mx, 32));
;     if (__builtin_amdgcn_ballot_w64((mx - m) * c > 8.f) != 0ull) {
;       const float mn = fmaxf(m, mx);
;       const float alpha = ex2((m - mn) * c);
;       m = mn;
;       l *= alpha;
; #pragma unroll
;       for (int dt = 0; dt < 4; ++dt)
; #pragma unroll
;         for (int e = 0; e < 16; ++e) o[dt][e] *= alpha;
;     }
;     ...
;     l += ps;
	v_cmp_le_i32_e64 s[34:35], v151, v212
	v_or_b32_e32 v151, 26, v150
	s_nop 0
	v_cndmask_b32_e64 v45, v152, v45, s[34:35]
	v_cmp_le_i32_e64 s[34:35], v151, v212
	v_or_b32_e32 v151, 58, v150
	v_cmp_le_i32_e64 s[36:37], v151, v212
	v_or_b32_e32 v151, 27, v150
	v_or_b32_e32 v150, 59, v150
	v_cndmask_b32_e64 v46, v152, v46, s[36:37]
	v_cmp_le_i32_e64 s[36:37], v151, v212
	v_cmp_gt_i32_e64 s[40:41], v150, v212
	s_and_saveexec_b64 s[48:49], s[40:41]
	v_mov_b32_e32 v47, s65
	s_or_b64 exec, exec, s[48:49]
	v_accvgpr_write_b32 a79, v47
	v_accvgpr_write_b32 a78, v46
	v_accvgpr_write_b32 a77, v45
	v_accvgpr_write_b32 a76, v44
	v_accvgpr_write_b32 a75, v43
	v_accvgpr_write_b32 a74, v42
	v_accvgpr_write_b32 a73, v41
	v_accvgpr_write_b32 a72, v40
	v_accvgpr_write_b32 a71, v39
	v_accvgpr_write_b32 a70, v38
	v_accvgpr_write_b32 a69, v37
	v_accvgpr_write_b32 a68, v36
	v_accvgpr_write_b32 a67, v35
	v_accvgpr_write_b32 a66, v34
	v_accvgpr_write_b32 a65, v33
	v_accvgpr_write_b32 a64, v32
	v_mov_b32_e32 v32, 0xff800000
	v_cndmask_b32_e64 v1, v32, v1, s[0:1]
	v_cndmask_b32_e32 v0, v32, v0, vcc
	v_cndmask_b32_e64 v2, v32, v2, s[6:7]
	v_cndmask_b32_e64 v3, v32, v3, s[8:9]
	v_cndmask_b32_e64 v4, v32, v4, s[10:11]
	v_cndmask_b32_e64 v5, v32, v5, s[12:13]
	v_cndmask_b32_e64 v6, v32, v6, s[14:15]
	v_cndmask_b32_e64 v7, v32, v7, s[16:17]
	v_cndmask_b32_e64 v8, v32, v8, s[18:19]
	v_cndmask_b32_e64 v9, v32, v9, s[22:23]
	v_cndmask_b32_e64 v10, v32, v10, s[24:25]
	v_cndmask_b32_e64 v11, v32, v11, s[26:27]
	v_cndmask_b32_e64 v12, v32, v12, s[28:29]
	v_cndmask_b32_e64 v13, v32, v13, s[30:31]
	v_cndmask_b32_e64 v14, v32, v14, s[34:35]
	v_cndmask_b32_e64 v15, v32, v15, s[36:37]
	v_accvgpr_write_b32 a80, v0
	v_accvgpr_write_b32 a81, v1
	v_accvgpr_write_b32 a82, v2
	v_accvgpr_write_b32 a83, v3
	v_accvgpr_write_b32 a84, v4
	v_accvgpr_write_b32 a85, v5
	v_accvgpr_write_b32 a86, v6
	v_accvgpr_write_b32 a87, v7
	v_accvgpr_write_b32 a88, v8
	v_accvgpr_write_b32 a89, v9
	v_accvgpr_write_b32 a90, v10
	v_accvgpr_write_b32 a91, v11
	v_accvgpr_write_b32 a92, v12
	v_accvgpr_write_b32 a93, v13
	v_accvgpr_write_b32 a94, v14
	v_accvgpr_write_b32 a95, v15
	s_mov_b64 s[40:41], s[70:71]
.LBB0_222:
	s_or_b64 exec, exec, s[46:47]
	v_add_f32_e32 v150, 0, v191
	v_add_f32_e32 v150, v192, v150
	v_add_f32_e32 v150, v193, v150
	v_add_f32_e32 v150, v198, v150
	v_add_f32_e32 v150, v199, v150
	v_add_f32_e32 v150, v200, v150
	v_add_f32_e32 v150, v201, v150
	v_add_f32_e32 v150, v202, v150
	v_add_f32_e32 v150, v203, v150
	v_add_f32_e32 v150, v204, v150
	v_add_f32_e32 v150, v205, v150
	v_add_f32_e32 v150, v206, v150
	v_add_f32_e32 v150, v207, v150
	v_add_f32_e32 v150, v208, v150
	v_add_f32_e32 v150, v209, v150
	v_add_f32_e32 v150, v248, v150
	v_add_f32_e32 v150, v213, v150
	v_add_f32_e32 v150, v214, v150
	v_add_f32_e32 v129, v129, v150
	v_add_f32_e32 v129, v215, v129
	v_add_f32_e32 v129, v227, v129
	v_add_f32_e32 v129, v228, v129
	v_add_f32_e32 v129, v229, v129
	v_accvgpr_read_b32 v0, a64
	v_accvgpr_read_b32 v32, a80
	v_add_f32_e32 v129, v230, v129
	v_add_f32_e32 v129, v149, v129
	v_max_f32_e32 v149, v0, v0
	v_max_f32_e32 v150, v32, v32
	v_accvgpr_read_b32 v1, a65
	v_accvgpr_read_b32 v33, a81
	v_max_f32_e32 v149, v150, v149
	v_accvgpr_read_b32 v2, a66
	v_accvgpr_read_b32 v34, a82
	v_max3_f32 v149, v149, v33, v1
	v_accvgpr_read_b32 v3, a67
	v_accvgpr_read_b32 v35, a83
	v_max3_f32 v149, v149, v34, v2
	v_accvgpr_read_b32 v4, a68
	v_accvgpr_read_b32 v36, a84
	v_max3_f32 v149, v149, v35, v3
	v_accvgpr_read_b32 v5, a69
	v_accvgpr_read_b32 v37, a85
	v_max3_f32 v149, v149, v36, v4
	v_accvgpr_read_b32 v6, a70
	v_accvgpr_read_b32 v38, a86
	v_max3_f32 v149, v149, v37, v5
	v_accvgpr_read_b32 v7, a71
	v_accvgpr_read_b32 v39, a87
	v_max3_f32 v149, v149, v38, v6
	v_accvgpr_read_b32 v8, a72
	v_accvgpr_read_b32 v40, a88
	v_max3_f32 v149, v149, v39, v7
	v_accvgpr_read_b32 v9, a73
	v_accvgpr_read_b32 v41, a89
	v_max3_f32 v149, v149, v40, v8
	v_accvgpr_read_b32 v10, a74
	v_accvgpr_read_b32 v42, a90
	v_max3_f32 v149, v149, v41, v9
	v_accvgpr_read_b32 v11, a75
	v_accvgpr_read_b32 v43, a91
	v_max3_f32 v149, v149, v42, v10
	v_accvgpr_read_b32 v12, a76
	v_accvgpr_read_b32 v44, a92
	v_max3_f32 v149, v149, v43, v11
	v_accvgpr_read_b32 v13, a77
	v_accvgpr_read_b32 v45, a93
	v_max3_f32 v149, v149, v44, v12
	v_accvgpr_read_b32 v14, a78
	v_accvgpr_read_b32 v46, a94
	v_max3_f32 v149, v149, v45, v13
	v_accvgpr_read_b32 v15, a79
	v_accvgpr_read_b32 v47, a95
	v_add_f32_e32 v129, v231, v129
	v_max3_f32 v149, v149, v46, v14
	v_add_f32_e32 v129, v218, v129
	v_max3_f32 v149, v149, v47, v15
	v_add_f32_e32 v129, v234, v129
	ds_bpermute_b32 v150, v232, v149
	v_add_f32_e32 v129, v244, v129
	v_add_f32_e32 v129, v146, v129
	v_add_f32_e32 v129, v147, v129
	v_add_f32_e32 v129, v148, v129
	v_add_f32_e32 v146, v190, v129
	s_waitcnt lgkmcnt(0)
	v_max_f32_e32 v129, v150, v150
	v_max_f32_e32 v129, v149, v129
	v_sub_f32_e32 v147, v129, v216
	v_mul_f32_e32 v147, 0x3dd53b94, v147
	v_cmp_lt_f32_e32 vcc, s33, v147
	s_cbranch_vccz .LBB0_224
; DI float ex2(float x) { return __builtin_amdgcn_exp2f(x); }
; template <int DQK>
; DI void attn_item_c(const u16* __restrict__ Qp, int ldq, const u16* __restrict__ Kp, const u16* __restrict__ Vtp, int ldv,
;                     int nkt, int q0, float c, u16* Yp, int ldy, char* smem, bool dry) {
;     ...
;     if (__builtin_amdgcn_ballot_w64((mx - m) * c > 8.f) != 0ull) {
;       const float mn = fmaxf(m, mx);
;       const float alpha = ex2((m - mn) * c);
;       m = mn;
;       l *= alpha;
; #pragma unroll
;       for (int dt = 0; dt < 4; ++dt)
; #pragma unroll
;         for (int e = 0; e < 16; ++e) o[dt][e] *= alpha;
;     }
	v_accvgpr_read_b32 v16, a48
	v_accvgpr_read_b32 v63, a47
	v_accvgpr_read_b32 v79, a31
	v_accvgpr_read_b32 v95, a15
	v_accvgpr_read_b32 v17, a49
	v_accvgpr_read_b32 v18, a50
	v_accvgpr_read_b32 v19, a51
	v_accvgpr_read_b32 v20, a52
	v_accvgpr_read_b32 v21, a53
	v_accvgpr_read_b32 v22, a54
	v_accvgpr_read_b32 v23, a55
	v_accvgpr_read_b32 v24, a56
	v_accvgpr_read_b32 v25, a57
	v_accvgpr_read_b32 v26, a58
	v_accvgpr_read_b32 v27, a59
	v_accvgpr_read_b32 v28, a60
	v_accvgpr_read_b32 v29, a61
	v_accvgpr_read_b32 v30, a62
	v_accvgpr_read_b32 v31, a63
	v_accvgpr_read_b32 v62, a46
	v_accvgpr_read_b32 v61, a45
	v_accvgpr_read_b32 v60, a44
	v_accvgpr_read_b32 v59, a43
	v_accvgpr_read_b32 v58, a42
	v_accvgpr_read_b32 v57, a41
	v_accvgpr_read_b32 v56, a40
	v_accvgpr_read_b32 v55, a39
	v_accvgpr_read_b32 v54, a38
	v_accvgpr_read_b32 v53, a37
	v_accvgpr_read_b32 v52, a36
	v_accvgpr_read_b32 v51, a35
	v_accvgpr_read_b32 v50, a34
	v_accvgpr_read_b32 v49, a33
	v_accvgpr_read_b32 v48, a32
	v_accvgpr_read_b32 v78, a30
	v_accvgpr_read_b32 v77, a29
	v_accvgpr_read_b32 v76, a28
	v_accvgpr_read_b32 v75, a27
	v_accvgpr_read_b32 v74, a26
	v_accvgpr_read_b32 v73, a25
	v_accvgpr_read_b32 v72, a24
	v_accvgpr_read_b32 v71, a23
	v_accvgpr_read_b32 v70, a22
	v_accvgpr_read_b32 v69, a21
	v_accvgpr_read_b32 v68, a20
	v_accvgpr_read_b32 v67, a19
	v_accvgpr_read_b32 v66, a18
	v_accvgpr_read_b32 v65, a17
	v_accvgpr_read_b32 v64, a16
	v_accvgpr_read_b32 v94, a14
	v_accvgpr_read_b32 v93, a13
	v_accvgpr_read_b32 v92, a12
	v_accvgpr_read_b32 v91, a11
	v_accvgpr_read_b32 v90, a10
	v_accvgpr_read_b32 v89, a9
	v_accvgpr_read_b32 v88, a8
	v_accvgpr_read_b32 v87, a7
	v_accvgpr_read_b32 v86, a6
	v_accvgpr_read_b32 v85, a5
	v_accvgpr_read_b32 v84, a4
	v_accvgpr_read_b32 v83, a3
	v_accvgpr_read_b32 v82, a2
	v_accvgpr_read_b32 v81, a1
	v_accvgpr_read_b32 v80, a0
	v_max_f32_e32 v129, v129, v129
	v_max_f32_e32 v147, v216, v216
	v_max_f32_e32 v147, v147, v129
	v_sub_f32_e32 v129, v216, v147
	v_mul_f32_e32 v129, 0x3dd53b94, v129
	v_exp_f32_e32 v216, v129
	s_nop 0
	v_pk_mul_f32 v[80:81], v[80:81], v[216:217] op_sel_hi:[1,0]
	v_pk_mul_f32 v[64:65], v[64:65], v[216:217] op_sel_hi:[1,0]
	v_pk_mul_f32 v[48:49], v[48:49], v[216:217] op_sel_hi:[1,0]
	v_pk_mul_f32 v[30:31], v[30:31], v[216:217] op_sel_hi:[1,0]
	v_pk_mul_f32 v[94:95], v[94:95], v[216:217] op_sel_hi:[1,0]
	v_pk_mul_f32 v[92:93], v[92:93], v[216:217] op_sel_hi:[1,0]
	v_pk_mul_f32 v[90:91], v[90:91], v[216:217] op_sel_hi:[1,0]
	v_pk_mul_f32 v[88:89], v[88:89], v[216:217] op_sel_hi:[1,0]
	v_pk_mul_f32 v[86:87], v[86:87], v[216:217] op_sel_hi:[1,0]
	v_pk_mul_f32 v[84:85], v[84:85], v[216:217] op_sel_hi:[1,0]
	v_pk_mul_f32 v[82:83], v[82:83], v[216:217] op_sel_hi:[1,0]
	v_pk_mul_f32 v[78:79], v[78:79], v[216:217] op_sel_hi:[1,0]
	v_accvgpr_write_b32 a0, v80
	v_pk_mul_f32 v[76:77], v[76:77], v[216:217] op_sel_hi:[1,0]
	v_pk_mul_f32 v[74:75], v[74:75], v[216:217] op_sel_hi:[1,0]
	v_pk_mul_f32 v[72:73], v[72:73], v[216:217] op_sel_hi:[1,0]
	v_pk_mul_f32 v[70:71], v[70:71], v[216:217] op_sel_hi:[1,0]
	v_pk_mul_f32 v[68:69], v[68:69], v[216:217] op_sel_hi:[1,0]
	v_pk_mul_f32 v[66:67], v[66:67], v[216:217] op_sel_hi:[1,0]
	v_pk_mul_f32 v[62:63], v[62:63], v[216:217] op_sel_hi:[1,0]
	v_accvgpr_write_b32 a16, v64
	v_pk_mul_f32 v[60:61], v[60:61], v[216:217] op_sel_hi:[1,0]
	v_pk_mul_f32 v[58:59], v[58:59], v[216:217] op_sel_hi:[1,0]
	v_pk_mul_f32 v[56:57], v[56:57], v[216:217] op_sel_hi:[1,0]
	v_pk_mul_f32 v[54:55], v[54:55], v[216:217] op_sel_hi:[1,0]
	v_pk_mul_f32 v[52:53], v[52:53], v[216:217] op_sel_hi:[1,0]
	v_pk_mul_f32 v[50:51], v[50:51], v[216:217] op_sel_hi:[1,0]
	v_pk_mul_f32 v[28:29], v[28:29], v[216:217] op_sel_hi:[1,0]
	v_accvgpr_write_b32 a32, v48
	v_pk_mul_f32 v[26:27], v[26:27], v[216:217] op_sel_hi:[1,0]
	v_pk_mul_f32 v[24:25], v[24:25], v[216:217] op_sel_hi:[1,0]
	v_pk_mul_f32 v[22:23], v[22:23], v[216:217] op_sel_hi:[1,0]
	v_pk_mul_f32 v[20:21], v[20:21], v[216:217] op_sel_hi:[1,0]
	v_pk_mul_f32 v[18:19], v[18:19], v[216:217] op_sel_hi:[1,0]
	v_pk_mul_f32 v[16:17], v[16:17], v[216:217] op_sel_hi:[1,0]
	v_pk_mul_f32 v[248:249], v[146:147], v[216:217]
	v_accvgpr_write_b32 a63, v31
	v_accvgpr_write_b32 a1, v81
	v_accvgpr_write_b32 a2, v82
	v_accvgpr_write_b32 a3, v83
	v_accvgpr_write_b32 a4, v84
	v_accvgpr_write_b32 a5, v85
	v_accvgpr_write_b32 a6, v86
	v_accvgpr_write_b32 a7, v87
	v_accvgpr_write_b32 a8, v88
	v_accvgpr_write_b32 a9, v89
	v_accvgpr_write_b32 a10, v90
	v_accvgpr_write_b32 a11, v91
	v_accvgpr_write_b32 a12, v92
	v_accvgpr_write_b32 a13, v93
	v_accvgpr_write_b32 a14, v94
	v_accvgpr_write_b32 a15, v95
	v_accvgpr_write_b32 a17, v65
	v_accvgpr_write_b32 a18, v66
	v_accvgpr_write_b32 a19, v67
	v_accvgpr_write_b32 a20, v68
	v_accvgpr_write_b32 a21, v69
	v_accvgpr_write_b32 a22, v70
	v_accvgpr_write_b32 a23, v71
	v_accvgpr_write_b32 a24, v72
	v_accvgpr_write_b32 a25, v73
	v_accvgpr_write_b32 a26, v74
	v_accvgpr_write_b32 a27, v75
	v_accvgpr_write_b32 a28, v76
	v_accvgpr_write_b32 a29, v77
	v_accvgpr_write_b32 a30, v78
	v_accvgpr_write_b32 a31, v79
	v_accvgpr_write_b32 a33, v49
	v_accvgpr_write_b32 a34, v50
	v_accvgpr_write_b32 a35, v51
	v_accvgpr_write_b32 a36, v52
	v_accvgpr_write_b32 a37, v53
	v_accvgpr_write_b32 a38, v54
	v_accvgpr_write_b32 a39, v55
	v_accvgpr_write_b32 a40, v56
	v_accvgpr_write_b32 a41, v57
	v_accvgpr_write_b32 a42, v58
	v_accvgpr_write_b32 a43, v59
	v_accvgpr_write_b32 a44, v60
	v_accvgpr_write_b32 a45, v61
	v_accvgpr_write_b32 a46, v62
	v_accvgpr_write_b32 a47, v63
	v_accvgpr_write_b32 a62, v30
	v_accvgpr_write_b32 a61, v29
	v_accvgpr_write_b32 a60, v28
	v_accvgpr_write_b32 a59, v27
	v_accvgpr_write_b32 a58, v26
	v_accvgpr_write_b32 a57, v25
	v_accvgpr_write_b32 a56, v24
	v_accvgpr_write_b32 a55, v23
	v_accvgpr_write_b32 a54, v22
	v_accvgpr_write_b32 a53, v21
	v_accvgpr_write_b32 a52, v20
	v_accvgpr_write_b32 a51, v19
	v_accvgpr_write_b32 a50, v18
	v_accvgpr_write_b32 a49, v17
	v_accvgpr_write_b32 a48, v16
	v_mov_b32_e32 v216, v147
	v_mov_b32_e32 v146, v248
; #define MFMA32(a, b, c) __builtin_amdgcn_mfma_f32_32x32x16_bf16((a), (b), (c), 0, 0, 0)
; DI float ex2(float x) { return __builtin_amdgcn_exp2f(x); }
; template <int DQK>
; DI void attn_item_c(const u16* __restrict__ Qp, int ldq, const u16* __restrict__ Kp, const u16* __restrict__ Vtp, int ldv,
;                     int nkt, int q0, float c, u16* Yp, int ldy, char* smem, bool dry) {
;     ...
;     const float mc = m * c;
; #pragma unroll
;     for (int e = 0; e < 16; ++e) { n0[e] = 0.f; n1[e] = 0.f; }
;     const u16* k0 = Ks + r * KLD + 8 * h;
;     bf16x8 ka[3][2];
;     ka[0][0] = *(const bf16x8*)(k0); ka[0][1] = *(const bf16x8*)(k0 + 32 * KLD);
;     ka[1][0] = *(const bf16x8*)(k0 + 16); ka[1][1] = *(const bf16x8*)(k0 + 32 * KLD + 16);
;     bf16x8 pf[4];
;     u32x4 pk[4];
;     float ps = 0.f;
; #pragma unroll
;     for (int ks = 0; ks < NKS; ++ks) {
;       if (ks + 2 < NKS) {
;         ka[(ks + 2) % 3][0] = *(const bf16x8*)(k0 + 16 * (ks + 2));
;         ka[(ks + 2) % 3][1] = *(const bf16x8*)(k0 + 32 * KLD + 16 * (ks + 2));
;       }
;       __builtin_amdgcn_sched_barrier(0);
;       n0 = MFMA32(ka[ks % 3][0], qf[ks], n0); n1 = MFMA32(ka[ks % 3][1], qf[ks], n1);
;       {
;         constexpr int dummy0 = 0; (void)dummy0;
;         const int e_lo = (32 * ks) / NKS, e_hi = (32 * (ks + 1)) / NKS;
; #pragma unroll
;         for (int q = 0; q < 3; ++q) {
;           const int e = e_lo + q;
;           if (e < e_hi) {
;             if (e < 16) { s0[e & 15] = ex2(fmaf(s0[e & 15], c, -mc)); ps += s0[e & 15]; }
;             else        { s1[e & 15] = ex2(fmaf(s1[e & 15], c, -mc)); ps += s1[e & 15]; }
;           }
;         }
;       }
.LBB0_224:
	ds_read_b128 v[18:21], v235 offset:44032
	ds_read_b128 v[22:25], v235 offset:44064
	ds_read_b128 v[26:29], v235 offset:56832
	ds_read_b128 v[48:51], v235 offset:44096
	ds_read_b128 v[52:55], v235 offset:56864
	ds_read_b128 v[56:59], v235 offset:56896
	v_accvgpr_read_b32 v17, a238
	v_mov_b32_e32 v16, v249
	v_cmp_le_i32_e32 vcc, s20, v17
	s_waitcnt lgkmcnt(5)
	v_mfma_f32_32x32x16_bf16 a[80:95], v[18:21], v[96:99], 0
	v_fmamk_f32 v17, v32, 0x3dd53b94, v16
	v_exp_f32_e32 v147, v17
	v_fmamk_f32 v17, v33, 0x3dd53b94, v16
	v_exp_f32_e32 v148, v17
	s_waitcnt lgkmcnt(3)
	v_mfma_f32_32x32x16_bf16 a[64:79], v[26:29], v[96:99], 0
	ds_read_b128 v[18:21], v235 offset:44128
	ds_read_b128 v[26:29], v235 offset:56928
	v_mfma_f32_32x32x16_bf16 a[80:95], v[22:25], v[100:103], a[80:95]
	v_fmamk_f32 v17, v34, 0x3dd53b94, v16
	v_exp_f32_e32 v149, v17
	v_fmamk_f32 v17, v35, 0x3dd53b94, v16
	v_exp_f32_e32 v150, v17
	v_fmamk_f32 v17, v36, 0x3dd53b94, v16
	v_exp_f32_e32 v151, v17
	s_waitcnt lgkmcnt(3)
	v_mfma_f32_32x32x16_bf16 a[64:79], v[52:55], v[100:103], a[64:79]
	ds_read_b128 v[22:25], v235 offset:44160
	ds_read_b128 v[30:33], v235 offset:56960
	v_mfma_f32_32x32x16_bf16 a[80:95], v[48:51], v[104:107], a[80:95]
	v_fmamk_f32 v17, v37, 0x3dd53b94, v16
	v_exp_f32_e32 v152, v17
	v_fmamk_f32 v17, v38, 0x3dd53b94, v16
	v_exp_f32_e32 v153, v17
	v_fmamk_f32 v17, v39, 0x3dd53b94, v16
	v_exp_f32_e32 v154, v17
	s_waitcnt lgkmcnt(4)
	v_mfma_f32_32x32x16_bf16 a[64:79], v[56:59], v[104:107], a[64:79]
	ds_read_b128 v[34:37], v235 offset:44192
	ds_read_b128 v[48:51], v235 offset:56992
	s_waitcnt lgkmcnt(5)
	v_mfma_f32_32x32x16_bf16 a[80:95], v[18:21], v[108:111], a[80:95]
	v_fmamk_f32 v17, v40, 0x3dd53b94, v16
	v_exp_f32_e32 v155, v17
	v_fmamk_f32 v17, v41, 0x3dd53b94, v16
	v_exp_f32_e32 v156, v17
	s_waitcnt lgkmcnt(4)
	v_mfma_f32_32x32x16_bf16 a[64:79], v[26:29], v[108:111], a[64:79]
	ds_read_b128 v[18:21], v235 offset:44224
	ds_read_b128 v[26:29], v235 offset:57024
	s_waitcnt lgkmcnt(5)
	v_mfma_f32_32x32x16_bf16 a[80:95], v[22:25], v[112:115], a[80:95]
	v_fmamk_f32 v17, v42, 0x3dd53b94, v16
	v_exp_f32_e32 v157, v17
	v_fmamk_f32 v17, v43, 0x3dd53b94, v16
	v_exp_f32_e32 v158, v17
	v_fmamk_f32 v17, v44, 0x3dd53b94, v16
	v_exp_f32_e32 v159, v17
	s_waitcnt lgkmcnt(4)
	v_mfma_f32_32x32x16_bf16 a[64:79], v[30:33], v[112:115], a[64:79]
	ds_read_b128 v[22:25], v235 offset:44256
	ds_read_b128 v[30:33], v235 offset:57056
	s_waitcnt lgkmcnt(5)
	v_mfma_f32_32x32x16_bf16 a[80:95], v[34:37], v[116:119], a[80:95]
	v_fmamk_f32 v17, v45, 0x3dd53b94, v16
	v_exp_f32_e32 v160, v17
	v_fmamk_f32 v17, v46, 0x3dd53b94, v16
	v_exp_f32_e32 v161, v17
	v_fmamk_f32 v17, v47, 0x3dd53b94, v16
	v_exp_f32_e32 v248, v17
	s_waitcnt lgkmcnt(4)
	v_mfma_f32_32x32x16_bf16 a[64:79], v[48:51], v[116:119], a[64:79]
	ds_read_b128 v[34:37], v235 offset:44288
	ds_read_b128 v[38:41], v235 offset:57088
	s_waitcnt lgkmcnt(5)
	v_mfma_f32_32x32x16_bf16 a[80:95], v[18:21], v[120:123], a[80:95]
	v_fmamk_f32 v0, v0, 0x3dd53b94, v16
	v_exp_f32_e32 v213, v0
	v_fmamk_f32 v0, v1, 0x3dd53b94, v16
	v_exp_f32_e32 v214, v0
	s_waitcnt lgkmcnt(4)
	v_mfma_f32_32x32x16_bf16 a[64:79], v[26:29], v[120:123], a[64:79]
	ds_read_b128 v[18:21], v235 offset:44320
	ds_read_b128 v[26:29], v235 offset:57120
	s_waitcnt lgkmcnt(5)
	v_mfma_f32_32x32x16_bf16 a[80:95], v[22:25], v[124:127], a[80:95]
	v_fmamk_f32 v0, v2, 0x3dd53b94, v16
	v_exp_f32_e32 v129, v0
	v_fmamk_f32 v0, v3, 0x3dd53b94, v16
	v_exp_f32_e32 v215, v0
	v_fmamk_f32 v0, v4, 0x3dd53b94, v16
	v_exp_f32_e32 v227, v0
	s_waitcnt lgkmcnt(4)
	v_mfma_f32_32x32x16_bf16 a[64:79], v[30:33], v[124:127], a[64:79]
	ds_read_b128 v[0:3], v235 offset:44352
	ds_read_b128 v[22:25], v235 offset:57152
	s_waitcnt lgkmcnt(5)
	v_mfma_f32_32x32x16_bf16 a[80:95], v[34:37], v[130:133], a[80:95]
	v_fmamk_f32 v4, v5, 0x3dd53b94, v16
	v_exp_f32_e32 v228, v4
	v_fmamk_f32 v4, v6, 0x3dd53b94, v16
	v_exp_f32_e32 v229, v4
	v_fmamk_f32 v4, v7, 0x3dd53b94, v16
	v_exp_f32_e32 v230, v4
	s_waitcnt lgkmcnt(4)
	v_mfma_f32_32x32x16_bf16 a[64:79], v[38:41], v[130:133], a[64:79]
	ds_read_b128 v[4:7], v235 offset:44384
	ds_read_b128 v[30:33], v235 offset:57184
	s_waitcnt lgkmcnt(5)
	v_mfma_f32_32x32x16_bf16 a[80:95], v[18:21], v[134:137], a[80:95]
	v_fmamk_f32 v8, v8, 0x3dd53b94, v16
	v_exp_f32_e32 v244, v8
	v_fmamk_f32 v8, v9, 0x3dd53b94, v16
	v_exp_f32_e32 v245, v8
	s_waitcnt lgkmcnt(4)
	v_mfma_f32_32x32x16_bf16 a[64:79], v[26:29], v[134:137], a[64:79]
	s_waitcnt lgkmcnt(3)
	v_mfma_f32_32x32x16_bf16 a[80:95], v[0:3], v[138:141], a[80:95]
	v_fmamk_f32 v0, v10, 0x3dd53b94, v16
	v_exp_f32_e32 v246, v0
	v_fmamk_f32 v0, v11, 0x3dd53b94, v16
	v_exp_f32_e32 v247, v0
	v_fmamk_f32 v0, v12, 0x3dd53b94, v16
	v_exp_f32_e32 v162, v0
	s_waitcnt lgkmcnt(2)
	v_mfma_f32_32x32x16_bf16 a[64:79], v[22:25], v[138:141], a[64:79]
	s_waitcnt lgkmcnt(1)
	v_mfma_f32_32x32x16_bf16 a[80:95], v[4:7], v[142:145], a[80:95]
	v_fmamk_f32 v0, v13, 0x3dd53b94, v16
	v_exp_f32_e32 v231, v0
	v_fmamk_f32 v0, v14, 0x3dd53b94, v16
	v_fmac_f32_e32 v16, 0x3dd53b94, v15
	v_exp_f32_e32 v234, v0
	v_exp_f32_e32 v218, v16
	s_waitcnt lgkmcnt(0)
	v_mfma_f32_32x32x16_bf16 a[64:79], v[30:33], v[142:145], a[64:79]
	s_and_saveexec_b64 s[0:1], vcc
	s_xor_b64 s[0:1], exec, s[0:1]
	s_cbranch_execz .LBB0_226
; #define MFMA32(a, b, c) __builtin_amdgcn_mfma_f32_32x32x16_bf16((a), (b), (c), 0, 0, 0)
; template <int DQK>
; DI void attn_item_c(const u16* __restrict__ Qp, int ldq, const u16* __restrict__ Kp, const u16* __restrict__ Vtp, int ldv,
;                     int nkt, int q0, float c, u16* Yp, int ldy, char* smem, bool dry) {
;     ...
;   auto gload = [&](u32x4* ks_, u32x4* vs_, int j) {
;     const u16* kg = Kp + (size_t)(j + 1) * 64 * DQK;
; #pragma unroll
;     for (int i = 0; i < NKC; ++i) ks_[i] = *(const u32x4*)(kg + (size_t)(tid + 256 * i) * 8);
; #pragma unroll
;     for (int i = 0; i < 4; ++i) vs_[i] = *(const u32x4*)(Vtp + (size_t)j * 8192 + (size_t)(tid + 256 * i) * 8);
;   };
;   auto lstore = [&](const u32x4* ks_, const u32x4* vs_, u16* Lb) {
; #pragma unroll
;     for (int i = 0; i < NKC; ++i) *(u32x4*)(Lb + kso[i]) = ks_[i];
; #pragma unroll
;     for (int i = 0; i < 4; ++i) {
;       u16* dst = Lb + vso + (32 * i) * 72;
;       u32x2 lo = {vs_[i].x, vs_[i].y}, hi = {vs_[i].z, vs_[i].w};
;       *(u32x2*)dst = lo; *(u32x2*)(dst + 8) = hi;
;     }
;   };
;     ...
;     if (active) {
;       const u16* v0 = Vs + r * 72 + 8 * h;
;       bf16x8 va[2][4];
; #pragma unroll
;       for (int dt = 0; dt < 4; ++dt) va[0][dt] = *(const bf16x8*)(v0 + (32 * dt) * 72);
; #pragma unroll
;       for (int kk = 0; kk < 4; ++kk) {
;         if (kk < 3) {
; #pragma unroll
;           for (int dt = 0; dt < 4; ++dt) va[(kk + 1) & 1][dt] = *(const bf16x8*)(v0 + (32 * dt) * 72 + 16 * (kk + 1));
;         }
;         __builtin_amdgcn_sched_barrier(0);
; #pragma unroll
;         for (int dt = 0; dt < 4; ++dt) o[dt] = MFMA32(va[kk & 1][dt], pf[kk], o[dt]);
;         if (kk == 0) lstoreK(wk, Ln);
;         if (kk == 1) lstoreV(wv, Ln);
;         if (kk == 2) gloadK(wk, kt + 3);
;         if (kk == 3) gloadV(wv, kt + 3);
;         __builtin_amdgcn_sched_barrier(0);
;       }
;     } else {
;       lstore(wk, wv, Ln);
;       gload(wk, wv, kt + 3);
;     }
	ds_read_b128 v[16:19], v250
	ds_read_b128 v[20:23], v250 offset:32
	ds_read_b128 v[24:27], v250 offset:4608
	ds_read_b128 v[28:31], v250 offset:4640
	ds_read_b128 v[32:35], v250 offset:9216
	ds_read_b128 v[36:39], v250 offset:9248
	ds_read_b128 v[40:43], v250 offset:13824
	ds_read_b128 v[44:47], v250 offset:13856
	s_add_i32 s20, s44, 4
	s_add_i32 s8, s44, 5
	v_cvt_pk_bf16_f32 v0, v244, v245
	v_cvt_pk_bf16_f32 v1, v246, v247
	v_cvt_pk_bf16_f32 v2, v162, v231
	v_cvt_pk_bf16_f32 v3, v234, v218
	v_cvt_pk_bf16_f32 v4, v213, v214
	v_cvt_pk_bf16_f32 v5, v129, v215
	v_cvt_pk_bf16_f32 v6, v227, v228
	v_cvt_pk_bf16_f32 v7, v229, v230
	v_cvt_pk_bf16_f32 v8, v155, v156
	v_cvt_pk_bf16_f32 v9, v157, v158
	v_cvt_pk_bf16_f32 v10, v159, v160
	v_cvt_pk_bf16_f32 v11, v161, v248
	v_cvt_pk_bf16_f32 v12, v147, v148
	v_cvt_pk_bf16_f32 v13, v149, v150
	v_cvt_pk_bf16_f32 v14, v151, v152
	v_cvt_pk_bf16_f32 v15, v153, v154
	s_lshl_b64 s[6:7], s[20:21], 14
	s_mul_hi_u32 s9, s8, 0x6000
	s_mulk_i32 s8, 0x6000
	s_waitcnt lgkmcnt(7)
	v_mfma_f32_32x32x16_bf16 a[0:15], v[16:19], v[12:15], a[0:15]
	s_waitcnt vmcnt(10)
	ds_write_b128 v221, a[120:123]
	ds_write_b128 v222, a[124:127]
	ds_write_b128 v223, a[132:135]
	ds_write_b128 v224, a[136:139]
	ds_write_b128 v225, a[140:143]
	ds_write_b128 v226, a[144:147]
	s_waitcnt lgkmcnt(11)
	v_mfma_f32_32x32x16_bf16 a[16:31], v[24:27], v[12:15], a[16:31]
	s_waitcnt lgkmcnt(9)
	v_mfma_f32_32x32x16_bf16 a[32:47], v[32:35], v[12:15], a[32:47]
	s_waitcnt lgkmcnt(7)
	v_mfma_f32_32x32x16_bf16 a[48:63], v[40:43], v[12:15], a[48:63]
	ds_read_b128 v[12:15], v250 offset:64
	ds_read_b128 v[16:19], v250 offset:4672
	ds_read_b128 v[24:27], v250 offset:9280
	ds_read_b128 v[32:35], v250 offset:13888
	v_mfma_f32_32x32x16_bf16 a[0:15], v[20:23], v[8:11], a[0:15]
	v_accvgpr_read_b32 v20, a229
	v_mfma_f32_32x32x16_bf16 a[16:31], v[28:31], v[8:11], a[16:31]
	v_accvgpr_read_b32 v28, a244
	v_accvgpr_read_b32 v29, a245
	v_accvgpr_read_b32 v30, a246
	v_accvgpr_read_b32 v31, a247
	ds_write2_b64 v20, v[28:29], v[30:31] offset0:128 offset1:130
	v_accvgpr_read_b32 v20, a234
	ds_write2_b64 v20, v[170:171], v[172:173] offset0:192 offset1:194
	v_mfma_f32_32x32x16_bf16 a[32:47], v[36:39], v[8:11], a[32:47]
	v_accvgpr_read_b32 v20, a235
	ds_write2_b64 v20, v[166:167], v[168:169] offset1:2
	v_accvgpr_read_b32 v20, a236
	ds_write2_b64 v20, v[174:175], v[176:177] offset0:64 offset1:66
	s_waitcnt lgkmcnt(14)
	v_mfma_f32_32x32x16_bf16 a[48:63], v[44:47], v[8:11], a[48:63]
	ds_read_b128 v[8:11], v250 offset:96
	ds_read_b128 v[20:23], v250 offset:4704
	ds_read_b128 v[28:31], v250 offset:9312
	ds_read_b128 v[36:39], v250 offset:13920
	s_add_u32 s8, s94, s8
	s_addc_u32 s9, s95, s9
	s_waitcnt lgkmcnt(11)
	v_mfma_f32_32x32x16_bf16 a[0:15], v[12:15], v[4:7], a[0:15]
	v_lshl_add_u64 v[12:13], s[8:9], 0, v[236:237]
	v_lshl_add_u64 v[14:15], s[8:9], 0, v[238:239]
	global_load_dwordx4 a[156:159], v[12:13], off
	global_load_dwordx4 a[164:167], v[14:15], off
	v_lshl_add_u64 v[12:13], s[8:9], 0, v[240:241]
	v_lshl_add_u64 v[14:15], s[8:9], 0, v[242:243]
	global_load_dwordx4 a[172:175], v[12:13], off
	global_load_dwordx4 a[180:183], v[14:15], off
	v_accvgpr_read_b32 v12, a230
	v_accvgpr_read_b32 v13, a231
	v_accvgpr_read_b32 v14, a232
	v_lshl_add_u64 v[12:13], s[8:9], 0, v[12:13]
	v_accvgpr_read_b32 v15, a233
	v_lshl_add_u64 v[14:15], s[8:9], 0, v[14:15]
	global_load_dwordx4 a[188:191], v[12:13], off
	global_load_dwordx4 a[192:195], v[14:15], off
	s_waitcnt lgkmcnt(10)
	v_mfma_f32_32x32x16_bf16 a[16:31], v[16:19], v[4:7], a[16:31]
	s_waitcnt lgkmcnt(9)
	v_mfma_f32_32x32x16_bf16 a[32:47], v[24:27], v[4:7], a[32:47]
	s_waitcnt lgkmcnt(8)
	v_mfma_f32_32x32x16_bf16 a[48:63], v[32:35], v[4:7], a[48:63]
	s_add_u32 s6, s60, s6
	s_addc_u32 s7, s61, s7
	s_waitcnt lgkmcnt(3)
	v_mfma_f32_32x32x16_bf16 a[0:15], v[8:11], v[0:3], a[0:15]
	s_waitcnt lgkmcnt(2)
	v_mfma_f32_32x32x16_bf16 a[16:31], v[20:23], v[0:3], a[16:31]
	s_waitcnt lgkmcnt(1)
	v_mfma_f32_32x32x16_bf16 a[32:47], v[28:31], v[0:3], a[32:47]
	s_waitcnt lgkmcnt(0)
	v_mfma_f32_32x32x16_bf16 a[48:63], v[36:39], v[0:3], a[48:63]
	v_lshl_add_u64 v[0:1], s[6:7], 0, v[236:237]
	global_load_dwordx4 v[190:193], v[0:1], off
	v_lshl_add_u64 v[0:1], s[6:7], 0, v[238:239]
	global_load_dwordx4 v[202:205], v[0:1], off
	v_lshl_add_u64 v[0:1], s[6:7], 0, v[240:241]
	global_load_dwordx4 v[198:201], v[0:1], off
	v_lshl_add_u64 v[0:1], s[6:7], 0, v[242:243]
	global_load_dwordx4 v[206:209], v[0:1], off
.LBB0_226:
	s_andn2_saveexec_b64 s[0:1], s[0:1]
	s_cbranch_execz .LBB0_228
	v_accvgpr_read_b32 v2, a244
	v_accvgpr_read_b32 v0, a229
	v_accvgpr_read_b32 v3, a245
	v_accvgpr_read_b32 v4, a246
	v_accvgpr_read_b32 v5, a247
	s_add_i32 s6, s44, 5
	s_waitcnt vmcnt(10)
	ds_write_b128 v221, a[120:123]
	ds_write_b128 v222, a[124:127]
	ds_write_b128 v223, a[132:135]
	ds_write_b128 v224, a[136:139]
	ds_write_b128 v225, a[140:143]
	ds_write_b128 v226, a[144:147]
	ds_write2_b64 v0, v[2:3], v[4:5] offset0:128 offset1:130
	v_accvgpr_read_b32 v0, a234
	s_add_i32 s20, s44, 4
	s_mul_hi_u32 s7, s6, 0x6000
	s_mulk_i32 s6, 0x6000
	ds_write2_b64 v0, v[170:171], v[172:173] offset0:192 offset1:194
	v_accvgpr_read_b32 v0, a235
	s_add_u32 s6, s94, s6
	ds_write2_b64 v0, v[166:167], v[168:169] offset1:2
	v_accvgpr_read_b32 v0, a236
	s_addc_u32 s7, s95, s7
	ds_write2_b64 v0, v[174:175], v[176:177] offset0:64 offset1:66
	v_lshl_add_u64 v[0:1], s[6:7], 0, v[236:237]
	global_load_dwordx4 a[156:159], v[0:1], off
	v_lshl_add_u64 v[0:1], s[6:7], 0, v[238:239]
	global_load_dwordx4 a[164:167], v[0:1], off
	v_lshl_add_u64 v[0:1], s[6:7], 0, v[240:241]
	global_load_dwordx4 a[172:175], v[0:1], off
	v_lshl_add_u64 v[0:1], s[6:7], 0, v[242:243]
	global_load_dwordx4 a[180:183], v[0:1], off
	v_accvgpr_read_b32 v0, a230
	v_accvgpr_read_b32 v1, a231
	v_lshl_add_u64 v[0:1], s[6:7], 0, v[0:1]
	global_load_dwordx4 a[188:191], v[0:1], off
	v_accvgpr_read_b32 v0, a232
	v_accvgpr_read_b32 v1, a233
	v_lshl_add_u64 v[0:1], s[6:7], 0, v[0:1]
	s_lshl_b64 s[6:7], s[20:21], 14
	s_add_u32 s6, s60, s6
	s_addc_u32 s7, s61, s7
	global_load_dwordx4 a[192:195], v[0:1], off
	v_lshl_add_u64 v[0:1], s[6:7], 0, v[236:237]
	global_load_dwordx4 v[190:193], v[0:1], off
	v_lshl_add_u64 v[0:1], s[6:7], 0, v[238:239]
	global_load_dwordx4 v[202:205], v[0:1], off
	v_lshl_add_u64 v[0:1], s[6:7], 0, v[240:241]
	global_load_dwordx4 v[198:201], v[0:1], off
	v_lshl_add_u64 v[0:1], s[6:7], 0, v[242:243]
	global_load_dwordx4 v[206:209], v[0:1], off
; DI int crow(int reg, int h) { return (reg & 3) + 8 * (reg >> 2) + 4 * h; }
; template <int DQK>
; DI void attn_item_c(const u16* __restrict__ Qp, int ldq, const u16* __restrict__ Kp, const u16* __restrict__ Vtp, int ldv,
;                     int nkt, int q0, float c, u16* Yp, int ldy, char* smem, bool dry) {
;     ...
;   auto body = [&](int kt, u32x4* wk, u32x4* wv, f32x16& s0, f32x16& s1, f32x16& n0, f32x16& n1) {
;     const u16* Ks = L0 + (kt & 1) * BUFE;
;     const u16* Vs = Ks + 64 * KLD;
;     u16* Ln = L0 + ((kt + 1) & 1) * BUFE;
;     const bool active = !(kt * 64 > qmin + 31);
;     if (kt * 64 + 63 > qmin) {
; #pragma unroll
;       for (int e = 0; e < 16; ++e) {
;         int key = kt * 64 + crow(e, h);
;         if (key > qi) s0[e] = -INFINITY;
;         if (key + 32 > qi) s1[e] = -INFINITY;
;       }
;     }
.LBB0_228:
	s_or_b64 exec, exec, s[0:1]
	s_nop 0
	s_or_b32 s0, s45, 0xbf
	s_or_b32 s20, s45, 0x80
	v_cmp_gt_i32_e32 vcc, s0, v233
	s_waitcnt lgkmcnt(0)
	s_barrier
	s_and_saveexec_b64 s[46:47], vcc
	s_cbranch_execz .LBB0_232
	v_accvgpr_read_b32 v0, a80
	v_accvgpr_read_b32 v32, a64
	v_accvgpr_read_b32 v1, a81
	v_accvgpr_read_b32 v2, a82
	v_accvgpr_read_b32 v3, a83
	v_accvgpr_read_b32 v4, a84
	v_accvgpr_read_b32 v5, a85
	v_accvgpr_read_b32 v6, a86
	v_accvgpr_read_b32 v7, a87
	v_accvgpr_read_b32 v8, a88
	v_accvgpr_read_b32 v9, a89
	v_accvgpr_read_b32 v10, a90
	v_accvgpr_read_b32 v11, a91
	v_accvgpr_read_b32 v12, a92
	v_accvgpr_read_b32 v13, a93
	v_accvgpr_read_b32 v14, a94
	v_accvgpr_read_b32 v15, a95
	v_accvgpr_read_b32 v33, a65
	v_accvgpr_read_b32 v34, a66
	v_accvgpr_read_b32 v35, a67
	v_accvgpr_read_b32 v36, a68
	v_accvgpr_read_b32 v37, a69
	v_accvgpr_read_b32 v38, a70
	v_accvgpr_read_b32 v39, a71
	v_accvgpr_read_b32 v40, a72
	v_accvgpr_read_b32 v41, a73
	v_accvgpr_read_b32 v42, a74
	v_accvgpr_read_b32 v43, a75
	v_accvgpr_read_b32 v44, a76
	v_accvgpr_read_b32 v45, a77
	v_accvgpr_read_b32 v46, a78
	v_accvgpr_read_b32 v47, a79
	v_accvgpr_read_b32 v163, a237
	v_or_b32_e32 v163, s20, v163
	v_or_b32_e32 v164, 32, v163
	v_cmp_le_i32_e64 s[0:1], v164, v212
	v_or_b32_e32 v164, 33, v163
	v_mov_b32_e32 v165, 0xff800000
	v_cmp_le_i32_e64 s[6:7], v164, v212
	v_or_b32_e32 v164, 2, v163
	v_cmp_le_i32_e32 vcc, v163, v212
	v_cndmask_b32_e64 v33, v165, v33, s[6:7]
	v_cmp_le_i32_e64 s[6:7], v164, v212
	v_or_b32_e32 v164, 34, v163
	v_cmp_le_i32_e64 s[8:9], v164, v212
	v_or_b32_e32 v164, 3, v163
	v_cndmask_b32_e64 v32, v165, v32, s[0:1]
	v_cndmask_b32_e64 v34, v165, v34, s[8:9]
	v_cmp_le_i32_e64 s[8:9], v164, v212
	v_or_b32_e32 v164, 35, v163
	v_cmp_le_i32_e64 s[10:11], v164, v212
	v_or_b32_e32 v164, 8, v163
	v_cmp_lt_i32_e64 s[0:1], v163, v212
	v_cndmask_b32_e64 v35, v165, v35, s[10:11]
	v_cmp_le_i32_e64 s[10:11], v164, v212
	v_or_b32_e32 v164, 40, v163
	v_cmp_le_i32_e64 s[12:13], v164, v212
	v_or_b32_e32 v164, 9, v163
	s_nop 0
	v_cndmask_b32_e64 v36, v165, v36, s[12:13]
	v_cmp_le_i32_e64 s[12:13], v164, v212
	v_or_b32_e32 v164, 41, v163
	v_cmp_le_i32_e64 s[14:15], v164, v212
	v_or_b32_e32 v164, 10, v163
	s_nop 0
	v_cndmask_b32_e64 v37, v165, v37, s[14:15]
	v_cmp_le_i32_e64 s[14:15], v164, v212
	v_or_b32_e32 v164, 42, v163
	v_cmp_le_i32_e64 s[16:17], v164, v212
	v_or_b32_e32 v164, 11, v163
	s_nop 0
	v_cndmask_b32_e64 v38, v165, v38, s[16:17]
	v_cmp_le_i32_e64 s[16:17], v164, v212
	v_or_b32_e32 v164, 43, v163
	v_cmp_le_i32_e64 s[18:19], v164, v212
	v_or_b32_e32 v164, 16, v163
	s_nop 0
	v_cndmask_b32_e64 v39, v165, v39, s[18:19]
	v_cmp_le_i32_e64 s[18:19], v164, v212
	v_or_b32_e32 v164, 48, v163
	v_cmp_le_i32_e64 s[22:23], v164, v212
	v_or_b32_e32 v164, 17, v163
	s_nop 0
	v_cndmask_b32_e64 v40, v165, v40, s[22:23]
	v_cmp_le_i32_e64 s[22:23], v164, v212
	v_or_b32_e32 v164, 49, v163
	v_cmp_le_i32_e64 s[24:25], v164, v212
	v_or_b32_e32 v164, 18, v163
	s_nop 0
	v_cndmask_b32_e64 v41, v165, v41, s[24:25]
	v_cmp_le_i32_e64 s[24:25], v164, v212
	v_or_b32_e32 v164, 50, v163
	v_cmp_le_i32_e64 s[26:27], v164, v212
	v_or_b32_e32 v164, 19, v163
	s_nop 0
	v_cndmask_b32_e64 v42, v165, v42, s[26:27]
	v_cmp_le_i32_e64 s[26:27], v164, v212
	v_or_b32_e32 v164, 51, v163
	v_cmp_le_i32_e64 s[28:29], v164, v212
	v_or_b32_e32 v164, 24, v163
	s_nop 0
	v_cndmask_b32_e64 v43, v165, v43, s[28:29]
	v_cmp_le_i32_e64 s[28:29], v164, v212
	v_or_b32_e32 v164, 56, v163
	v_cmp_le_i32_e64 s[30:31], v164, v212
	v_or_b32_e32 v164, 25, v163
	s_nop 0
	v_cndmask_b32_e64 v44, v165, v44, s[30:31]
	v_cmp_le_i32_e64 s[30:31], v164, v212
	v_or_b32_e32 v164, 57, v163
	v_cmp_le_i32_e64 s[34:35], v164, v212
	v_or_b32_e32 v164, 26, v163
	s_nop 0
	v_cndmask_b32_e64 v45, v165, v45, s[34:35]
	v_cmp_le_i32_e64 s[34:35], v164, v212
	v_or_b32_e32 v164, 58, v163
	v_cmp_le_i32_e64 s[36:37], v164, v212
	v_or_b32_e32 v164, 27, v163
	v_or_b32_e32 v163, 59, v163
	v_cndmask_b32_e64 v46, v165, v46, s[36:37]
	v_cmp_le_i32_e64 s[36:37], v164, v212
	v_cmp_gt_i32_e64 s[40:41], v163, v212
	s_and_saveexec_b64 s[48:49], s[40:41]
	v_mov_b32_e32 v47, s65
	s_or_b64 exec, exec, s[48:49]
	v_accvgpr_write_b32 a79, v47
	v_accvgpr_write_b32 a78, v46
	v_accvgpr_write_b32 a77, v45
	v_accvgpr_write_b32 a76, v44
	v_accvgpr_write_b32 a75, v43
	v_accvgpr_write_b32 a74, v42
	v_accvgpr_write_b32 a73, v41
	v_accvgpr_write_b32 a72, v40
	v_accvgpr_write_b32 a71, v39
	v_accvgpr_write_b32 a70, v38
	v_accvgpr_write_b32 a69, v37
	v_accvgpr_write_b32 a68, v36
	v_accvgpr_write_b32 a67, v35
	v_accvgpr_write_b32 a66, v34
	v_accvgpr_write_b32 a65, v33
	v_accvgpr_write_b32 a64, v32
	v_mov_b32_e32 v32, 0xff800000
	v_cndmask_b32_e64 v1, v32, v1, s[0:1]
	v_cndmask_b32_e32 v0, v32, v0, vcc
	v_cndmask_b32_e64 v2, v32, v2, s[6:7]
	v_cndmask_b32_e64 v3, v32, v3, s[8:9]
	v_cndmask_b32_e64 v4, v32, v4, s[10:11]
	v_cndmask_b32_e64 v5, v32, v5, s[12:13]
	v_cndmask_b32_e64 v6, v32, v6, s[14:15]
	v_cndmask_b32_e64 v7, v32, v7, s[16:17]
	v_cndmask_b32_e64 v8, v32, v8, s[18:19]
	v_cndmask_b32_e64 v9, v32, v9, s[22:23]
	v_cndmask_b32_e64 v10, v32, v10, s[24:25]
	v_cndmask_b32_e64 v11, v32, v11, s[26:27]
	v_cndmask_b32_e64 v12, v32, v12, s[28:29]
	v_cndmask_b32_e64 v13, v32, v13, s[30:31]
	v_cndmask_b32_e64 v14, v32, v14, s[34:35]
	v_cndmask_b32_e64 v15, v32, v15, s[36:37]
	v_accvgpr_write_b32 a80, v0
	v_accvgpr_write_b32 a81, v1
	v_accvgpr_write_b32 a82, v2
	v_accvgpr_write_b32 a83, v3
	v_accvgpr_write_b32 a84, v4
	v_accvgpr_write_b32 a85, v5
	v_accvgpr_write_b32 a86, v6
	v_accvgpr_write_b32 a87, v7
	v_accvgpr_write_b32 a88, v8
	v_accvgpr_write_b32 a89, v9
	v_accvgpr_write_b32 a90, v10
	v_accvgpr_write_b32 a91, v11
	v_accvgpr_write_b32 a92, v12
	v_accvgpr_write_b32 a93, v13
	v_accvgpr_write_b32 a94, v14
	v_accvgpr_write_b32 a95, v15
	s_mov_b64 s[40:41], s[70:71]
; DI float ex2(float x) { return __builtin_amdgcn_exp2f(x); }
; template <int DQK>
; DI void attn_item_c(const u16* __restrict__ Qp, int ldq, const u16* __restrict__ Kp, const u16* __restrict__ Vtp, int ldv,
;                     int nkt, int q0, float c, u16* Yp, int ldy, char* smem, bool dry) {
;     ...
;     float mx = fmaxf(s0[0], s1[0]);
; #pragma unroll
;     for (int e = 1; e < 16; ++e) mx = fmaxf(fmaxf(mx, s0[e]), s1[e]);
;     mx = fmaxf(mx, __shfl_xor(mx, 32));
;     if (__builtin_amdgcn_ballot_w64((mx - m) * c > 8.f) != 0ull) {
;       const float mn = fmaxf(m, mx);
;       const float alpha = ex2((m - mn) * c);
;       m = mn;
;       l *= alpha;
; #pragma unroll
;       for (int dt = 0; dt < 4; ++dt)
; #pragma unroll
;         for (int e = 0; e < 16; ++e) o[dt][e] *= alpha;
;     }
;     ...
;     l += ps;
.LBB0_232:
	s_or_b64 exec, exec, s[46:47]
	v_add_f32_e32 v147, 0, v147
	v_add_f32_e32 v147, v148, v147
	v_add_f32_e32 v147, v149, v147
	v_add_f32_e32 v147, v150, v147
	v_add_f32_e32 v147, v151, v147
	v_add_f32_e32 v147, v152, v147
	v_add_f32_e32 v147, v153, v147
	v_add_f32_e32 v147, v154, v147
	v_add_f32_e32 v147, v155, v147
	v_add_f32_e32 v147, v156, v147
	v_add_f32_e32 v147, v157, v147
	v_add_f32_e32 v147, v158, v147
	v_add_f32_e32 v147, v159, v147
	v_add_f32_e32 v147, v160, v147
	v_add_f32_e32 v147, v161, v147
	v_add_f32_e32 v147, v248, v147
	v_add_f32_e32 v147, v213, v147
	v_accvgpr_read_b32 v32, a80
	v_accvgpr_read_b32 v0, a64
	v_add_f32_e32 v147, v214, v147
	v_add_f32_e32 v129, v129, v147
	v_max_f32_e32 v147, v0, v0
	v_max_f32_e32 v148, v32, v32
	v_accvgpr_read_b32 v33, a81
	v_accvgpr_read_b32 v1, a65
	v_max_f32_e32 v147, v148, v147
	v_accvgpr_read_b32 v34, a82
	v_accvgpr_read_b32 v2, a66
	v_max3_f32 v147, v147, v33, v1
	v_accvgpr_read_b32 v35, a83
	v_accvgpr_read_b32 v3, a67
	v_max3_f32 v147, v147, v34, v2
	v_accvgpr_read_b32 v36, a84
	v_accvgpr_read_b32 v4, a68
	v_max3_f32 v147, v147, v35, v3
	v_accvgpr_read_b32 v37, a85
	v_accvgpr_read_b32 v5, a69
	v_max3_f32 v147, v147, v36, v4
	v_accvgpr_read_b32 v38, a86
	v_accvgpr_read_b32 v6, a70
	v_max3_f32 v147, v147, v37, v5
	v_accvgpr_read_b32 v39, a87
	v_accvgpr_read_b32 v7, a71
	v_max3_f32 v147, v147, v38, v6
	v_accvgpr_read_b32 v40, a88
	v_accvgpr_read_b32 v8, a72
	v_max3_f32 v147, v147, v39, v7
	v_accvgpr_read_b32 v41, a89
	v_accvgpr_read_b32 v9, a73
	v_add_f32_e32 v129, v215, v129
	v_max3_f32 v147, v147, v40, v8
	v_accvgpr_read_b32 v42, a90
	v_accvgpr_read_b32 v10, a74
	v_add_f32_e32 v129, v227, v129
	v_max3_f32 v147, v147, v41, v9
	v_accvgpr_read_b32 v43, a91
	v_accvgpr_read_b32 v11, a75
	v_add_f32_e32 v129, v228, v129
	v_max3_f32 v147, v147, v42, v10
	v_accvgpr_read_b32 v44, a92
	v_accvgpr_read_b32 v12, a76
	v_add_f32_e32 v129, v229, v129
	v_max3_f32 v147, v147, v43, v11
	v_accvgpr_read_b32 v45, a93
	v_accvgpr_read_b32 v13, a77
	v_add_f32_e32 v129, v230, v129
	v_max3_f32 v147, v147, v44, v12
	v_accvgpr_read_b32 v46, a94
	v_accvgpr_read_b32 v14, a78
	v_add_f32_e32 v129, v244, v129
	v_max3_f32 v147, v147, v45, v13
	v_accvgpr_read_b32 v47, a95
	v_accvgpr_read_b32 v15, a79
	v_add_f32_e32 v129, v245, v129
	v_max3_f32 v147, v147, v46, v14
	v_add_f32_e32 v129, v246, v129
	v_max3_f32 v147, v147, v47, v15
	v_add_f32_e32 v129, v247, v129
	ds_bpermute_b32 v148, v232, v147
	v_add_f32_e32 v129, v162, v129
	v_add_f32_e32 v129, v231, v129
	v_add_f32_e32 v129, v234, v129
	v_add_f32_e32 v129, v218, v129
	v_add_f32_e32 v248, v146, v129
	s_waitcnt lgkmcnt(0)
	v_max_f32_e32 v129, v148, v148
	v_max_f32_e32 v129, v147, v129
	v_sub_f32_e32 v146, v129, v216
	v_mul_f32_e32 v146, 0x3dd53b94, v146
	v_cmp_lt_f32_e32 vcc, s33, v146
	s_cbranch_vccz .LBB0_234
	v_accvgpr_read_b32 v16, a48
	v_accvgpr_read_b32 v63, a47
	v_accvgpr_read_b32 v79, a31
	v_accvgpr_read_b32 v95, a15
	v_accvgpr_read_b32 v17, a49
	v_accvgpr_read_b32 v18, a50
	v_accvgpr_read_b32 v19, a51
	v_accvgpr_read_b32 v20, a52
	v_accvgpr_read_b32 v21, a53
	v_accvgpr_read_b32 v22, a54
	v_accvgpr_read_b32 v23, a55
	v_accvgpr_read_b32 v24, a56
	v_accvgpr_read_b32 v25, a57
	v_accvgpr_read_b32 v26, a58
	v_accvgpr_read_b32 v27, a59
	v_accvgpr_read_b32 v28, a60
	v_accvgpr_read_b32 v29, a61
	v_accvgpr_read_b32 v30, a62
	v_accvgpr_read_b32 v31, a63
	v_accvgpr_read_b32 v62, a46
	v_accvgpr_read_b32 v61, a45
	v_accvgpr_read_b32 v60, a44
	v_accvgpr_read_b32 v59, a43
	v_accvgpr_read_b32 v58, a42
	v_accvgpr_read_b32 v57, a41
	v_accvgpr_read_b32 v56, a40
	v_accvgpr_read_b32 v55, a39
	v_accvgpr_read_b32 v54, a38
	v_accvgpr_read_b32 v53, a37
	v_accvgpr_read_b32 v52, a36
	v_accvgpr_read_b32 v51, a35
	v_accvgpr_read_b32 v50, a34
	v_accvgpr_read_b32 v49, a33
	v_accvgpr_read_b32 v48, a32
	v_accvgpr_read_b32 v78, a30
	v_accvgpr_read_b32 v77, a29
	v_accvgpr_read_b32 v76, a28
	v_accvgpr_read_b32 v75, a27
	v_accvgpr_read_b32 v74, a26
	v_accvgpr_read_b32 v73, a25
	v_accvgpr_read_b32 v72, a24
	v_accvgpr_read_b32 v71, a23
	v_accvgpr_read_b32 v70, a22
	v_accvgpr_read_b32 v69, a21
	v_accvgpr_read_b32 v68, a20
	v_accvgpr_read_b32 v67, a19
	v_accvgpr_read_b32 v66, a18
	v_accvgpr_read_b32 v65, a17
	v_accvgpr_read_b32 v64, a16
	v_accvgpr_read_b32 v94, a14
	v_accvgpr_read_b32 v93, a13
	v_accvgpr_read_b32 v92, a12
	v_accvgpr_read_b32 v91, a11
	v_accvgpr_read_b32 v90, a10
	v_accvgpr_read_b32 v89, a9
	v_accvgpr_read_b32 v88, a8
	v_accvgpr_read_b32 v87, a7
	v_accvgpr_read_b32 v86, a6
	v_accvgpr_read_b32 v85, a5
	v_accvgpr_read_b32 v84, a4
	v_accvgpr_read_b32 v83, a3
	v_accvgpr_read_b32 v82, a2
	v_accvgpr_read_b32 v81, a1
	v_accvgpr_read_b32 v80, a0
	v_max_f32_e32 v129, v129, v129
	v_max_f32_e32 v146, v216, v216
	v_max_f32_e32 v249, v146, v129
	v_sub_f32_e32 v129, v216, v249
	v_mul_f32_e32 v129, 0x3dd53b94, v129
	v_exp_f32_e32 v216, v129
	s_nop 0
	v_pk_mul_f32 v[30:31], v[30:31], v[216:217] op_sel_hi:[1,0]
	v_pk_mul_f32 v[80:81], v[80:81], v[216:217] op_sel_hi:[1,0]
	v_pk_mul_f32 v[64:65], v[64:65], v[216:217] op_sel_hi:[1,0]
	v_pk_mul_f32 v[48:49], v[48:49], v[216:217] op_sel_hi:[1,0]
	v_pk_mul_f32 v[28:29], v[28:29], v[216:217] op_sel_hi:[1,0]
	v_pk_mul_f32 v[26:27], v[26:27], v[216:217] op_sel_hi:[1,0]
	v_pk_mul_f32 v[24:25], v[24:25], v[216:217] op_sel_hi:[1,0]
	v_pk_mul_f32 v[22:23], v[22:23], v[216:217] op_sel_hi:[1,0]
	v_pk_mul_f32 v[20:21], v[20:21], v[216:217] op_sel_hi:[1,0]
	v_pk_mul_f32 v[18:19], v[18:19], v[216:217] op_sel_hi:[1,0]
	v_pk_mul_f32 v[16:17], v[16:17], v[216:217] op_sel_hi:[1,0]
	v_pk_mul_f32 v[94:95], v[94:95], v[216:217] op_sel_hi:[1,0]
	v_accvgpr_write_b32 a63, v31
; #define MFMA32(a, b, c) __builtin_amdgcn_mfma_f32_32x32x16_bf16((a), (b), (c), 0, 0, 0)
; DI float ex2(float x) { return __builtin_amdgcn_exp2f(x); }
; template <int DQK>
; DI void attn_item_c(const u16* __restrict__ Qp, int ldq, const u16* __restrict__ Kp, const u16* __restrict__ Vtp, int ldv,
;                     int nkt, int q0, float c, u16* Yp, int ldy, char* smem, bool dry) {
;     ...
;       const float mn = fmaxf(m, mx);
;       const float alpha = ex2((m - mn) * c);
;       m = mn;
;       l *= alpha;
; #pragma unroll
;       for (int dt = 0; dt < 4; ++dt)
; #pragma unroll
;         for (int e = 0; e < 16; ++e) o[dt][e] *= alpha;
;     }
;     ...
; #pragma unroll
;     for (int ks = 0; ks < NKS; ++ks) {
;       if (ks + 2 < NKS) {
;         ka[(ks + 2) % 3][0] = *(const bf16x8*)(k0 + 16 * (ks + 2));
;         ka[(ks + 2) % 3][1] = *(const bf16x8*)(k0 + 32 * KLD + 16 * (ks + 2));
;       }
;       __builtin_amdgcn_sched_barrier(0);
;       n0 = MFMA32(ka[ks % 3][0], qf[ks], n0); n1 = MFMA32(ka[ks % 3][1], qf[ks], n1);
;       {
;         constexpr int dummy0 = 0; (void)dummy0;
;         const int e_lo = (32 * ks) / NKS, e_hi = (32 * (ks + 1)) / NKS;
; #pragma unroll
;         for (int q = 0; q < 3; ++q) {
;           const int e = e_lo + q;
;           if (e < e_hi) {
;             if (e < 16) { s0[e & 15] = ex2(fmaf(s0[e & 15], c, -mc)); ps += s0[e & 15]; }
;             else        { s1[e & 15] = ex2(fmaf(s1[e & 15], c, -mc)); ps += s1[e & 15]; }
;           }
;         }
;       }
	v_pk_mul_f32 v[92:93], v[92:93], v[216:217] op_sel_hi:[1,0]
	v_pk_mul_f32 v[90:91], v[90:91], v[216:217] op_sel_hi:[1,0]
	v_pk_mul_f32 v[88:89], v[88:89], v[216:217] op_sel_hi:[1,0]
	v_pk_mul_f32 v[86:87], v[86:87], v[216:217] op_sel_hi:[1,0]
	v_pk_mul_f32 v[84:85], v[84:85], v[216:217] op_sel_hi:[1,0]
	v_pk_mul_f32 v[82:83], v[82:83], v[216:217] op_sel_hi:[1,0]
	v_pk_mul_f32 v[78:79], v[78:79], v[216:217] op_sel_hi:[1,0]
	v_accvgpr_write_b32 a0, v80
	v_pk_mul_f32 v[76:77], v[76:77], v[216:217] op_sel_hi:[1,0]
	v_pk_mul_f32 v[74:75], v[74:75], v[216:217] op_sel_hi:[1,0]
	v_pk_mul_f32 v[72:73], v[72:73], v[216:217] op_sel_hi:[1,0]
	v_pk_mul_f32 v[70:71], v[70:71], v[216:217] op_sel_hi:[1,0]
	v_pk_mul_f32 v[68:69], v[68:69], v[216:217] op_sel_hi:[1,0]
	v_pk_mul_f32 v[66:67], v[66:67], v[216:217] op_sel_hi:[1,0]
	v_pk_mul_f32 v[62:63], v[62:63], v[216:217] op_sel_hi:[1,0]
	v_accvgpr_write_b32 a16, v64
	v_pk_mul_f32 v[60:61], v[60:61], v[216:217] op_sel_hi:[1,0]
	v_pk_mul_f32 v[58:59], v[58:59], v[216:217] op_sel_hi:[1,0]
	v_pk_mul_f32 v[56:57], v[56:57], v[216:217] op_sel_hi:[1,0]
	v_pk_mul_f32 v[54:55], v[54:55], v[216:217] op_sel_hi:[1,0]
	v_pk_mul_f32 v[52:53], v[52:53], v[216:217] op_sel_hi:[1,0]
	v_pk_mul_f32 v[50:51], v[50:51], v[216:217] op_sel_hi:[1,0]
	v_accvgpr_write_b32 a62, v30
	v_accvgpr_write_b32 a32, v48
	v_accvgpr_write_b32 a61, v29
	v_accvgpr_write_b32 a60, v28
	v_accvgpr_write_b32 a59, v27
	v_accvgpr_write_b32 a58, v26
	v_accvgpr_write_b32 a57, v25
	v_accvgpr_write_b32 a56, v24
	v_accvgpr_write_b32 a55, v23
	v_accvgpr_write_b32 a54, v22
	v_accvgpr_write_b32 a53, v21
	v_accvgpr_write_b32 a52, v20
	v_accvgpr_write_b32 a51, v19
	v_accvgpr_write_b32 a50, v18
	v_accvgpr_write_b32 a49, v17
	v_accvgpr_write_b32 a48, v16
	v_pk_mul_f32 v[16:17], v[248:249], v[216:217]
	v_accvgpr_write_b32 a1, v81
	v_accvgpr_write_b32 a2, v82
	v_accvgpr_write_b32 a3, v83
	v_accvgpr_write_b32 a4, v84
	v_accvgpr_write_b32 a5, v85
	v_accvgpr_write_b32 a6, v86
	v_accvgpr_write_b32 a7, v87
	v_accvgpr_write_b32 a8, v88
	v_accvgpr_write_b32 a9, v89
	v_accvgpr_write_b32 a10, v90
	v_accvgpr_write_b32 a11, v91
	v_accvgpr_write_b32 a12, v92
	v_accvgpr_write_b32 a13, v93
	v_accvgpr_write_b32 a14, v94
	v_accvgpr_write_b32 a15, v95
	v_accvgpr_write_b32 a17, v65
	v_accvgpr_write_b32 a18, v66
	v_accvgpr_write_b32 a19, v67
	v_accvgpr_write_b32 a20, v68
	v_accvgpr_write_b32 a21, v69
	v_accvgpr_write_b32 a22, v70
	v_accvgpr_write_b32 a23, v71
	v_accvgpr_write_b32 a24, v72
	v_accvgpr_write_b32 a25, v73
	v_accvgpr_write_b32 a26, v74
	v_accvgpr_write_b32 a27, v75
	v_accvgpr_write_b32 a28, v76
	v_accvgpr_write_b32 a29, v77
	v_accvgpr_write_b32 a30, v78
	v_accvgpr_write_b32 a31, v79
	v_accvgpr_write_b32 a33, v49
	v_accvgpr_write_b32 a34, v50
	v_accvgpr_write_b32 a35, v51
	v_accvgpr_write_b32 a36, v52
	v_accvgpr_write_b32 a37, v53
	v_accvgpr_write_b32 a38, v54
	v_accvgpr_write_b32 a39, v55
	v_accvgpr_write_b32 a40, v56
	v_accvgpr_write_b32 a41, v57
	v_accvgpr_write_b32 a42, v58
	v_accvgpr_write_b32 a43, v59
	v_accvgpr_write_b32 a44, v60
	v_accvgpr_write_b32 a45, v61
	v_accvgpr_write_b32 a46, v62
	v_accvgpr_write_b32 a47, v63
	v_mov_b32_e32 v216, v249
	v_mov_b64_e32 v[248:249], v[16:17]
.LBB0_234:
	ds_read_b128 v[16:19], v219
	ds_read_b128 v[20:23], v219 offset:32
	ds_read_b128 v[24:27], v219 offset:12800
	ds_read_b128 v[28:31], v219 offset:64
	ds_read_b128 v[48:51], v219 offset:12832
	ds_read_b128 v[52:55], v219 offset:12864
	v_accvgpr_read_b32 v56, a238
	v_cmp_le_i32_e32 vcc, s20, v56
	s_waitcnt lgkmcnt(5)
	v_mfma_f32_32x32x16_bf16 a[80:95], v[16:19], v[96:99], 0
	v_fmamk_f32 v16, v32, 0x3dd53b94, v249
	v_exp_f32_e32 v162, v16
	v_fmamk_f32 v16, v33, 0x3dd53b94, v249
	v_exp_f32_e32 v163, v16
	s_waitcnt lgkmcnt(3)
	v_mfma_f32_32x32x16_bf16 a[64:79], v[24:27], v[96:99], 0
	ds_read_b128 v[16:19], v219 offset:96
	ds_read_b128 v[24:27], v219 offset:12896
	v_mfma_f32_32x32x16_bf16 a[80:95], v[20:23], v[100:103], a[80:95]
	v_fmamk_f32 v20, v34, 0x3dd53b94, v249
	v_exp_f32_e32 v164, v20
	v_fmamk_f32 v20, v35, 0x3dd53b94, v249
	v_exp_f32_e32 v165, v20
	v_fmamk_f32 v20, v36, 0x3dd53b94, v249
	v_exp_f32_e32 v166, v20
	s_waitcnt lgkmcnt(3)
	v_mfma_f32_32x32x16_bf16 a[64:79], v[48:51], v[100:103], a[64:79]
	ds_read_b128 v[20:23], v219 offset:128
	ds_read_b128 v[32:35], v219 offset:12928
	v_mfma_f32_32x32x16_bf16 a[80:95], v[28:31], v[104:107], a[80:95]
	v_fmamk_f32 v28, v37, 0x3dd53b94, v249
	v_exp_f32_e32 v167, v28
	v_fmamk_f32 v28, v38, 0x3dd53b94, v249
	v_exp_f32_e32 v168, v28
	v_fmamk_f32 v28, v39, 0x3dd53b94, v249
	v_exp_f32_e32 v169, v28
	s_waitcnt lgkmcnt(4)
	v_mfma_f32_32x32x16_bf16 a[64:79], v[52:55], v[104:107], a[64:79]
	ds_read_b128 v[28:31], v219 offset:160
	ds_read_b128 v[36:39], v219 offset:12960
	s_waitcnt lgkmcnt(5)
	v_mfma_f32_32x32x16_bf16 a[80:95], v[16:19], v[108:111], a[80:95]
	v_fmamk_f32 v16, v40, 0x3dd53b94, v249
	v_exp_f32_e32 v170, v16
	v_fmamk_f32 v16, v41, 0x3dd53b94, v249
	v_exp_f32_e32 v171, v16
	s_waitcnt lgkmcnt(4)
	v_mfma_f32_32x32x16_bf16 a[64:79], v[24:27], v[108:111], a[64:79]
	ds_read_b128 v[16:19], v219 offset:192
	ds_read_b128 v[24:27], v219 offset:12992
	s_waitcnt lgkmcnt(5)
	v_mfma_f32_32x32x16_bf16 a[80:95], v[20:23], v[112:115], a[80:95]
	v_fmamk_f32 v20, v42, 0x3dd53b94, v249
	v_exp_f32_e32 v172, v20
	v_fmamk_f32 v20, v43, 0x3dd53b94, v249
	v_exp_f32_e32 v173, v20
	v_fmamk_f32 v20, v44, 0x3dd53b94, v249
	v_exp_f32_e32 v174, v20
	s_waitcnt lgkmcnt(4)
	v_mfma_f32_32x32x16_bf16 a[64:79], v[32:35], v[112:115], a[64:79]
	ds_read_b128 v[20:23], v219 offset:224
	ds_read_b128 v[32:35], v219 offset:13024
	s_waitcnt lgkmcnt(5)
; template <int DQK>
; DI void attn_item_c(const u16* __restrict__ Qp, int ldq, const u16* __restrict__ Kp, const u16* __restrict__ Vtp, int ldv,
;                     int nkt, int q0, float c, u16* Yp, int ldy, char* smem, bool dry) {
;     ...
; #pragma unroll
;     for (int ks = 0; ks < NKS; ++ks) {
;       if (ks + 2 < NKS) {
;         ka[(ks + 2) % 3][0] = *(const bf16x8*)(k0 + 16 * (ks + 2));
;         ka[(ks + 2) % 3][1] = *(const bf16x8*)(k0 + 32 * KLD + 16 * (ks + 2));
;       }
;       __builtin_amdgcn_sched_barrier(0);
;       n0 = MFMA32(ka[ks % 3][0], qf[ks], n0); n1 = MFMA32(ka[ks % 3][1], qf[ks], n1);
;       {
;         constexpr int dummy0 = 0; (void)dummy0;
;         const int e_lo = (32 * ks) / NKS, e_hi = (32 * (ks + 1)) / NKS;
; #pragma unroll
;         for (int q = 0; q < 3; ++q) {
;           const int e = e_lo + q;
;           if (e < e_hi) {
;             if (e < 16) { s0[e & 15] = ex2(fmaf(s0[e & 15], c, -mc)); ps += s0[e & 15]; }
;             else        { s1[e & 15] = ex2(fmaf(s1[e & 15], c, -mc)); ps += s1[e & 15]; }
;           }
;         }
;       }
;       if (ks == 3)  { pk[0].x = pack2(s0[0], s0[1]);  pk[0].y = pack2(s0[2], s0[3]);   pk[0].z = pack2(s0[4], s0[5]);   pk[0].w = pack2(s0[6], s0[7]); }
;       if (ks == 6)  { pk[1].x = pack2(s0[8], s0[9]);  pk[1].y = pack2(s0[10], s0[11]); pk[1].z = pack2(s0[12], s0[13]); pk[1].w = pack2(s0[14], s0[15]); }
;       if (ks == 9)  { pk[2].x = pack2(s1[0], s1[1]);  pk[2].y = pack2(s1[2], s1[3]);   pk[2].z = pack2(s1[4], s1[5]);   pk[2].w = pack2(s1[6], s1[7]); }
;       if (ks == NKS - 1) { pk[3].x = pack2(s1[8], s1[9]);  pk[3].y = pack2(s1[10], s1[11]); pk[3].z = pack2(s1[12], s1[13]); pk[3].w = pack2(s1[14], s1[15]); }
;       __builtin_amdgcn_sched_barrier(0);
;     }
;     l += ps;
; #pragma unroll
;     for (int i = 0; i < 4; ++i) pf[i] = __builtin_bit_cast(bf16x8, pk[i]);
;     if (active) {
;       const u16* v0 = Vs + r * 72 + 8 * h;
;       bf16x8 va[2][4];
; #pragma unroll
;       for (int dt = 0; dt < 4; ++dt) va[0][dt] = *(const bf16x8*)(v0 + (32 * dt) * 72);
; #pragma unroll
;       for (int kk = 0; kk < 4; ++kk) {
;         if (kk < 3) {
; #pragma unroll
;           for (int dt = 0; dt < 4; ++dt) va[(kk + 1) & 1][dt] = *(const bf16x8*)(v0 + (32 * dt) * 72 + 16 * (kk + 1));
;         }
;         __builtin_amdgcn_sched_barrier(0);
; #pragma unroll
	v_mfma_f32_32x32x16_bf16 a[80:95], v[28:31], v[116:119], a[80:95]
	v_fmamk_f32 v28, v45, 0x3dd53b94, v249
	v_exp_f32_e32 v175, v28
	v_fmamk_f32 v28, v46, 0x3dd53b94, v249
	v_exp_f32_e32 v176, v28
	v_fmamk_f32 v28, v47, 0x3dd53b94, v249
	v_exp_f32_e32 v177, v28
	s_waitcnt lgkmcnt(4)
	v_mfma_f32_32x32x16_bf16 a[64:79], v[36:39], v[116:119], a[64:79]
	ds_read_b128 v[28:31], v219 offset:256
	ds_read_b128 v[36:39], v219 offset:13056
	s_waitcnt lgkmcnt(5)
	v_mfma_f32_32x32x16_bf16 a[80:95], v[16:19], v[120:123], a[80:95]
	v_fmamk_f32 v0, v0, 0x3dd53b94, v249
	v_exp_f32_e32 v213, v0
	v_fmamk_f32 v0, v1, 0x3dd53b94, v249
	v_exp_f32_e32 v214, v0
	s_waitcnt lgkmcnt(4)
	v_mfma_f32_32x32x16_bf16 a[64:79], v[24:27], v[120:123], a[64:79]
	ds_read_b128 v[16:19], v219 offset:288
	ds_read_b128 v[24:27], v219 offset:13088
	s_waitcnt lgkmcnt(5)
	v_mfma_f32_32x32x16_bf16 a[80:95], v[20:23], v[124:127], a[80:95]
	v_fmamk_f32 v0, v2, 0x3dd53b94, v249
	v_exp_f32_e32 v215, v0
	v_fmamk_f32 v0, v3, 0x3dd53b94, v249
	v_exp_f32_e32 v129, v0
	v_fmamk_f32 v0, v4, 0x3dd53b94, v249
	v_exp_f32_e32 v227, v0
	s_waitcnt lgkmcnt(4)
	v_mfma_f32_32x32x16_bf16 a[64:79], v[32:35], v[124:127], a[64:79]
	ds_read_b128 v[0:3], v219 offset:320
	ds_read_b128 v[20:23], v219 offset:13120
	s_waitcnt lgkmcnt(5)
	v_mfma_f32_32x32x16_bf16 a[80:95], v[28:31], v[130:133], a[80:95]
	v_fmamk_f32 v4, v5, 0x3dd53b94, v249
	v_exp_f32_e32 v228, v4
	v_fmamk_f32 v4, v6, 0x3dd53b94, v249
	v_exp_f32_e32 v229, v4
	v_fmamk_f32 v4, v7, 0x3dd53b94, v249
	v_exp_f32_e32 v230, v4
	s_waitcnt lgkmcnt(4)
	v_mfma_f32_32x32x16_bf16 a[64:79], v[36:39], v[130:133], a[64:79]
	ds_read_b128 v[4:7], v219 offset:352
	ds_read_b128 v[28:31], v219 offset:13152
	s_waitcnt lgkmcnt(5)
	v_mfma_f32_32x32x16_bf16 a[80:95], v[16:19], v[134:137], a[80:95]
	v_fmamk_f32 v8, v8, 0x3dd53b94, v249
	v_exp_f32_e32 v147, v8
	v_fmamk_f32 v8, v9, 0x3dd53b94, v249
	v_exp_f32_e32 v148, v8
	s_waitcnt lgkmcnt(4)
	v_mfma_f32_32x32x16_bf16 a[64:79], v[24:27], v[134:137], a[64:79]
	s_waitcnt lgkmcnt(3)
	v_mfma_f32_32x32x16_bf16 a[80:95], v[0:3], v[138:141], a[80:95]
	v_fmamk_f32 v0, v10, 0x3dd53b94, v249
	v_exp_f32_e32 v149, v0
	v_fmamk_f32 v0, v11, 0x3dd53b94, v249
	v_exp_f32_e32 v218, v0
	v_fmamk_f32 v0, v12, 0x3dd53b94, v249
	v_exp_f32_e32 v244, v0
	s_waitcnt lgkmcnt(2)
	v_mfma_f32_32x32x16_bf16 a[64:79], v[20:23], v[138:141], a[64:79]
	s_waitcnt lgkmcnt(1)
	v_mfma_f32_32x32x16_bf16 a[80:95], v[4:7], v[142:145], a[80:95]
	v_fmamk_f32 v0, v13, 0x3dd53b94, v249
	v_exp_f32_e32 v231, v0
	v_fmamk_f32 v0, v14, 0x3dd53b94, v249
	v_exp_f32_e32 v234, v0
	v_fmamk_f32 v0, v15, 0x3dd53b94, v249
	v_exp_f32_e32 v146, v0
	s_waitcnt lgkmcnt(0)
	v_mfma_f32_32x32x16_bf16 a[64:79], v[28:31], v[142:145], a[64:79]
	s_and_saveexec_b64 s[0:1], vcc
	s_xor_b64 s[0:1], exec, s[0:1]
	s_cbranch_execz .LBB0_236
	ds_read_b128 v[16:19], v128 offset:25600
	ds_read_b128 v[20:23], v128 offset:25632
	ds_read_b128 v[24:27], v128 offset:30208
	ds_read_b128 v[28:31], v128 offset:30240
	ds_read_b128 v[32:35], v128 offset:34816
	ds_read_b128 v[36:39], v128 offset:34848
	ds_read_b128 v[40:43], v128 offset:39424
	ds_read_b128 v[44:47], v128 offset:39456
	s_add_i32 s20, s44, 5
	s_add_i32 s8, s44, 6
	v_cvt_pk_bf16_f32 v0, v147, v148
	v_cvt_pk_bf16_f32 v1, v149, v218
	v_cvt_pk_bf16_f32 v2, v244, v231
	v_cvt_pk_bf16_f32 v3, v234, v146
	v_cvt_pk_bf16_f32 v4, v213, v214
	v_cvt_pk_bf16_f32 v5, v215, v129
	v_cvt_pk_bf16_f32 v6, v227, v228
	v_cvt_pk_bf16_f32 v7, v229, v230
	v_cvt_pk_bf16_f32 v8, v170, v171
	v_cvt_pk_bf16_f32 v9, v172, v173
	v_cvt_pk_bf16_f32 v10, v174, v175
	v_cvt_pk_bf16_f32 v11, v176, v177
	v_cvt_pk_bf16_f32 v12, v162, v163
	v_cvt_pk_bf16_f32 v13, v164, v165
	v_cvt_pk_bf16_f32 v14, v166, v167
	v_cvt_pk_bf16_f32 v15, v168, v169
	s_lshl_b64 s[6:7], s[20:21], 14
	s_mul_hi_u32 s9, s8, 0x6000
	s_mulk_i32 s8, 0x6000
	s_waitcnt lgkmcnt(7)
	v_mfma_f32_32x32x16_bf16 a[0:15], v[16:19], v[12:15], a[0:15]
	s_waitcnt vmcnt(10)
	ds_write_b128 v221, a[148:151] offset:44032
	ds_write_b128 v222, a[152:155] offset:44032
	ds_write_b128 v223, a[160:163] offset:44032
	ds_write_b128 v224, a[168:171] offset:44032
	ds_write_b128 v225, a[176:179] offset:44032
	ds_write_b128 v226, a[184:187] offset:44032
	s_waitcnt lgkmcnt(11)
	v_mfma_f32_32x32x16_bf16 a[16:31], v[24:27], v[12:15], a[16:31]
	s_waitcnt lgkmcnt(9)
	v_mfma_f32_32x32x16_bf16 a[32:47], v[32:35], v[12:15], a[32:47]
	s_waitcnt lgkmcnt(7)
	v_mfma_f32_32x32x16_bf16 a[48:63], v[40:43], v[12:15], a[48:63]
	ds_read_b128 v[12:15], v128 offset:25664
	ds_read_b128 v[16:19], v128 offset:30272
	ds_read_b128 v[24:27], v128 offset:34880
	ds_read_b128 v[32:35], v128 offset:39488
	v_mfma_f32_32x32x16_bf16 a[0:15], v[20:23], v[8:11], a[0:15]
	ds_write2_b64 v220, v[178:179], v[180:181] offset1:2
	ds_write2_b64 v211, v[186:187], v[188:189] offset0:64 offset1:66
	ds_write2_b64 v251, v[182:183], v[184:185] offset0:128 offset1:130
	ds_write2_b64 v210, v[194:195], v[196:197] offset0:192 offset1:194
	v_mfma_f32_32x32x16_bf16 a[16:31], v[28:31], v[8:11], a[16:31]
	v_mfma_f32_32x32x16_bf16 a[32:47], v[36:39], v[8:11], a[32:47]
	s_waitcnt lgkmcnt(14)
	v_mfma_f32_32x32x16_bf16 a[48:63], v[44:47], v[8:11], a[48:63]
	ds_read_b128 v[8:11], v128 offset:25696
	ds_read_b128 v[20:23], v128 offset:30304
	ds_read_b128 v[28:31], v128 offset:34912
	ds_read_b128 v[36:39], v128 offset:39520
	s_add_u32 s8, s94, s8
	s_addc_u32 s9, s95, s9
	s_waitcnt lgkmcnt(11)
; #define MFMA32(a, b, c) __builtin_amdgcn_mfma_f32_32x32x16_bf16((a), (b), (c), 0, 0, 0)
; DI int crow(int reg, int h) { return (reg & 3) + 8 * (reg >> 2) + 4 * h; }
; template <int DQK>
; DI void attn_item_c(const u16* __restrict__ Qp, int ldq, const u16* __restrict__ Kp, const u16* __restrict__ Vtp, int ldv,
;                     int nkt, int q0, float c, u16* Yp, int ldy, char* smem, bool dry) {
;     ...
;   auto body = [&](int kt, u32x4* wk, u32x4* wv, f32x16& s0, f32x16& s1, f32x16& n0, f32x16& n1) {
;     const u16* Ks = L0 + (kt & 1) * BUFE;
;     const u16* Vs = Ks + 64 * KLD;
;     u16* Ln = L0 + ((kt + 1) & 1) * BUFE;
;     const bool active = !(kt * 64 > qmin + 31);
;     if (kt * 64 + 63 > qmin) {
; #pragma unroll
;       for (int e = 0; e < 16; ++e) {
;         int key = kt * 64 + crow(e, h);
;         if (key > qi) s0[e] = -INFINITY;
;         if (key + 32 > qi) s1[e] = -INFINITY;
;       }
;     }
;     ...
;     if (active) {
;       const u16* v0 = Vs + r * 72 + 8 * h;
;       bf16x8 va[2][4];
; #pragma unroll
;       for (int dt = 0; dt < 4; ++dt) va[0][dt] = *(const bf16x8*)(v0 + (32 * dt) * 72);
; #pragma unroll
;       for (int kk = 0; kk < 4; ++kk) {
;         if (kk < 3) {
; #pragma unroll
;           for (int dt = 0; dt < 4; ++dt) va[(kk + 1) & 1][dt] = *(const bf16x8*)(v0 + (32 * dt) * 72 + 16 * (kk + 1));
;         }
;         __builtin_amdgcn_sched_barrier(0);
; #pragma unroll
;         for (int dt = 0; dt < 4; ++dt) o[dt] = MFMA32(va[kk & 1][dt], pf[kk], o[dt]);
;         if (kk == 0) lstoreK(wk, Ln);
;         if (kk == 1) lstoreV(wv, Ln);
;         if (kk == 2) gloadK(wk, kt + 3);
;         if (kk == 3) gloadV(wv, kt + 3);
;         __builtin_amdgcn_sched_barrier(0);
;       }
;     } else {
;       lstore(wk, wv, Ln);
;       gload(wk, wv, kt + 3);
;     }
;     __syncthreads();
	v_mfma_f32_32x32x16_bf16 a[0:15], v[12:15], v[4:7], a[0:15]
	v_lshl_add_u64 v[12:13], s[8:9], 0, v[236:237]
	v_lshl_add_u64 v[14:15], s[8:9], 0, v[238:239]
	global_load_dwordx4 a[96:99], v[12:13], off
	global_load_dwordx4 a[100:103], v[14:15], off
	v_lshl_add_u64 v[12:13], s[8:9], 0, v[240:241]
	v_lshl_add_u64 v[14:15], s[8:9], 0, v[242:243]
	global_load_dwordx4 a[104:107], v[12:13], off
	global_load_dwordx4 a[108:111], v[14:15], off
	v_accvgpr_read_b32 v12, a230
	v_accvgpr_read_b32 v13, a231
	v_accvgpr_read_b32 v14, a232
	v_lshl_add_u64 v[12:13], s[8:9], 0, v[12:13]
	v_accvgpr_read_b32 v15, a233
	v_lshl_add_u64 v[14:15], s[8:9], 0, v[14:15]
	global_load_dwordx4 a[112:115], v[12:13], off
	global_load_dwordx4 a[116:119], v[14:15], off
	s_waitcnt lgkmcnt(10)
	v_mfma_f32_32x32x16_bf16 a[16:31], v[16:19], v[4:7], a[16:31]
	s_waitcnt lgkmcnt(9)
	v_mfma_f32_32x32x16_bf16 a[32:47], v[24:27], v[4:7], a[32:47]
	s_waitcnt lgkmcnt(8)
	v_mfma_f32_32x32x16_bf16 a[48:63], v[32:35], v[4:7], a[48:63]
	s_add_u32 s6, s60, s6
	s_addc_u32 s7, s61, s7
	s_waitcnt lgkmcnt(3)
	v_mfma_f32_32x32x16_bf16 a[0:15], v[8:11], v[0:3], a[0:15]
	s_waitcnt lgkmcnt(2)
	v_mfma_f32_32x32x16_bf16 a[16:31], v[20:23], v[0:3], a[16:31]
	s_waitcnt lgkmcnt(1)
	v_mfma_f32_32x32x16_bf16 a[32:47], v[28:31], v[0:3], a[32:47]
	s_waitcnt lgkmcnt(0)
	v_mfma_f32_32x32x16_bf16 a[48:63], v[36:39], v[0:3], a[48:63]
	v_lshl_add_u64 v[0:1], s[6:7], 0, v[236:237]
	global_load_dwordx4 a[240:243], v[0:1], off
	v_lshl_add_u64 v[0:1], s[6:7], 0, v[238:239]
	global_load_dwordx4 v[150:153], v[0:1], off
	v_lshl_add_u64 v[0:1], s[6:7], 0, v[240:241]
	global_load_dwordx4 v[154:157], v[0:1], off
	v_lshl_add_u64 v[0:1], s[6:7], 0, v[242:243]
	global_load_dwordx4 v[158:161], v[0:1], off
.LBB0_236:
	s_andn2_saveexec_b64 s[0:1], s[0:1]
	s_cbranch_execz .LBB0_238
	s_add_i32 s6, s44, 6
	s_add_i32 s20, s44, 5
	s_mul_hi_u32 s7, s6, 0x6000
	s_mulk_i32 s6, 0x6000
	s_add_u32 s6, s94, s6
	s_addc_u32 s7, s95, s7
	s_waitcnt vmcnt(10)
	ds_write_b128 v221, a[148:151] offset:44032
	ds_write_b128 v222, a[152:155] offset:44032
	ds_write_b128 v223, a[160:163] offset:44032
	ds_write_b128 v224, a[168:171] offset:44032
	ds_write_b128 v225, a[176:179] offset:44032
	ds_write_b128 v226, a[184:187] offset:44032
	ds_write2_b64 v220, v[178:179], v[180:181] offset1:2
	ds_write2_b64 v211, v[186:187], v[188:189] offset0:64 offset1:66
	ds_write2_b64 v251, v[182:183], v[184:185] offset0:128 offset1:130
	ds_write2_b64 v210, v[194:195], v[196:197] offset0:192 offset1:194
	v_lshl_add_u64 v[0:1], s[6:7], 0, v[236:237]
	global_load_dwordx4 a[96:99], v[0:1], off
	v_lshl_add_u64 v[0:1], s[6:7], 0, v[238:239]
	global_load_dwordx4 a[100:103], v[0:1], off
	v_lshl_add_u64 v[0:1], s[6:7], 0, v[240:241]
	global_load_dwordx4 a[104:107], v[0:1], off
	v_lshl_add_u64 v[0:1], s[6:7], 0, v[242:243]
	global_load_dwordx4 a[108:111], v[0:1], off
	v_accvgpr_read_b32 v0, a230
	v_accvgpr_read_b32 v1, a231
	v_lshl_add_u64 v[0:1], s[6:7], 0, v[0:1]
	global_load_dwordx4 a[112:115], v[0:1], off
	v_accvgpr_read_b32 v0, a232
	v_accvgpr_read_b32 v1, a233
	v_lshl_add_u64 v[0:1], s[6:7], 0, v[0:1]
	s_lshl_b64 s[6:7], s[20:21], 14
	s_add_u32 s6, s60, s6
	s_addc_u32 s7, s61, s7
	global_load_dwordx4 a[116:119], v[0:1], off
	v_lshl_add_u64 v[0:1], s[6:7], 0, v[236:237]
	global_load_dwordx4 a[240:243], v[0:1], off
	v_lshl_add_u64 v[0:1], s[6:7], 0, v[238:239]
	global_load_dwordx4 v[150:153], v[0:1], off
	v_lshl_add_u64 v[0:1], s[6:7], 0, v[240:241]
	global_load_dwordx4 v[154:157], v[0:1], off
	v_lshl_add_u64 v[0:1], s[6:7], 0, v[242:243]
	global_load_dwordx4 v[158:161], v[0:1], off
.LBB0_238:
	s_or_b64 exec, exec, s[0:1]
	s_nop 0
	s_or_b32 s0, s45, 0xff
	s_or_b32 s20, s45, 0xc0
	v_cmp_gt_i32_e32 vcc, s0, v233
	s_waitcnt lgkmcnt(0)
	s_barrier
	s_and_saveexec_b64 s[46:47], vcc
	s_cbranch_execz .LBB0_242
	v_accvgpr_read_b32 v0, a80
	v_accvgpr_read_b32 v32, a64
	v_accvgpr_read_b32 v1, a81
	v_accvgpr_read_b32 v2, a82
	v_accvgpr_read_b32 v3, a83
	v_accvgpr_read_b32 v4, a84
	v_accvgpr_read_b32 v5, a85
	v_accvgpr_read_b32 v6, a86
	v_accvgpr_read_b32 v7, a87
	v_accvgpr_read_b32 v8, a88
	v_accvgpr_read_b32 v9, a89
	v_accvgpr_read_b32 v10, a90
	v_accvgpr_read_b32 v11, a91
	v_accvgpr_read_b32 v12, a92
	v_accvgpr_read_b32 v13, a93
	v_accvgpr_read_b32 v14, a94
	v_accvgpr_read_b32 v15, a95
	v_accvgpr_read_b32 v33, a65
	v_accvgpr_read_b32 v34, a66
	v_accvgpr_read_b32 v35, a67
	v_accvgpr_read_b32 v36, a68
	v_accvgpr_read_b32 v37, a69
	v_accvgpr_read_b32 v38, a70
	v_accvgpr_read_b32 v39, a71
	v_accvgpr_read_b32 v40, a72
	v_accvgpr_read_b32 v41, a73
	v_accvgpr_read_b32 v42, a74
	v_accvgpr_read_b32 v43, a75
	v_accvgpr_read_b32 v44, a76
	v_accvgpr_read_b32 v45, a77
	v_accvgpr_read_b32 v46, a78
	v_accvgpr_read_b32 v47, a79
	v_accvgpr_read_b32 v178, a237
	v_or_b32_e32 v178, s20, v178
	v_or_b32_e32 v179, 32, v178
	v_cmp_le_i32_e64 s[0:1], v179, v212
	v_or_b32_e32 v179, 33, v178
	v_mov_b32_e32 v180, 0xff800000
	v_cmp_le_i32_e64 s[6:7], v179, v212
	v_or_b32_e32 v179, 2, v178
	v_cmp_le_i32_e32 vcc, v178, v212
	v_cndmask_b32_e64 v33, v180, v33, s[6:7]
	v_cmp_le_i32_e64 s[6:7], v179, v212
	v_or_b32_e32 v179, 34, v178
	v_cmp_le_i32_e64 s[8:9], v179, v212
	v_or_b32_e32 v179, 3, v178
	v_cndmask_b32_e64 v32, v180, v32, s[0:1]
	v_cndmask_b32_e64 v34, v180, v34, s[8:9]
	v_cmp_le_i32_e64 s[8:9], v179, v212
	v_or_b32_e32 v179, 35, v178
	v_cmp_le_i32_e64 s[10:11], v179, v212
	v_or_b32_e32 v179, 8, v178
	v_cmp_lt_i32_e64 s[0:1], v178, v212
	v_cndmask_b32_e64 v35, v180, v35, s[10:11]
	v_cmp_le_i32_e64 s[10:11], v179, v212
	v_or_b32_e32 v179, 40, v178
	v_cmp_le_i32_e64 s[12:13], v179, v212
	v_or_b32_e32 v179, 9, v178
; DI int crow(int reg, int h) { return (reg & 3) + 8 * (reg >> 2) + 4 * h; }
; template <int DQK>
; DI void attn_item_c(const u16* __restrict__ Qp, int ldq, const u16* __restrict__ Kp, const u16* __restrict__ Vtp, int ldv,
;                     int nkt, int q0, float c, u16* Yp, int ldy, char* smem, bool dry) {
;     ...
;     const bool active = !(kt * 64 > qmin + 31);
;     if (kt * 64 + 63 > qmin) {
; #pragma unroll
;       for (int e = 0; e < 16; ++e) {
;         int key = kt * 64 + crow(e, h);
;         if (key > qi) s0[e] = -INFINITY;
;         if (key + 32 > qi) s1[e] = -INFINITY;
;       }
;     }
;     float mx = fmaxf(s0[0], s1[0]);
; #pragma unroll
;     for (int e = 1; e < 16; ++e) mx = fmaxf(fmaxf(mx, s0[e]), s1[e]);
;     mx = fmaxf(mx, __shfl_xor(mx, 32));
;     if (__builtin_amdgcn_ballot_w64((mx - m) * c > 8.f) != 0ull) {
;     ...
;     l += ps;
	s_nop 0
	v_cndmask_b32_e64 v36, v180, v36, s[12:13]
	v_cmp_le_i32_e64 s[12:13], v179, v212
	v_or_b32_e32 v179, 41, v178
	v_cmp_le_i32_e64 s[14:15], v179, v212
	v_or_b32_e32 v179, 10, v178
	s_nop 0
	v_cndmask_b32_e64 v37, v180, v37, s[14:15]
	v_cmp_le_i32_e64 s[14:15], v179, v212
	v_or_b32_e32 v179, 42, v178
	v_cmp_le_i32_e64 s[16:17], v179, v212
	v_or_b32_e32 v179, 11, v178
	s_nop 0
	v_cndmask_b32_e64 v38, v180, v38, s[16:17]
	v_cmp_le_i32_e64 s[16:17], v179, v212
	v_or_b32_e32 v179, 43, v178
	v_cmp_le_i32_e64 s[18:19], v179, v212
	v_or_b32_e32 v179, 16, v178
	s_nop 0
	v_cndmask_b32_e64 v39, v180, v39, s[18:19]
	v_cmp_le_i32_e64 s[18:19], v179, v212
	v_or_b32_e32 v179, 48, v178
	v_cmp_le_i32_e64 s[22:23], v179, v212
	v_or_b32_e32 v179, 17, v178
	s_nop 0
	v_cndmask_b32_e64 v40, v180, v40, s[22:23]
	v_cmp_le_i32_e64 s[22:23], v179, v212
	v_or_b32_e32 v179, 49, v178
	v_cmp_le_i32_e64 s[24:25], v179, v212
	v_or_b32_e32 v179, 18, v178
	s_nop 0
	v_cndmask_b32_e64 v41, v180, v41, s[24:25]
	v_cmp_le_i32_e64 s[24:25], v179, v212
	v_or_b32_e32 v179, 50, v178
	v_cmp_le_i32_e64 s[26:27], v179, v212
	v_or_b32_e32 v179, 19, v178
	s_nop 0
	v_cndmask_b32_e64 v42, v180, v42, s[26:27]
	v_cmp_le_i32_e64 s[26:27], v179, v212
	v_or_b32_e32 v179, 51, v178
	v_cmp_le_i32_e64 s[28:29], v179, v212
	v_or_b32_e32 v179, 24, v178
	s_nop 0
	v_cndmask_b32_e64 v43, v180, v43, s[28:29]
	v_cmp_le_i32_e64 s[28:29], v179, v212
	v_or_b32_e32 v179, 56, v178
	v_cmp_le_i32_e64 s[30:31], v179, v212
	v_or_b32_e32 v179, 25, v178
	s_nop 0
	v_cndmask_b32_e64 v44, v180, v44, s[30:31]
	v_cmp_le_i32_e64 s[30:31], v179, v212
	v_or_b32_e32 v179, 57, v178
	v_cmp_le_i32_e64 s[34:35], v179, v212
	v_or_b32_e32 v179, 26, v178
	s_nop 0
	v_cndmask_b32_e64 v45, v180, v45, s[34:35]
	v_cmp_le_i32_e64 s[34:35], v179, v212
	v_or_b32_e32 v179, 58, v178
	v_cmp_le_i32_e64 s[36:37], v179, v212
	v_or_b32_e32 v179, 27, v178
	v_or_b32_e32 v178, 59, v178
	v_cndmask_b32_e64 v46, v180, v46, s[36:37]
	v_cmp_le_i32_e64 s[36:37], v179, v212
	v_cmp_gt_i32_e64 s[40:41], v178, v212
	s_and_saveexec_b64 s[48:49], s[40:41]
	v_mov_b32_e32 v47, s65
	s_or_b64 exec, exec, s[48:49]
	v_accvgpr_write_b32 a79, v47
	v_accvgpr_write_b32 a78, v46
	v_accvgpr_write_b32 a77, v45
	v_accvgpr_write_b32 a76, v44
	v_accvgpr_write_b32 a75, v43
	v_accvgpr_write_b32 a74, v42
	v_accvgpr_write_b32 a73, v41
	v_accvgpr_write_b32 a72, v40
	v_accvgpr_write_b32 a71, v39
	v_accvgpr_write_b32 a70, v38
	v_accvgpr_write_b32 a69, v37
	v_accvgpr_write_b32 a68, v36
	v_accvgpr_write_b32 a67, v35
	v_accvgpr_write_b32 a66, v34
	v_accvgpr_write_b32 a65, v33
	v_accvgpr_write_b32 a64, v32
	v_mov_b32_e32 v32, 0xff800000
	v_cndmask_b32_e64 v1, v32, v1, s[0:1]
	v_cndmask_b32_e32 v0, v32, v0, vcc
	v_cndmask_b32_e64 v2, v32, v2, s[6:7]
	v_cndmask_b32_e64 v3, v32, v3, s[8:9]
	v_cndmask_b32_e64 v4, v32, v4, s[10:11]
	v_cndmask_b32_e64 v5, v32, v5, s[12:13]
	v_cndmask_b32_e64 v6, v32, v6, s[14:15]
	v_cndmask_b32_e64 v7, v32, v7, s[16:17]
	v_cndmask_b32_e64 v8, v32, v8, s[18:19]
	v_cndmask_b32_e64 v9, v32, v9, s[22:23]
	v_cndmask_b32_e64 v10, v32, v10, s[24:25]
	v_cndmask_b32_e64 v11, v32, v11, s[26:27]
	v_cndmask_b32_e64 v12, v32, v12, s[28:29]
	v_cndmask_b32_e64 v13, v32, v13, s[30:31]
	v_cndmask_b32_e64 v14, v32, v14, s[34:35]
	v_cndmask_b32_e64 v15, v32, v15, s[36:37]
	v_accvgpr_write_b32 a80, v0
	v_accvgpr_write_b32 a81, v1
	v_accvgpr_write_b32 a82, v2
	v_accvgpr_write_b32 a83, v3
	v_accvgpr_write_b32 a84, v4
	v_accvgpr_write_b32 a85, v5
	v_accvgpr_write_b32 a86, v6
	v_accvgpr_write_b32 a87, v7
	v_accvgpr_write_b32 a88, v8
	v_accvgpr_write_b32 a89, v9
	v_accvgpr_write_b32 a90, v10
	v_accvgpr_write_b32 a91, v11
	v_accvgpr_write_b32 a92, v12
	v_accvgpr_write_b32 a93, v13
	v_accvgpr_write_b32 a94, v14
	v_accvgpr_write_b32 a95, v15
	s_mov_b64 s[40:41], s[70:71]
.LBB0_242:
	s_or_b64 exec, exec, s[46:47]
	v_add_f32_e32 v162, 0, v162
	v_add_f32_e32 v162, v163, v162
	v_add_f32_e32 v162, v164, v162
	v_add_f32_e32 v162, v165, v162
	v_add_f32_e32 v162, v166, v162
	v_add_f32_e32 v162, v167, v162
	v_add_f32_e32 v162, v168, v162
	v_add_f32_e32 v162, v169, v162
	v_add_f32_e32 v162, v170, v162
	v_add_f32_e32 v162, v171, v162
	v_add_f32_e32 v162, v172, v162
	v_add_f32_e32 v162, v173, v162
	v_add_f32_e32 v162, v174, v162
	v_add_f32_e32 v162, v175, v162
	v_add_f32_e32 v162, v176, v162
	v_add_f32_e32 v162, v177, v162
	v_add_f32_e32 v162, v213, v162
	v_add_f32_e32 v162, v214, v162
	v_add_f32_e32 v162, v215, v162
	v_add_f32_e32 v129, v129, v162
	v_add_f32_e32 v129, v227, v129
	v_add_f32_e32 v129, v228, v129
	v_add_f32_e32 v129, v229, v129
	v_add_f32_e32 v129, v230, v129
	v_accvgpr_read_b32 v0, a64
	v_accvgpr_read_b32 v32, a80
	v_add_f32_e32 v129, v147, v129
	v_add_f32_e32 v129, v148, v129
	v_max_f32_e32 v147, v0, v0
	v_max_f32_e32 v148, v32, v32
	v_accvgpr_read_b32 v1, a65
	v_accvgpr_read_b32 v33, a81
	v_max_f32_e32 v147, v148, v147
	v_accvgpr_read_b32 v2, a66
	v_accvgpr_read_b32 v34, a82
	v_max3_f32 v147, v147, v33, v1
	v_accvgpr_read_b32 v3, a67
	v_accvgpr_read_b32 v35, a83
	v_max3_f32 v147, v147, v34, v2
	v_accvgpr_read_b32 v4, a68
	v_accvgpr_read_b32 v36, a84
	v_max3_f32 v147, v147, v35, v3
	v_accvgpr_read_b32 v5, a69
	v_accvgpr_read_b32 v37, a85
	v_max3_f32 v147, v147, v36, v4
	v_accvgpr_read_b32 v6, a70
	v_accvgpr_read_b32 v38, a86
	v_max3_f32 v147, v147, v37, v5
	v_accvgpr_read_b32 v7, a71
	v_accvgpr_read_b32 v39, a87
	v_max3_f32 v147, v147, v38, v6
	v_accvgpr_read_b32 v8, a72
	v_accvgpr_read_b32 v40, a88
	v_max3_f32 v147, v147, v39, v7
	v_accvgpr_read_b32 v9, a73
	v_accvgpr_read_b32 v41, a89
	v_max3_f32 v147, v147, v40, v8
	v_accvgpr_read_b32 v10, a74
	v_accvgpr_read_b32 v42, a90
	v_max3_f32 v147, v147, v41, v9
	v_accvgpr_read_b32 v11, a75
	v_accvgpr_read_b32 v43, a91
	v_max3_f32 v147, v147, v42, v10
	v_accvgpr_read_b32 v12, a76
	v_accvgpr_read_b32 v44, a92
	v_max3_f32 v147, v147, v43, v11
	v_accvgpr_read_b32 v13, a77
	v_accvgpr_read_b32 v45, a93
	v_max3_f32 v147, v147, v44, v12
	v_accvgpr_read_b32 v14, a78
	v_accvgpr_read_b32 v46, a94
	v_max3_f32 v147, v147, v45, v13
	v_accvgpr_read_b32 v15, a79
	v_accvgpr_read_b32 v47, a95
	v_max3_f32 v147, v147, v46, v14
	v_add_f32_e32 v129, v149, v129
	v_max3_f32 v147, v147, v47, v15
	v_add_f32_e32 v129, v218, v129
	ds_bpermute_b32 v148, v232, v147
	v_add_f32_e32 v129, v244, v129
	v_add_f32_e32 v129, v231, v129
	v_add_f32_e32 v129, v234, v129
	v_add_f32_e32 v129, v146, v129
	v_add_f32_e32 v248, v248, v129
	s_waitcnt lgkmcnt(0)
	v_max_f32_e32 v129, v148, v148
	v_max_f32_e32 v129, v147, v129
	v_sub_f32_e32 v146, v129, v216
	v_mul_f32_e32 v146, 0x3dd53b94, v146
	v_cmp_lt_f32_e32 vcc, s33, v146
	s_cbranch_vccz .LBB0_244
; DI float ex2(float x) { return __builtin_amdgcn_exp2f(x); }
; template <int DQK>
; DI void attn_item_c(const u16* __restrict__ Qp, int ldq, const u16* __restrict__ Kp, const u16* __restrict__ Vtp, int ldv,
;                     int nkt, int q0, float c, u16* Yp, int ldy, char* smem, bool dry) {
;     ...
;     if (__builtin_amdgcn_ballot_w64((mx - m) * c > 8.f) != 0ull) {
;       const float mn = fmaxf(m, mx);
;       const float alpha = ex2((m - mn) * c);
;       m = mn;
;       l *= alpha;
; #pragma unroll
;       for (int dt = 0; dt < 4; ++dt)
; #pragma unroll
;         for (int e = 0; e < 16; ++e) o[dt][e] *= alpha;
;     }
	v_accvgpr_read_b32 v16, a48
	v_accvgpr_read_b32 v63, a47
	v_accvgpr_read_b32 v79, a31
	v_accvgpr_read_b32 v95, a15
	v_accvgpr_read_b32 v17, a49
	v_accvgpr_read_b32 v18, a50
	v_accvgpr_read_b32 v19, a51
	v_accvgpr_read_b32 v20, a52
	v_accvgpr_read_b32 v21, a53
	v_accvgpr_read_b32 v22, a54
	v_accvgpr_read_b32 v23, a55
	v_accvgpr_read_b32 v24, a56
	v_accvgpr_read_b32 v25, a57
	v_accvgpr_read_b32 v26, a58
	v_accvgpr_read_b32 v27, a59
	v_accvgpr_read_b32 v28, a60
	v_accvgpr_read_b32 v29, a61
	v_accvgpr_read_b32 v30, a62
	v_accvgpr_read_b32 v31, a63
	v_accvgpr_read_b32 v62, a46
	v_accvgpr_read_b32 v61, a45
	v_accvgpr_read_b32 v60, a44
	v_accvgpr_read_b32 v59, a43
	v_accvgpr_read_b32 v58, a42
	v_accvgpr_read_b32 v57, a41
	v_accvgpr_read_b32 v56, a40
	v_accvgpr_read_b32 v55, a39
	v_accvgpr_read_b32 v54, a38
	v_accvgpr_read_b32 v53, a37
	v_accvgpr_read_b32 v52, a36
	v_accvgpr_read_b32 v51, a35
	v_accvgpr_read_b32 v50, a34
	v_accvgpr_read_b32 v49, a33
	v_accvgpr_read_b32 v48, a32
	v_accvgpr_read_b32 v78, a30
	v_accvgpr_read_b32 v77, a29
	v_accvgpr_read_b32 v76, a28
	v_accvgpr_read_b32 v75, a27
	v_accvgpr_read_b32 v74, a26
	v_accvgpr_read_b32 v73, a25
	v_accvgpr_read_b32 v72, a24
	v_accvgpr_read_b32 v71, a23
	v_accvgpr_read_b32 v70, a22
	v_accvgpr_read_b32 v69, a21
	v_accvgpr_read_b32 v68, a20
	v_accvgpr_read_b32 v67, a19
	v_accvgpr_read_b32 v66, a18
	v_accvgpr_read_b32 v65, a17
	v_accvgpr_read_b32 v64, a16
	v_accvgpr_read_b32 v94, a14
	v_accvgpr_read_b32 v93, a13
	v_accvgpr_read_b32 v92, a12
	v_accvgpr_read_b32 v91, a11
	v_accvgpr_read_b32 v90, a10
	v_accvgpr_read_b32 v89, a9
	v_accvgpr_read_b32 v88, a8
	v_accvgpr_read_b32 v87, a7
	v_accvgpr_read_b32 v86, a6
	v_accvgpr_read_b32 v85, a5
	v_accvgpr_read_b32 v84, a4
	v_accvgpr_read_b32 v83, a3
	v_accvgpr_read_b32 v82, a2
	v_accvgpr_read_b32 v81, a1
	v_accvgpr_read_b32 v80, a0
	v_max_f32_e32 v129, v129, v129
	v_max_f32_e32 v146, v216, v216
	v_max_f32_e32 v249, v146, v129
	v_sub_f32_e32 v129, v216, v249
	v_mul_f32_e32 v129, 0x3dd53b94, v129
	v_exp_f32_e32 v216, v129
	s_nop 0
	v_pk_mul_f32 v[30:31], v[30:31], v[216:217] op_sel_hi:[1,0]
	v_pk_mul_f32 v[80:81], v[80:81], v[216:217] op_sel_hi:[1,0]
	v_pk_mul_f32 v[64:65], v[64:65], v[216:217] op_sel_hi:[1,0]
	v_pk_mul_f32 v[48:49], v[48:49], v[216:217] op_sel_hi:[1,0]
	v_pk_mul_f32 v[28:29], v[28:29], v[216:217] op_sel_hi:[1,0]
	v_pk_mul_f32 v[26:27], v[26:27], v[216:217] op_sel_hi:[1,0]
	v_pk_mul_f32 v[24:25], v[24:25], v[216:217] op_sel_hi:[1,0]
	v_pk_mul_f32 v[22:23], v[22:23], v[216:217] op_sel_hi:[1,0]
	v_pk_mul_f32 v[20:21], v[20:21], v[216:217] op_sel_hi:[1,0]
	v_pk_mul_f32 v[18:19], v[18:19], v[216:217] op_sel_hi:[1,0]
	v_pk_mul_f32 v[16:17], v[16:17], v[216:217] op_sel_hi:[1,0]
	v_pk_mul_f32 v[94:95], v[94:95], v[216:217] op_sel_hi:[1,0]
	v_accvgpr_write_b32 a63, v31
	v_pk_mul_f32 v[92:93], v[92:93], v[216:217] op_sel_hi:[1,0]
	v_pk_mul_f32 v[90:91], v[90:91], v[216:217] op_sel_hi:[1,0]
	v_pk_mul_f32 v[88:89], v[88:89], v[216:217] op_sel_hi:[1,0]
	v_pk_mul_f32 v[86:87], v[86:87], v[216:217] op_sel_hi:[1,0]
	v_pk_mul_f32 v[84:85], v[84:85], v[216:217] op_sel_hi:[1,0]
	v_pk_mul_f32 v[82:83], v[82:83], v[216:217] op_sel_hi:[1,0]
	v_pk_mul_f32 v[78:79], v[78:79], v[216:217] op_sel_hi:[1,0]
	v_accvgpr_write_b32 a0, v80
	v_pk_mul_f32 v[76:77], v[76:77], v[216:217] op_sel_hi:[1,0]
	v_pk_mul_f32 v[74:75], v[74:75], v[216:217] op_sel_hi:[1,0]
	v_pk_mul_f32 v[72:73], v[72:73], v[216:217] op_sel_hi:[1,0]
	v_pk_mul_f32 v[70:71], v[70:71], v[216:217] op_sel_hi:[1,0]
	v_pk_mul_f32 v[68:69], v[68:69], v[216:217] op_sel_hi:[1,0]
	v_pk_mul_f32 v[66:67], v[66:67], v[216:217] op_sel_hi:[1,0]
	v_pk_mul_f32 v[62:63], v[62:63], v[216:217] op_sel_hi:[1,0]
	v_accvgpr_write_b32 a16, v64
	v_pk_mul_f32 v[60:61], v[60:61], v[216:217] op_sel_hi:[1,0]
	v_pk_mul_f32 v[58:59], v[58:59], v[216:217] op_sel_hi:[1,0]
	v_pk_mul_f32 v[56:57], v[56:57], v[216:217] op_sel_hi:[1,0]
	v_pk_mul_f32 v[54:55], v[54:55], v[216:217] op_sel_hi:[1,0]
	v_pk_mul_f32 v[52:53], v[52:53], v[216:217] op_sel_hi:[1,0]
	v_pk_mul_f32 v[50:51], v[50:51], v[216:217] op_sel_hi:[1,0]
	v_accvgpr_write_b32 a62, v30
	v_accvgpr_write_b32 a32, v48
	v_accvgpr_write_b32 a61, v29
	v_accvgpr_write_b32 a60, v28
	v_accvgpr_write_b32 a59, v27
	v_accvgpr_write_b32 a58, v26
	v_accvgpr_write_b32 a57, v25
	v_accvgpr_write_b32 a56, v24
	v_accvgpr_write_b32 a55, v23
	v_accvgpr_write_b32 a54, v22
	v_accvgpr_write_b32 a53, v21
	v_accvgpr_write_b32 a52, v20
	v_accvgpr_write_b32 a51, v19
	v_accvgpr_write_b32 a50, v18
	v_accvgpr_write_b32 a49, v17
	v_accvgpr_write_b32 a48, v16
	v_pk_mul_f32 v[16:17], v[248:249], v[216:217]
	v_accvgpr_write_b32 a1, v81
	v_accvgpr_write_b32 a2, v82
	v_accvgpr_write_b32 a3, v83
	v_accvgpr_write_b32 a4, v84
	v_accvgpr_write_b32 a5, v85
	v_accvgpr_write_b32 a6, v86
	v_accvgpr_write_b32 a7, v87
	v_accvgpr_write_b32 a8, v88
	v_accvgpr_write_b32 a9, v89
	v_accvgpr_write_b32 a10, v90
	v_accvgpr_write_b32 a11, v91
	v_accvgpr_write_b32 a12, v92
	v_accvgpr_write_b32 a13, v93
	v_accvgpr_write_b32 a14, v94
	v_accvgpr_write_b32 a15, v95
	v_accvgpr_write_b32 a17, v65
	v_accvgpr_write_b32 a18, v66
	v_accvgpr_write_b32 a19, v67
	v_accvgpr_write_b32 a20, v68
	v_accvgpr_write_b32 a21, v69
	v_accvgpr_write_b32 a22, v70
	v_accvgpr_write_b32 a23, v71
	v_accvgpr_write_b32 a24, v72
	v_accvgpr_write_b32 a25, v73
	v_accvgpr_write_b32 a26, v74
	v_accvgpr_write_b32 a27, v75
	v_accvgpr_write_b32 a28, v76
	v_accvgpr_write_b32 a29, v77
	v_accvgpr_write_b32 a30, v78
	v_accvgpr_write_b32 a31, v79
	v_accvgpr_write_b32 a33, v49
	v_accvgpr_write_b32 a34, v50
	v_accvgpr_write_b32 a35, v51
	v_accvgpr_write_b32 a36, v52
	v_accvgpr_write_b32 a37, v53
	v_accvgpr_write_b32 a38, v54
	v_accvgpr_write_b32 a39, v55
	v_accvgpr_write_b32 a40, v56
	v_accvgpr_write_b32 a41, v57
	v_accvgpr_write_b32 a42, v58
	v_accvgpr_write_b32 a43, v59
	v_accvgpr_write_b32 a44, v60
	v_accvgpr_write_b32 a45, v61
	v_accvgpr_write_b32 a46, v62
	v_accvgpr_write_b32 a47, v63
	v_mov_b32_e32 v216, v249
	v_mov_b64_e32 v[248:249], v[16:17]
; #define MFMA32(a, b, c) __builtin_amdgcn_mfma_f32_32x32x16_bf16((a), (b), (c), 0, 0, 0)
; DI float ex2(float x) { return __builtin_amdgcn_exp2f(x); }
; template <int DQK>
; DI void attn_item_c(const u16* __restrict__ Qp, int ldq, const u16* __restrict__ Kp, const u16* __restrict__ Vtp, int ldv,
;                     int nkt, int q0, float c, u16* Yp, int ldy, char* smem, bool dry) {
;     ...
;     const float mc = m * c;
; #pragma unroll
;     for (int e = 0; e < 16; ++e) { n0[e] = 0.f; n1[e] = 0.f; }
;     const u16* k0 = Ks + r * KLD + 8 * h;
;     bf16x8 ka[3][2];
;     ka[0][0] = *(const bf16x8*)(k0); ka[0][1] = *(const bf16x8*)(k0 + 32 * KLD);
;     ka[1][0] = *(const bf16x8*)(k0 + 16); ka[1][1] = *(const bf16x8*)(k0 + 32 * KLD + 16);
;     bf16x8 pf[4];
;     u32x4 pk[4];
;     float ps = 0.f;
; #pragma unroll
;     for (int ks = 0; ks < NKS; ++ks) {
;       if (ks + 2 < NKS) {
;         ka[(ks + 2) % 3][0] = *(const bf16x8*)(k0 + 16 * (ks + 2));
;         ka[(ks + 2) % 3][1] = *(const bf16x8*)(k0 + 32 * KLD + 16 * (ks + 2));
;       }
;       __builtin_amdgcn_sched_barrier(0);
;       n0 = MFMA32(ka[ks % 3][0], qf[ks], n0); n1 = MFMA32(ka[ks % 3][1], qf[ks], n1);
;       {
;         constexpr int dummy0 = 0; (void)dummy0;
;         const int e_lo = (32 * ks) / NKS, e_hi = (32 * (ks + 1)) / NKS;
; #pragma unroll
;         for (int q = 0; q < 3; ++q) {
;           const int e = e_lo + q;
;           if (e < e_hi) {
;             if (e < 16) { s0[e & 15] = ex2(fmaf(s0[e & 15], c, -mc)); ps += s0[e & 15]; }
;             else        { s1[e & 15] = ex2(fmaf(s1[e & 15], c, -mc)); ps += s1[e & 15]; }
;           }
;         }
;       }
.LBB0_244:
	ds_read_b128 v[16:19], v235 offset:44032
	ds_read_b128 v[20:23], v235 offset:44064
	ds_read_b128 v[24:27], v235 offset:56832
	ds_read_b128 v[28:31], v235 offset:44096
	ds_read_b128 v[48:51], v235 offset:56864
	ds_read_b128 v[52:55], v235 offset:56896
	v_accvgpr_read_b32 v56, a238
	v_cmp_le_i32_e32 vcc, s20, v56
	s_waitcnt lgkmcnt(5)
	v_mfma_f32_32x32x16_bf16 a[80:95], v[16:19], v[96:99], 0
	v_fmamk_f32 v16, v32, 0x3dd53b94, v249
	v_fmamk_f32 v17, v33, 0x3dd53b94, v249
	v_exp_f32_e32 v16, v16
	v_exp_f32_e32 v17, v17
	s_waitcnt lgkmcnt(3)
	v_mfma_f32_32x32x16_bf16 a[64:79], v[24:27], v[96:99], 0
	ds_read_b128 v[24:27], v235 offset:44128
	ds_read_b128 v[56:59], v235 offset:56928
	v_mfma_f32_32x32x16_bf16 a[80:95], v[20:23], v[100:103], a[80:95]
	v_fmamk_f32 v18, v34, 0x3dd53b94, v249
	v_fmamk_f32 v19, v35, 0x3dd53b94, v249
	v_fmamk_f32 v20, v36, 0x3dd53b94, v249
	v_exp_f32_e32 v18, v18
	v_exp_f32_e32 v19, v19
	v_exp_f32_e32 v20, v20
	s_waitcnt lgkmcnt(3)
	v_mfma_f32_32x32x16_bf16 a[64:79], v[48:51], v[100:103], a[64:79]
	ds_read_b128 v[32:35], v235 offset:44160
	ds_read_b128 v[48:51], v235 offset:56960
	v_mfma_f32_32x32x16_bf16 a[80:95], v[28:31], v[104:107], a[80:95]
	v_fmamk_f32 v21, v37, 0x3dd53b94, v249
	v_fmamk_f32 v22, v38, 0x3dd53b94, v249
	v_fmamk_f32 v23, v39, 0x3dd53b94, v249
	v_exp_f32_e32 v21, v21
	v_exp_f32_e32 v22, v22
	v_exp_f32_e32 v23, v23
	s_waitcnt lgkmcnt(4)
	v_mfma_f32_32x32x16_bf16 a[64:79], v[52:55], v[104:107], a[64:79]
	ds_read_b128 v[36:39], v235 offset:44192
	ds_read_b128 v[52:55], v235 offset:56992
	s_waitcnt lgkmcnt(5)
	v_mfma_f32_32x32x16_bf16 a[80:95], v[24:27], v[108:111], a[80:95]
	v_fmamk_f32 v24, v40, 0x3dd53b94, v249
	v_fmamk_f32 v25, v41, 0x3dd53b94, v249
	v_exp_f32_e32 v24, v24
	v_exp_f32_e32 v25, v25
	s_waitcnt lgkmcnt(4)
	v_mfma_f32_32x32x16_bf16 a[64:79], v[56:59], v[108:111], a[64:79]
	ds_read_b128 v[56:59], v235 offset:44224
	ds_read_b128 v[60:63], v235 offset:57024
	s_waitcnt lgkmcnt(5)
	v_mfma_f32_32x32x16_bf16 a[80:95], v[32:35], v[112:115], a[80:95]
	v_fmamk_f32 v26, v42, 0x3dd53b94, v249
	v_fmamk_f32 v27, v43, 0x3dd53b94, v249
	v_fmamk_f32 v28, v44, 0x3dd53b94, v249
	v_exp_f32_e32 v26, v26
	v_exp_f32_e32 v27, v27
	v_exp_f32_e32 v28, v28
	s_waitcnt lgkmcnt(4)
	v_mfma_f32_32x32x16_bf16 a[64:79], v[48:51], v[112:115], a[64:79]
	ds_read_b128 v[32:35], v235 offset:44256
	ds_read_b128 v[40:43], v235 offset:57056
	s_waitcnt lgkmcnt(5)
	v_mfma_f32_32x32x16_bf16 a[80:95], v[36:39], v[116:119], a[80:95]
	v_fmamk_f32 v29, v45, 0x3dd53b94, v249
	v_fmamk_f32 v30, v46, 0x3dd53b94, v249
	v_fmamk_f32 v31, v47, 0x3dd53b94, v249
	v_exp_f32_e32 v29, v29
	v_exp_f32_e32 v30, v30
	v_exp_f32_e32 v31, v31
	s_waitcnt lgkmcnt(4)
	v_mfma_f32_32x32x16_bf16 a[64:79], v[52:55], v[116:119], a[64:79]
	ds_read_b128 v[36:39], v235 offset:44288
	ds_read_b128 v[44:47], v235 offset:57088
	s_waitcnt lgkmcnt(5)
	v_mfma_f32_32x32x16_bf16 a[80:95], v[56:59], v[120:123], a[80:95]
	v_fmamk_f32 v0, v0, 0x3dd53b94, v249
	v_fmamk_f32 v1, v1, 0x3dd53b94, v249
	v_exp_f32_e32 v0, v0
	v_exp_f32_e32 v1, v1
	s_waitcnt lgkmcnt(4)
	v_mfma_f32_32x32x16_bf16 a[64:79], v[60:63], v[120:123], a[64:79]
	ds_read_b128 v[48:51], v235 offset:44320
	ds_read_b128 v[52:55], v235 offset:57120
	s_waitcnt lgkmcnt(5)
	v_mfma_f32_32x32x16_bf16 a[80:95], v[32:35], v[124:127], a[80:95]
	v_fmamk_f32 v2, v2, 0x3dd53b94, v249
	v_fmamk_f32 v3, v3, 0x3dd53b94, v249
	v_fmamk_f32 v4, v4, 0x3dd53b94, v249
	v_exp_f32_e32 v2, v2
	v_exp_f32_e32 v3, v3
	v_exp_f32_e32 v4, v4
	s_waitcnt lgkmcnt(4)
	v_mfma_f32_32x32x16_bf16 a[64:79], v[40:43], v[124:127], a[64:79]
	ds_read_b128 v[32:35], v235 offset:44352
	ds_read_b128 v[40:43], v235 offset:57152
	s_waitcnt lgkmcnt(5)
	v_mfma_f32_32x32x16_bf16 a[80:95], v[36:39], v[130:133], a[80:95]
	v_fmamk_f32 v5, v5, 0x3dd53b94, v249
	v_fmamk_f32 v6, v6, 0x3dd53b94, v249
	v_fmamk_f32 v7, v7, 0x3dd53b94, v249
	v_exp_f32_e32 v5, v5
	v_exp_f32_e32 v6, v6
	v_exp_f32_e32 v7, v7
	s_waitcnt lgkmcnt(4)
	v_mfma_f32_32x32x16_bf16 a[64:79], v[44:47], v[130:133], a[64:79]
	ds_read_b128 v[36:39], v235 offset:44384
	ds_read_b128 v[44:47], v235 offset:57184
	s_waitcnt lgkmcnt(5)
	v_mfma_f32_32x32x16_bf16 a[80:95], v[48:51], v[134:137], a[80:95]
	v_fmamk_f32 v8, v8, 0x3dd53b94, v249
	v_fmamk_f32 v9, v9, 0x3dd53b94, v249
	v_exp_f32_e32 v8, v8
	v_exp_f32_e32 v9, v9
	s_waitcnt lgkmcnt(4)
	v_mfma_f32_32x32x16_bf16 a[64:79], v[52:55], v[134:137], a[64:79]
	s_waitcnt lgkmcnt(3)
	v_mfma_f32_32x32x16_bf16 a[80:95], v[32:35], v[138:141], a[80:95]
	v_fmamk_f32 v10, v10, 0x3dd53b94, v249
	v_fmamk_f32 v11, v11, 0x3dd53b94, v249
	v_fmamk_f32 v12, v12, 0x3dd53b94, v249
	v_exp_f32_e32 v10, v10
	v_exp_f32_e32 v11, v11
	v_exp_f32_e32 v12, v12
	s_waitcnt lgkmcnt(2)
	v_mfma_f32_32x32x16_bf16 a[64:79], v[40:43], v[138:141], a[64:79]
	s_waitcnt lgkmcnt(1)
	v_mfma_f32_32x32x16_bf16 a[80:95], v[36:39], v[142:145], a[80:95]
	v_fmamk_f32 v13, v13, 0x3dd53b94, v249
	v_fmamk_f32 v14, v14, 0x3dd53b94, v249
	v_fmamk_f32 v15, v15, 0x3dd53b94, v249
	v_exp_f32_e32 v13, v13
	v_exp_f32_e32 v14, v14
	v_exp_f32_e32 v15, v15
	s_waitcnt lgkmcnt(0)
	v_mfma_f32_32x32x16_bf16 a[64:79], v[44:47], v[142:145], a[64:79]
	s_and_saveexec_b64 s[0:1], vcc
	s_xor_b64 s[0:1], exec, s[0:1]
	s_cbranch_execz .LBB0_246
; #define MFMA32(a, b, c) __builtin_amdgcn_mfma_f32_32x32x16_bf16((a), (b), (c), 0, 0, 0)
; template <int DQK>
; DI void attn_item_c(const u16* __restrict__ Qp, int ldq, const u16* __restrict__ Kp, const u16* __restrict__ Vtp, int ldv,
;                     int nkt, int q0, float c, u16* Yp, int ldy, char* smem, bool dry) {
;     ...
;     if (active) {
;       const u16* v0 = Vs + r * 72 + 8 * h;
;       bf16x8 va[2][4];
; #pragma unroll
;       for (int dt = 0; dt < 4; ++dt) va[0][dt] = *(const bf16x8*)(v0 + (32 * dt) * 72);
; #pragma unroll
;       for (int kk = 0; kk < 4; ++kk) {
;         if (kk < 3) {
; #pragma unroll
;           for (int dt = 0; dt < 4; ++dt) va[(kk + 1) & 1][dt] = *(const bf16x8*)(v0 + (32 * dt) * 72 + 16 * (kk + 1));
;         }
;         __builtin_amdgcn_sched_barrier(0);
; #pragma unroll
;         for (int dt = 0; dt < 4; ++dt) o[dt] = MFMA32(va[kk & 1][dt], pf[kk], o[dt]);
;         if (kk == 0) lstoreK(wk, Ln);
;         if (kk == 1) lstoreV(wv, Ln);
;         if (kk == 2) gloadK(wk, kt + 3);
;         if (kk == 3) gloadV(wv, kt + 3);
;         __builtin_amdgcn_sched_barrier(0);
;       }
;     } else {
;       lstore(wk, wv, Ln);
;       gload(wk, wv, kt + 3);
;     }
;     __syncthreads();
;   };
;   for (int kt4 = 0; kt4 < nktp; kt4 += 4) {
;     body(kt4 + 0, kstB, vstB, sa0, sa1, sb0, sb1); body(kt4 + 1, kstA, vstA, sb0, sb1, sa0, sa1);
;     body(kt4 + 2, kstB, vstB, sa0, sa1, sb0, sb1); body(kt4 + 3, kstA, vstA, sb0, sb1, sa0, sa1);
;   }
	ds_read_b128 v[48:51], v250
	ds_read_b128 v[52:55], v250 offset:32
	ds_read_b128 v[56:59], v250 offset:4608
	ds_read_b128 v[60:63], v250 offset:4640
	ds_read_b128 v[64:67], v250 offset:9216
	ds_read_b128 v[68:71], v250 offset:9248
	ds_read_b128 v[72:75], v250 offset:13824
	ds_read_b128 v[76:79], v250 offset:13856
	s_add_i32 s20, s44, 6
	s_add_i32 s8, s44, 7
	v_cvt_pk_bf16_f32 v32, v8, v9
	v_cvt_pk_bf16_f32 v33, v10, v11
	v_cvt_pk_bf16_f32 v34, v12, v13
	v_cvt_pk_bf16_f32 v35, v14, v15
	v_cvt_pk_bf16_f32 v36, v0, v1
	v_cvt_pk_bf16_f32 v37, v2, v3
	v_cvt_pk_bf16_f32 v38, v4, v5
	v_cvt_pk_bf16_f32 v39, v6, v7
	v_cvt_pk_bf16_f32 v40, v24, v25
	v_cvt_pk_bf16_f32 v41, v26, v27
	v_cvt_pk_bf16_f32 v42, v28, v29
	v_cvt_pk_bf16_f32 v43, v30, v31
	v_cvt_pk_bf16_f32 v44, v16, v17
	v_cvt_pk_bf16_f32 v45, v18, v19
	v_cvt_pk_bf16_f32 v46, v20, v21
	v_cvt_pk_bf16_f32 v47, v22, v23
	s_lshl_b64 s[6:7], s[20:21], 14
	s_mul_hi_u32 s9, s8, 0x6000
	s_mulk_i32 s8, 0x6000
	s_waitcnt lgkmcnt(7)
	v_mfma_f32_32x32x16_bf16 a[0:15], v[48:51], v[44:47], a[0:15]
	s_waitcnt vmcnt(10)
	ds_write_b128 v221, a[156:159]
	ds_write_b128 v222, a[164:167]
	ds_write_b128 v223, a[172:175]
	ds_write_b128 v224, a[180:183]
	ds_write_b128 v225, a[188:191]
	ds_write_b128 v226, a[192:195]
	s_waitcnt lgkmcnt(11)
	v_mfma_f32_32x32x16_bf16 a[16:31], v[56:59], v[44:47], a[16:31]
	s_waitcnt lgkmcnt(9)
	v_mfma_f32_32x32x16_bf16 a[32:47], v[64:67], v[44:47], a[32:47]
	s_waitcnt lgkmcnt(7)
	v_mfma_f32_32x32x16_bf16 a[48:63], v[72:75], v[44:47], a[48:63]
	ds_read_b128 v[44:47], v250 offset:64
	ds_read_b128 v[48:51], v250 offset:4672
	ds_read_b128 v[56:59], v250 offset:9280
	ds_read_b128 v[64:67], v250 offset:13888
	v_mfma_f32_32x32x16_bf16 a[0:15], v[52:55], v[40:43], a[0:15]
	v_accvgpr_read_b32 v52, a229
	ds_write2_b64 v52, v[190:191], v[192:193] offset0:128 offset1:130
	v_accvgpr_read_b32 v52, a234
	ds_write2_b64 v52, v[202:203], v[204:205] offset0:192 offset1:194
	v_accvgpr_read_b32 v52, a235
	ds_write2_b64 v52, v[198:199], v[200:201] offset1:2
	v_accvgpr_read_b32 v52, a236
	v_mfma_f32_32x32x16_bf16 a[16:31], v[60:63], v[40:43], a[16:31]
	ds_write2_b64 v52, v[206:207], v[208:209] offset0:64 offset1:66
	v_mfma_f32_32x32x16_bf16 a[32:47], v[68:71], v[40:43], a[32:47]
	s_waitcnt lgkmcnt(14)
	v_mfma_f32_32x32x16_bf16 a[48:63], v[76:79], v[40:43], a[48:63]
	ds_read_b128 v[40:43], v250 offset:96
	ds_read_b128 v[52:55], v250 offset:4704
	ds_read_b128 v[60:63], v250 offset:9312
	ds_read_b128 v[68:71], v250 offset:13920
	s_add_u32 s8, s94, s8
	s_addc_u32 s9, s95, s9
	s_waitcnt lgkmcnt(11)
	v_mfma_f32_32x32x16_bf16 a[0:15], v[44:47], v[36:39], a[0:15]
	v_lshl_add_u64 v[44:45], s[8:9], 0, v[236:237]
	v_lshl_add_u64 v[46:47], s[8:9], 0, v[238:239]
	global_load_dwordx4 a[120:123], v[44:45], off
	global_load_dwordx4 a[124:127], v[46:47], off
	v_lshl_add_u64 v[44:45], s[8:9], 0, v[240:241]
	v_lshl_add_u64 v[46:47], s[8:9], 0, v[242:243]
	global_load_dwordx4 a[132:135], v[44:45], off
	global_load_dwordx4 a[136:139], v[46:47], off
	v_accvgpr_read_b32 v44, a230
	v_accvgpr_read_b32 v45, a231
	v_accvgpr_read_b32 v46, a232
	v_lshl_add_u64 v[44:45], s[8:9], 0, v[44:45]
	v_accvgpr_read_b32 v47, a233
	v_lshl_add_u64 v[46:47], s[8:9], 0, v[46:47]
	global_load_dwordx4 a[140:143], v[44:45], off
	global_load_dwordx4 a[144:147], v[46:47], off
	s_waitcnt lgkmcnt(10)
	v_mfma_f32_32x32x16_bf16 a[16:31], v[48:51], v[36:39], a[16:31]
	s_waitcnt lgkmcnt(9)
	v_mfma_f32_32x32x16_bf16 a[32:47], v[56:59], v[36:39], a[32:47]
	s_waitcnt lgkmcnt(8)
	v_mfma_f32_32x32x16_bf16 a[48:63], v[64:67], v[36:39], a[48:63]
	s_add_u32 s6, s60, s6
	s_addc_u32 s7, s61, s7
	s_waitcnt lgkmcnt(3)
	v_mfma_f32_32x32x16_bf16 a[0:15], v[40:43], v[32:35], a[0:15]
	s_waitcnt lgkmcnt(2)
	v_mfma_f32_32x32x16_bf16 a[16:31], v[52:55], v[32:35], a[16:31]
	s_waitcnt lgkmcnt(1)
	v_mfma_f32_32x32x16_bf16 a[32:47], v[60:63], v[32:35], a[32:47]
	s_waitcnt lgkmcnt(0)
	v_mfma_f32_32x32x16_bf16 a[48:63], v[68:71], v[32:35], a[48:63]
	v_lshl_add_u64 v[32:33], s[6:7], 0, v[236:237]
	global_load_dwordx4 a[244:247], v[32:33], off
	v_lshl_add_u64 v[32:33], s[6:7], 0, v[238:239]
	global_load_dwordx4 v[170:173], v[32:33], off
	v_lshl_add_u64 v[32:33], s[6:7], 0, v[240:241]
	global_load_dwordx4 v[166:169], v[32:33], off
	v_lshl_add_u64 v[32:33], s[6:7], 0, v[242:243]
	global_load_dwordx4 v[174:177], v[32:33], off
.LBB0_246:
	s_andn2_saveexec_b64 s[0:1], s[0:1]
	s_cbranch_execz .LBB0_207
	v_accvgpr_read_b32 v32, a229
	s_add_i32 s6, s44, 7
	s_waitcnt vmcnt(10)
	ds_write_b128 v221, a[156:159]
	ds_write_b128 v222, a[164:167]
	ds_write_b128 v223, a[172:175]
	ds_write_b128 v224, a[180:183]
	ds_write_b128 v225, a[188:191]
	ds_write_b128 v226, a[192:195]
	ds_write2_b64 v32, v[190:191], v[192:193] offset0:128 offset1:130
	v_accvgpr_read_b32 v32, a234
	s_add_i32 s20, s44, 6
	s_mul_hi_u32 s7, s6, 0x6000
	s_mulk_i32 s6, 0x6000
	ds_write2_b64 v32, v[202:203], v[204:205] offset0:192 offset1:194
	v_accvgpr_read_b32 v32, a235
	s_add_u32 s6, s94, s6
	ds_write2_b64 v32, v[198:199], v[200:201] offset1:2
	v_accvgpr_read_b32 v32, a236
	s_addc_u32 s7, s95, s7
	ds_write2_b64 v32, v[206:207], v[208:209] offset0:64 offset1:66
	v_lshl_add_u64 v[32:33], s[6:7], 0, v[236:237]
	global_load_dwordx4 a[120:123], v[32:33], off
	v_lshl_add_u64 v[32:33], s[6:7], 0, v[238:239]
	global_load_dwordx4 a[124:127], v[32:33], off
	v_lshl_add_u64 v[32:33], s[6:7], 0, v[240:241]
	global_load_dwordx4 a[132:135], v[32:33], off
	v_lshl_add_u64 v[32:33], s[6:7], 0, v[242:243]
	global_load_dwordx4 a[136:139], v[32:33], off
	v_accvgpr_read_b32 v32, a230
	v_accvgpr_read_b32 v33, a231
	v_lshl_add_u64 v[32:33], s[6:7], 0, v[32:33]
	global_load_dwordx4 a[140:143], v[32:33], off
	v_accvgpr_read_b32 v32, a232
	v_accvgpr_read_b32 v33, a233
	v_lshl_add_u64 v[32:33], s[6:7], 0, v[32:33]
	s_lshl_b64 s[6:7], s[20:21], 14
	s_add_u32 s6, s60, s6
	s_addc_u32 s7, s61, s7
	global_load_dwordx4 a[144:147], v[32:33], off
	v_lshl_add_u64 v[32:33], s[6:7], 0, v[236:237]
	global_load_dwordx4 a[244:247], v[32:33], off
	v_lshl_add_u64 v[32:33], s[6:7], 0, v[238:239]
	global_load_dwordx4 v[170:173], v[32:33], off
	v_lshl_add_u64 v[32:33], s[6:7], 0, v[240:241]
	global_load_dwordx4 v[166:169], v[32:33], off
	v_lshl_add_u64 v[32:33], s[6:7], 0, v[242:243]
	global_load_dwordx4 v[174:177], v[32:33], off
	s_branch .LBB0_207

; DI int crow(int reg, int h) { return (reg & 3) + 8 * (reg >> 2) + 4 * h; }
; template <int DQK>
; DI void attn_item_c(const u16* __restrict__ Qp, int ldq, const u16* __restrict__ Kp, const u16* __restrict__ Vtp, int ldv,
;                     int nkt, int q0, float c, u16* Yp, int ldy, char* smem, bool dry) {
;     ...
;   auto body = [&](int kt, u32x4* wk, u32x4* wv, f32x16& s0, f32x16& s1, f32x16& n0, f32x16& n1) {
;     const u16* Ks = L0 + (kt & 1) * BUFE;
;     const u16* Vs = Ks + 64 * KLD;
;     u16* Ln = L0 + ((kt + 1) & 1) * BUFE;
;     const bool active = !(kt * 64 > qmin + 31);
;     if (kt * 64 + 63 > qmin) {
; #pragma unroll
;       for (int e = 0; e < 16; ++e) {
;         int key = kt * 64 + crow(e, h);
;         if (key > qi) s0[e] = -INFINITY;
;         if (key + 32 > qi) s1[e] = -INFINITY;
;       }
;     }
.LBB0_262:
	s_lshl_b32 s45, s44, 6
	s_or_b32 s0, s45, 63
	v_cmp_gt_i32_e32 vcc, s0, v233
	s_and_saveexec_b64 s[46:47], vcc
	s_cbranch_execz .LBB0_266
	v_accvgpr_read_b32 v32, a64
	v_accvgpr_read_b32 v0, a80
	v_accvgpr_read_b32 v33, a65
	v_accvgpr_read_b32 v34, a66
	v_accvgpr_read_b32 v35, a67
	v_accvgpr_read_b32 v36, a68
	v_accvgpr_read_b32 v37, a69
	v_accvgpr_read_b32 v38, a70
	v_accvgpr_read_b32 v39, a71
	v_accvgpr_read_b32 v40, a72
	v_accvgpr_read_b32 v41, a73
	v_accvgpr_read_b32 v42, a74
	v_accvgpr_read_b32 v43, a75
	v_accvgpr_read_b32 v44, a76
	v_accvgpr_read_b32 v45, a77
	v_accvgpr_read_b32 v46, a78
	v_accvgpr_read_b32 v47, a79
	v_accvgpr_read_b32 v1, a81
	v_accvgpr_read_b32 v2, a82
	v_accvgpr_read_b32 v3, a83
	v_accvgpr_read_b32 v4, a84
	v_accvgpr_read_b32 v5, a85
	v_accvgpr_read_b32 v6, a86
	v_accvgpr_read_b32 v7, a87
	v_accvgpr_read_b32 v8, a88
	v_accvgpr_read_b32 v9, a89
	v_accvgpr_read_b32 v10, a90
	v_accvgpr_read_b32 v11, a91
	v_accvgpr_read_b32 v12, a92
	v_accvgpr_read_b32 v13, a93
	v_accvgpr_read_b32 v14, a94
	v_accvgpr_read_b32 v15, a95
	v_accvgpr_read_b32 v129, a237
	v_or_b32_e32 v129, s45, v129
	v_or_b32_e32 v146, 32, v129
	v_cmp_le_i32_e64 s[0:1], v146, v234
	v_or_b32_e32 v146, 33, v129
	v_mov_b32_e32 v147, 0xff800000
	v_cmp_le_i32_e64 s[6:7], v146, v234
	v_or_b32_e32 v146, 2, v129
	v_cmp_le_i32_e32 vcc, v129, v234
	v_cndmask_b32_e64 v33, v147, v33, s[6:7]
	v_cmp_le_i32_e64 s[6:7], v146, v234
	v_or_b32_e32 v146, 34, v129
	v_cmp_le_i32_e64 s[8:9], v146, v234
	v_or_b32_e32 v146, 3, v129
	v_cndmask_b32_e64 v32, v147, v32, s[0:1]
	v_cndmask_b32_e64 v34, v147, v34, s[8:9]
	v_cmp_le_i32_e64 s[8:9], v146, v234
	v_or_b32_e32 v146, 35, v129
	v_cmp_le_i32_e64 s[10:11], v146, v234
	v_or_b32_e32 v146, 8, v129
	v_cmp_lt_i32_e64 s[0:1], v129, v234
	v_cndmask_b32_e64 v35, v147, v35, s[10:11]
	v_cmp_le_i32_e64 s[10:11], v146, v234
	v_or_b32_e32 v146, 40, v129
	v_cmp_le_i32_e64 s[12:13], v146, v234
	v_or_b32_e32 v146, 9, v129
	s_nop 0
	v_cndmask_b32_e64 v36, v147, v36, s[12:13]
	v_cmp_le_i32_e64 s[12:13], v146, v234
	v_or_b32_e32 v146, 41, v129
	v_cmp_le_i32_e64 s[14:15], v146, v234
	v_or_b32_e32 v146, 10, v129
	s_nop 0
	v_cndmask_b32_e64 v37, v147, v37, s[14:15]
	v_cmp_le_i32_e64 s[14:15], v146, v234
	v_or_b32_e32 v146, 42, v129
	v_cmp_le_i32_e64 s[16:17], v146, v234
	v_or_b32_e32 v146, 11, v129
	s_nop 0
	v_cndmask_b32_e64 v38, v147, v38, s[16:17]
	v_cmp_le_i32_e64 s[16:17], v146, v234
	v_or_b32_e32 v146, 43, v129
	v_cmp_le_i32_e64 s[18:19], v146, v234
	v_or_b32_e32 v146, 16, v129
	s_nop 0
	v_cndmask_b32_e64 v39, v147, v39, s[18:19]
	v_cmp_le_i32_e64 s[18:19], v146, v234
	v_or_b32_e32 v146, 48, v129
	v_cmp_le_i32_e64 s[22:23], v146, v234
	v_or_b32_e32 v146, 17, v129
	s_nop 0
	v_cndmask_b32_e64 v40, v147, v40, s[22:23]
	v_cmp_le_i32_e64 s[22:23], v146, v234
	v_or_b32_e32 v146, 49, v129
	v_cmp_le_i32_e64 s[24:25], v146, v234
	v_or_b32_e32 v146, 18, v129
	s_nop 0
	v_cndmask_b32_e64 v41, v147, v41, s[24:25]
	v_cmp_le_i32_e64 s[24:25], v146, v234
	v_or_b32_e32 v146, 50, v129
	v_cmp_le_i32_e64 s[26:27], v146, v234
	v_or_b32_e32 v146, 19, v129
	s_nop 0
	v_cndmask_b32_e64 v42, v147, v42, s[26:27]
	v_cmp_le_i32_e64 s[26:27], v146, v234
	v_or_b32_e32 v146, 51, v129
	v_cmp_le_i32_e64 s[28:29], v146, v234
	v_or_b32_e32 v146, 24, v129
	s_nop 0
	v_cndmask_b32_e64 v43, v147, v43, s[28:29]
	v_cmp_le_i32_e64 s[28:29], v146, v234
	v_or_b32_e32 v146, 56, v129
	v_cmp_le_i32_e64 s[30:31], v146, v234
	v_or_b32_e32 v146, 25, v129
	s_nop 0
	v_cndmask_b32_e64 v44, v147, v44, s[30:31]
	v_cmp_le_i32_e64 s[30:31], v146, v234
	v_or_b32_e32 v146, 57, v129
	v_cmp_le_i32_e64 s[34:35], v146, v234
	v_or_b32_e32 v146, 26, v129
	s_nop 0
	v_cndmask_b32_e64 v45, v147, v45, s[34:35]
	v_cmp_le_i32_e64 s[34:35], v146, v234
	v_or_b32_e32 v146, 58, v129
	v_cmp_le_i32_e64 s[36:37], v146, v234
	v_or_b32_e32 v146, 27, v129
	v_or_b32_e32 v129, 59, v129
	v_cndmask_b32_e64 v46, v147, v46, s[36:37]
	v_cmp_le_i32_e64 s[36:37], v146, v234
	v_cmp_gt_i32_e64 s[40:41], v129, v234
	s_and_saveexec_b64 s[48:49], s[40:41]
	v_mov_b32_e32 v47, s65
	s_or_b64 exec, exec, s[48:49]
	v_accvgpr_write_b32 a79, v47
	v_accvgpr_write_b32 a78, v46
	v_accvgpr_write_b32 a77, v45
	v_accvgpr_write_b32 a76, v44
	v_accvgpr_write_b32 a75, v43
	v_accvgpr_write_b32 a74, v42
	v_accvgpr_write_b32 a73, v41
	v_accvgpr_write_b32 a72, v40
	v_accvgpr_write_b32 a71, v39
	v_accvgpr_write_b32 a70, v38
	v_accvgpr_write_b32 a69, v37
	v_accvgpr_write_b32 a68, v36
	v_accvgpr_write_b32 a67, v35
	v_accvgpr_write_b32 a66, v34
	v_accvgpr_write_b32 a65, v33
	v_accvgpr_write_b32 a64, v32
	v_mov_b32_e32 v32, 0xff800000
	v_cndmask_b32_e64 v1, v32, v1, s[0:1]
	v_cndmask_b32_e32 v0, v32, v0, vcc
	v_cndmask_b32_e64 v2, v32, v2, s[6:7]
	v_cndmask_b32_e64 v3, v32, v3, s[8:9]
	v_cndmask_b32_e64 v4, v32, v4, s[10:11]
	v_cndmask_b32_e64 v5, v32, v5, s[12:13]
	v_cndmask_b32_e64 v6, v32, v6, s[14:15]
	v_cndmask_b32_e64 v7, v32, v7, s[16:17]
	v_cndmask_b32_e64 v8, v32, v8, s[18:19]
	v_cndmask_b32_e64 v9, v32, v9, s[22:23]
	v_cndmask_b32_e64 v10, v32, v10, s[24:25]
	v_cndmask_b32_e64 v11, v32, v11, s[26:27]
	v_cndmask_b32_e64 v12, v32, v12, s[28:29]
	v_cndmask_b32_e64 v13, v32, v13, s[30:31]
	v_cndmask_b32_e64 v14, v32, v14, s[34:35]
	v_cndmask_b32_e64 v15, v32, v15, s[36:37]
	v_accvgpr_write_b32 a80, v0
	v_accvgpr_write_b32 a81, v1
	v_accvgpr_write_b32 a82, v2
	v_accvgpr_write_b32 a83, v3
	v_accvgpr_write_b32 a84, v4
	v_accvgpr_write_b32 a85, v5
	v_accvgpr_write_b32 a86, v6
	v_accvgpr_write_b32 a87, v7
	v_accvgpr_write_b32 a88, v8
	v_accvgpr_write_b32 a89, v9
	v_accvgpr_write_b32 a90, v10
	v_accvgpr_write_b32 a91, v11
	v_accvgpr_write_b32 a92, v12
	v_accvgpr_write_b32 a93, v13
	v_accvgpr_write_b32 a94, v14
	v_accvgpr_write_b32 a95, v15
	s_mov_b64 s[40:41], s[70:71]

; #define MFMA32(a, b, c) __builtin_amdgcn_mfma_f32_32x32x16_bf16((a), (b), (c), 0, 0, 0)
; DI float ex2(float x) { return __builtin_amdgcn_exp2f(x); }
; template <int DQK>
; DI void attn_item_c(const u16* __restrict__ Qp, int ldq, const u16* __restrict__ Kp, const u16* __restrict__ Vtp, int ldv,
;                     int nkt, int q0, float c, u16* Yp, int ldy, char* smem, bool dry) {
;     ...
;     const float mc = m * c;
; #pragma unroll
;     for (int e = 0; e < 16; ++e) { n0[e] = 0.f; n1[e] = 0.f; }
;     const u16* k0 = Ks + r * KLD + 8 * h;
;     bf16x8 ka[3][2];
;     ka[0][0] = *(const bf16x8*)(k0); ka[0][1] = *(const bf16x8*)(k0 + 32 * KLD);
;     ka[1][0] = *(const bf16x8*)(k0 + 16); ka[1][1] = *(const bf16x8*)(k0 + 32 * KLD + 16);
;     bf16x8 pf[4];
;     u32x4 pk[4];
;     float ps = 0.f;
; #pragma unroll
;     for (int ks = 0; ks < NKS; ++ks) {
;       if (ks + 2 < NKS) {
;         ka[(ks + 2) % 3][0] = *(const bf16x8*)(k0 + 16 * (ks + 2));
;         ka[(ks + 2) % 3][1] = *(const bf16x8*)(k0 + 32 * KLD + 16 * (ks + 2));
;       }
;       __builtin_amdgcn_sched_barrier(0);
;       n0 = MFMA32(ka[ks % 3][0], qf[ks], n0); n1 = MFMA32(ka[ks % 3][1], qf[ks], n1);
;       {
;         constexpr int dummy0 = 0; (void)dummy0;
;         const int e_lo = (32 * ks) / NKS, e_hi = (32 * (ks + 1)) / NKS;
; #pragma unroll
;         for (int q = 0; q < 3; ++q) {
;           const int e = e_lo + q;
;           if (e < e_hi) {
;             if (e < 16) { s0[e & 15] = ex2(fmaf(s0[e & 15], c, -mc)); ps += s0[e & 15]; }
;             else        { s1[e & 15] = ex2(fmaf(s1[e & 15], c, -mc)); ps += s1[e & 15]; }
;           }
;         }
;       }
.LBB0_268:
	ds_read_b128 v[16:19], v212
	ds_read_b128 v[20:23], v212 offset:32
	ds_read_b128 v[24:27], v212 offset:12800
	ds_read_b128 v[28:31], v212 offset:64
	ds_read_b128 v[48:51], v212 offset:12832
	ds_read_b128 v[52:55], v212 offset:12864
	v_accvgpr_read_b32 v56, a238
	v_mul_f32_e32 v249, 0xbdd53b94, v216
	v_cmp_le_i32_e32 vcc, s45, v56
	s_waitcnt lgkmcnt(5)
	v_mfma_f32_32x32x16_bf16 a[80:95], v[16:19], v[96:99], 0
	v_fmamk_f32 v16, v32, 0x3dd53b94, v249
	v_exp_f32_e32 v191, v16
	v_fmamk_f32 v16, v33, 0x3dd53b94, v249
	v_exp_f32_e32 v192, v16
	s_waitcnt lgkmcnt(3)
	v_mfma_f32_32x32x16_bf16 a[64:79], v[24:27], v[96:99], 0
	ds_read_b128 v[16:19], v212 offset:96
	ds_read_b128 v[24:27], v212 offset:12896
	v_mfma_f32_32x32x16_bf16 a[80:95], v[20:23], v[100:103], a[80:95]
	v_fmamk_f32 v20, v34, 0x3dd53b94, v249
	v_exp_f32_e32 v193, v20
	v_fmamk_f32 v20, v35, 0x3dd53b94, v249
	v_exp_f32_e32 v198, v20
	v_fmamk_f32 v20, v36, 0x3dd53b94, v249
	v_exp_f32_e32 v199, v20
	s_waitcnt lgkmcnt(3)
	v_mfma_f32_32x32x16_bf16 a[64:79], v[48:51], v[100:103], a[64:79]
	ds_read_b128 v[20:23], v212 offset:128
	ds_read_b128 v[32:35], v212 offset:12928
	v_mfma_f32_32x32x16_bf16 a[80:95], v[28:31], v[104:107], a[80:95]
	v_fmamk_f32 v28, v37, 0x3dd53b94, v249
	v_exp_f32_e32 v200, v28
	v_fmamk_f32 v28, v38, 0x3dd53b94, v249
	v_exp_f32_e32 v201, v28
	v_fmamk_f32 v28, v39, 0x3dd53b94, v249
	v_exp_f32_e32 v202, v28
	s_waitcnt lgkmcnt(4)
	v_mfma_f32_32x32x16_bf16 a[64:79], v[52:55], v[104:107], a[64:79]
	ds_read_b128 v[28:31], v212 offset:160
	ds_read_b128 v[36:39], v212 offset:12960
	s_waitcnt lgkmcnt(5)
	v_mfma_f32_32x32x16_bf16 a[80:95], v[16:19], v[108:111], a[80:95]
	v_fmamk_f32 v16, v40, 0x3dd53b94, v249
	v_exp_f32_e32 v203, v16
	v_fmamk_f32 v16, v41, 0x3dd53b94, v249
	v_exp_f32_e32 v204, v16
	s_waitcnt lgkmcnt(4)
	v_mfma_f32_32x32x16_bf16 a[64:79], v[24:27], v[108:111], a[64:79]
	ds_read_b128 v[16:19], v212 offset:192
	ds_read_b128 v[24:27], v212 offset:12992
	s_waitcnt lgkmcnt(5)
	v_mfma_f32_32x32x16_bf16 a[80:95], v[20:23], v[112:115], a[80:95]
	v_fmamk_f32 v20, v42, 0x3dd53b94, v249
	v_exp_f32_e32 v205, v20
	v_fmamk_f32 v20, v43, 0x3dd53b94, v249
	v_exp_f32_e32 v206, v20
	v_fmamk_f32 v20, v44, 0x3dd53b94, v249
	v_exp_f32_e32 v207, v20
	s_waitcnt lgkmcnt(4)
	v_mfma_f32_32x32x16_bf16 a[64:79], v[32:35], v[112:115], a[64:79]
	ds_read_b128 v[20:23], v212 offset:224
	ds_read_b128 v[32:35], v212 offset:13024
	s_waitcnt lgkmcnt(5)
	v_mfma_f32_32x32x16_bf16 a[80:95], v[28:31], v[116:119], a[80:95]
	v_fmamk_f32 v28, v45, 0x3dd53b94, v249
	v_exp_f32_e32 v208, v28
	v_fmamk_f32 v28, v46, 0x3dd53b94, v249
	v_exp_f32_e32 v209, v28
	v_fmamk_f32 v28, v47, 0x3dd53b94, v249
	v_exp_f32_e32 v248, v28
	s_waitcnt lgkmcnt(4)
	v_mfma_f32_32x32x16_bf16 a[64:79], v[36:39], v[116:119], a[64:79]
	ds_read_b128 v[28:31], v212 offset:256
	ds_read_b128 v[36:39], v212 offset:13056
	s_waitcnt lgkmcnt(5)
	v_mfma_f32_32x32x16_bf16 a[80:95], v[16:19], v[120:123], a[80:95]
	v_fmamk_f32 v0, v0, 0x3dd53b94, v249
	v_exp_f32_e32 v213, v0
	v_fmamk_f32 v0, v1, 0x3dd53b94, v249
	v_exp_f32_e32 v214, v0
	s_waitcnt lgkmcnt(4)
	v_mfma_f32_32x32x16_bf16 a[64:79], v[24:27], v[120:123], a[64:79]
	ds_read_b128 v[16:19], v212 offset:288
	ds_read_b128 v[24:27], v212 offset:13088
	s_waitcnt lgkmcnt(5)
	v_mfma_f32_32x32x16_bf16 a[80:95], v[20:23], v[124:127], a[80:95]
	v_fmamk_f32 v0, v2, 0x3dd53b94, v249
	v_exp_f32_e32 v129, v0
	v_fmamk_f32 v0, v3, 0x3dd53b94, v249
	v_exp_f32_e32 v215, v0
	v_fmamk_f32 v0, v4, 0x3dd53b94, v249
	v_exp_f32_e32 v227, v0
	s_waitcnt lgkmcnt(4)
	v_mfma_f32_32x32x16_bf16 a[64:79], v[32:35], v[124:127], a[64:79]
	ds_read_b128 v[0:3], v212 offset:320
	ds_read_b128 v[20:23], v212 offset:13120
	s_waitcnt lgkmcnt(5)
	v_mfma_f32_32x32x16_bf16 a[80:95], v[28:31], v[130:133], a[80:95]
	v_fmamk_f32 v4, v5, 0x3dd53b94, v249
	v_exp_f32_e32 v228, v4
	v_fmamk_f32 v4, v6, 0x3dd53b94, v249
	v_exp_f32_e32 v229, v4
	v_fmamk_f32 v4, v7, 0x3dd53b94, v249
	v_exp_f32_e32 v230, v4
	s_waitcnt lgkmcnt(4)
	v_mfma_f32_32x32x16_bf16 a[64:79], v[36:39], v[130:133], a[64:79]
	ds_read_b128 v[4:7], v212 offset:352
	ds_read_b128 v[28:31], v212 offset:13152
	s_waitcnt lgkmcnt(5)
	v_mfma_f32_32x32x16_bf16 a[80:95], v[16:19], v[134:137], a[80:95]
	v_fmamk_f32 v8, v8, 0x3dd53b94, v249
	v_exp_f32_e32 v149, v8
	v_fmamk_f32 v8, v9, 0x3dd53b94, v249
	v_exp_f32_e32 v218, v8
	s_waitcnt lgkmcnt(4)
	v_mfma_f32_32x32x16_bf16 a[64:79], v[24:27], v[134:137], a[64:79]
	s_waitcnt lgkmcnt(3)
	v_mfma_f32_32x32x16_bf16 a[80:95], v[0:3], v[138:141], a[80:95]
	v_fmamk_f32 v0, v10, 0x3dd53b94, v249
	v_exp_f32_e32 v231, v0
	v_fmamk_f32 v0, v11, 0x3dd53b94, v249
	v_exp_f32_e32 v235, v0
	v_fmamk_f32 v0, v12, 0x3dd53b94, v249
	v_exp_f32_e32 v244, v0
	s_waitcnt lgkmcnt(2)
	v_mfma_f32_32x32x16_bf16 a[64:79], v[20:23], v[138:141], a[64:79]
	s_waitcnt lgkmcnt(1)
	v_mfma_f32_32x32x16_bf16 a[80:95], v[4:7], v[142:145], a[80:95]
	v_fmamk_f32 v0, v13, 0x3dd53b94, v249
	v_exp_f32_e32 v146, v0
	v_fmamk_f32 v0, v14, 0x3dd53b94, v249
	v_exp_f32_e32 v147, v0
	v_fmamk_f32 v0, v15, 0x3dd53b94, v249
	v_exp_f32_e32 v148, v0
	s_waitcnt lgkmcnt(0)
	v_mfma_f32_32x32x16_bf16 a[64:79], v[28:31], v[142:145], a[64:79]
	v_add_u32_e32 v211, 0x1000, v220
	v_add_u32_e32 v251, 0x2000, v220
	v_add_u32_e32 v210, 0x3000, v220
	s_and_saveexec_b64 s[0:1], vcc
	s_xor_b64 s[0:1], exec, s[0:1]
	s_cbranch_execz .LBB0_270
; #define MFMA32(a, b, c) __builtin_amdgcn_mfma_f32_32x32x16_bf16((a), (b), (c), 0, 0, 0)
; template <int DQK>
; DI void attn_item_c(const u16* __restrict__ Qp, int ldq, const u16* __restrict__ Kp, const u16* __restrict__ Vtp, int ldv,
;                     int nkt, int q0, float c, u16* Yp, int ldy, char* smem, bool dry) {
;     ...
;   auto gloadK = [&](u32x4* ks_, int j) {
;     const u16* kg = Kp + (size_t)(j + 1) * 64 * DQK;
; #pragma unroll
;     for (int i = 0; i < NKC; ++i) ks_[i] = *(const u32x4*)(kg + (size_t)(tid + 256 * i) * 8);
;   };
;   auto gloadV = [&](u32x4* vs_, int j) {
; #pragma unroll
;     for (int i = 0; i < 4; ++i) vs_[i] = *(const u32x4*)(Vtp + (size_t)j * 8192 + (size_t)(tid + 256 * i) * 8);
;   };
;   auto lstoreK = [&](const u32x4* ks_, u16* Lb) {
; #pragma unroll
;     for (int i = 0; i < NKC; ++i) *(u32x4*)(Lb + kso[i]) = ks_[i];
;   };
;   auto lstoreV = [&](const u32x4* vs_, u16* Lb) {
; #pragma unroll
;     for (int i = 0; i < 4; ++i) {
;       u16* dst = Lb + vso + (32 * i) * 72;
;       u32x2 lo = {vs_[i].x, vs_[i].y}, hi = {vs_[i].z, vs_[i].w};
;       *(u32x2*)dst = lo; *(u32x2*)(dst + 8) = hi;
;     }
;   };
;     ...
;     for (int i = 0; i < 4; ++i) pf[i] = __builtin_bit_cast(bf16x8, pk[i]);
;     if (active) {
;       const u16* v0 = Vs + r * 72 + 8 * h;
;       bf16x8 va[2][4];
; #pragma unroll
;       for (int dt = 0; dt < 4; ++dt) va[0][dt] = *(const bf16x8*)(v0 + (32 * dt) * 72);
; #pragma unroll
;       for (int kk = 0; kk < 4; ++kk) {
;         if (kk < 3) {
; #pragma unroll
;           for (int dt = 0; dt < 4; ++dt) va[(kk + 1) & 1][dt] = *(const bf16x8*)(v0 + (32 * dt) * 72 + 16 * (kk + 1));
;         }
;         __builtin_amdgcn_sched_barrier(0);
; #pragma unroll
;         for (int dt = 0; dt < 4; ++dt) o[dt] = MFMA32(va[kk & 1][dt], pf[kk], o[dt]);
;         if (kk == 0) lstoreK(wk, Ln);
;         if (kk == 1) lstoreV(wv, Ln);
;         if (kk == 2) gloadK(wk, kt + 3);
;         if (kk == 3) gloadV(wv, kt + 3);
;         __builtin_amdgcn_sched_barrier(0);
;       }
	ds_read_b128 v[16:19], v128 offset:25600
	ds_read_b128 v[20:23], v128 offset:25632
	ds_read_b128 v[24:27], v128 offset:30208
	ds_read_b128 v[28:31], v128 offset:30240
	ds_read_b128 v[32:35], v128 offset:34816
	ds_read_b128 v[36:39], v128 offset:34848
	ds_read_b128 v[40:43], v128 offset:39424
	ds_read_b128 v[44:47], v128 offset:39456
	s_or_b32 s20, s44, 3
	s_add_i32 s8, s44, 4
	v_cvt_pk_bf16_f32 v0, v149, v218
	v_cvt_pk_bf16_f32 v1, v231, v235
	v_cvt_pk_bf16_f32 v2, v244, v146
	v_cvt_pk_bf16_f32 v3, v147, v148
	v_cvt_pk_bf16_f32 v4, v213, v214
	v_cvt_pk_bf16_f32 v5, v129, v215
	v_cvt_pk_bf16_f32 v6, v227, v228
	v_cvt_pk_bf16_f32 v7, v229, v230
	v_cvt_pk_bf16_f32 v8, v203, v204
	v_cvt_pk_bf16_f32 v9, v205, v206
	v_cvt_pk_bf16_f32 v10, v207, v208
	v_cvt_pk_bf16_f32 v11, v209, v248
	v_cvt_pk_bf16_f32 v12, v191, v192
	v_cvt_pk_bf16_f32 v13, v193, v198
	v_cvt_pk_bf16_f32 v14, v199, v200
	v_cvt_pk_bf16_f32 v15, v201, v202
	s_lshl_b64 s[6:7], s[20:21], 14
	s_mul_hi_u32 s9, s8, 0x6000
	s_mulk_i32 s8, 0x6000
	s_waitcnt lgkmcnt(7)
	v_mfma_f32_32x32x16_bf16 a[0:15], v[16:19], v[12:15], a[0:15]
	s_waitcnt vmcnt(10)
	ds_write_b128 v221, a[96:99] offset:44032
	ds_write_b128 v222, a[100:103] offset:44032
	ds_write_b128 v223, a[104:107] offset:44032
	ds_write_b128 v224, a[108:111] offset:44032
	ds_write_b128 v225, a[112:115] offset:44032
	ds_write_b128 v226, a[116:119] offset:44032
	s_waitcnt lgkmcnt(11)
	v_mfma_f32_32x32x16_bf16 a[16:31], v[24:27], v[12:15], a[16:31]
	s_waitcnt lgkmcnt(9)
	v_mfma_f32_32x32x16_bf16 a[32:47], v[32:35], v[12:15], a[32:47]
	s_waitcnt lgkmcnt(7)
	v_mfma_f32_32x32x16_bf16 a[48:63], v[40:43], v[12:15], a[48:63]
	ds_read_b128 v[12:15], v128 offset:25664
	ds_read_b128 v[16:19], v128 offset:30272
	ds_read_b128 v[24:27], v128 offset:34880
	ds_read_b128 v[32:35], v128 offset:39488
	v_mfma_f32_32x32x16_bf16 a[0:15], v[20:23], v[8:11], a[0:15]
	v_accvgpr_read_b32 v20, a240
	v_accvgpr_read_b32 v21, a241
	v_accvgpr_read_b32 v22, a242
	v_accvgpr_read_b32 v23, a243
	ds_write2_b64 v220, v[20:21], v[22:23] offset1:2
	ds_write2_b64 v211, v[150:151], v[152:153] offset0:64 offset1:66
	ds_write2_b64 v251, v[154:155], v[156:157] offset0:128 offset1:130
	ds_write2_b64 v210, v[158:159], v[160:161] offset0:192 offset1:194
	v_mfma_f32_32x32x16_bf16 a[16:31], v[28:31], v[8:11], a[16:31]
	v_mfma_f32_32x32x16_bf16 a[32:47], v[36:39], v[8:11], a[32:47]
	s_waitcnt lgkmcnt(14)
	v_mfma_f32_32x32x16_bf16 a[48:63], v[44:47], v[8:11], a[48:63]
	ds_read_b128 v[8:11], v128 offset:25696
	ds_read_b128 v[20:23], v128 offset:30304
	ds_read_b128 v[28:31], v128 offset:34912
	ds_read_b128 v[36:39], v128 offset:39520
	s_add_u32 s8, s94, s8
	s_addc_u32 s9, s95, s9
	s_waitcnt lgkmcnt(11)
	v_mfma_f32_32x32x16_bf16 a[0:15], v[12:15], v[4:7], a[0:15]
	v_lshl_add_u64 v[12:13], s[8:9], 0, v[236:237]
	v_lshl_add_u64 v[14:15], s[8:9], 0, v[238:239]
	global_load_dwordx4 a[148:151], v[12:13], off
	global_load_dwordx4 a[152:155], v[14:15], off
	v_lshl_add_u64 v[12:13], s[8:9], 0, v[240:241]
	v_lshl_add_u64 v[14:15], s[8:9], 0, v[242:243]
	global_load_dwordx4 a[160:163], v[12:13], off
	global_load_dwordx4 a[168:171], v[14:15], off
	v_accvgpr_read_b32 v12, a230
	v_accvgpr_read_b32 v13, a231
	v_accvgpr_read_b32 v14, a232
	v_lshl_add_u64 v[12:13], s[8:9], 0, v[12:13]
	v_accvgpr_read_b32 v15, a233
	v_lshl_add_u64 v[14:15], s[8:9], 0, v[14:15]
	global_load_dwordx4 a[176:179], v[12:13], off
	global_load_dwordx4 a[184:187], v[14:15], off
	s_waitcnt lgkmcnt(10)
	v_mfma_f32_32x32x16_bf16 a[16:31], v[16:19], v[4:7], a[16:31]
	s_waitcnt lgkmcnt(9)
	v_mfma_f32_32x32x16_bf16 a[32:47], v[24:27], v[4:7], a[32:47]
	s_waitcnt lgkmcnt(8)
	v_mfma_f32_32x32x16_bf16 a[48:63], v[32:35], v[4:7], a[48:63]
	s_add_u32 s6, s60, s6
	s_addc_u32 s7, s61, s7
	s_waitcnt lgkmcnt(3)
	v_mfma_f32_32x32x16_bf16 a[0:15], v[8:11], v[0:3], a[0:15]
	s_waitcnt lgkmcnt(2)
	v_mfma_f32_32x32x16_bf16 a[16:31], v[20:23], v[0:3], a[16:31]
	s_waitcnt lgkmcnt(1)
	v_mfma_f32_32x32x16_bf16 a[32:47], v[28:31], v[0:3], a[32:47]
	s_waitcnt lgkmcnt(0)
	v_mfma_f32_32x32x16_bf16 a[48:63], v[36:39], v[0:3], a[48:63]
	v_lshl_add_u64 v[0:1], s[6:7], 0, v[236:237]
	global_load_dwordx4 v[178:181], v[0:1], off
	v_lshl_add_u64 v[0:1], s[6:7], 0, v[238:239]
	global_load_dwordx4 v[186:189], v[0:1], off
	v_lshl_add_u64 v[0:1], s[6:7], 0, v[240:241]
	global_load_dwordx4 v[182:185], v[0:1], off
	v_lshl_add_u64 v[0:1], s[6:7], 0, v[242:243]
	global_load_dwordx4 v[194:197], v[0:1], off

; DI int crow(int reg, int h) { return (reg & 3) + 8 * (reg >> 2) + 4 * h; }
; template <int DQK>
; DI void attn_item_c(const u16* __restrict__ Qp, int ldq, const u16* __restrict__ Kp, const u16* __restrict__ Vtp, int ldv,
;                     int nkt, int q0, float c, u16* Yp, int ldy, char* smem, bool dry) {
;     ...
;   auto body = [&](int kt, u32x4* wk, u32x4* wv, f32x16& s0, f32x16& s1, f32x16& n0, f32x16& n1) {
;     const u16* Ks = L0 + (kt & 1) * BUFE;
;     const u16* Vs = Ks + 64 * KLD;
;     u16* Ln = L0 + ((kt + 1) & 1) * BUFE;
;     const bool active = !(kt * 64 > qmin + 31);
;     if (kt * 64 + 63 > qmin) {
; #pragma unroll
;       for (int e = 0; e < 16; ++e) {
;         int key = kt * 64 + crow(e, h);
;         if (key > qi) s0[e] = -INFINITY;
;         if (key + 32 > qi) s1[e] = -INFINITY;
;       }
;     }
;     ...
;     __syncthreads();
.LBB0_272:
	s_or_b64 exec, exec, s[0:1]
	s_nop 0
	s_or_b32 s0, s45, 0x7f
	s_or_b32 s20, s45, 64
	v_cmp_gt_i32_e32 vcc, s0, v233
	s_waitcnt lgkmcnt(0)
	s_barrier
	s_and_saveexec_b64 s[46:47], vcc
	s_cbranch_execz .LBB0_276
	v_accvgpr_read_b32 v0, a80
	v_accvgpr_read_b32 v32, a64
	v_accvgpr_read_b32 v1, a81
	v_accvgpr_read_b32 v2, a82
	v_accvgpr_read_b32 v3, a83
	v_accvgpr_read_b32 v4, a84
	v_accvgpr_read_b32 v5, a85
	v_accvgpr_read_b32 v6, a86
	v_accvgpr_read_b32 v7, a87
	v_accvgpr_read_b32 v8, a88
	v_accvgpr_read_b32 v9, a89
	v_accvgpr_read_b32 v10, a90
	v_accvgpr_read_b32 v11, a91
	v_accvgpr_read_b32 v12, a92
	v_accvgpr_read_b32 v13, a93
	v_accvgpr_read_b32 v14, a94
	v_accvgpr_read_b32 v15, a95
	v_accvgpr_read_b32 v33, a65
	v_accvgpr_read_b32 v34, a66
	v_accvgpr_read_b32 v35, a67
	v_accvgpr_read_b32 v36, a68
	v_accvgpr_read_b32 v37, a69
	v_accvgpr_read_b32 v38, a70
	v_accvgpr_read_b32 v39, a71
	v_accvgpr_read_b32 v40, a72
	v_accvgpr_read_b32 v41, a73
	v_accvgpr_read_b32 v42, a74
	v_accvgpr_read_b32 v43, a75
	v_accvgpr_read_b32 v44, a76
	v_accvgpr_read_b32 v45, a77
	v_accvgpr_read_b32 v46, a78
	v_accvgpr_read_b32 v47, a79
	v_accvgpr_read_b32 v150, a237
	v_or_b32_e32 v150, s20, v150
	v_or_b32_e32 v151, 32, v150
	v_cmp_le_i32_e64 s[0:1], v151, v234
	v_or_b32_e32 v151, 33, v150
	v_mov_b32_e32 v152, 0xff800000
	v_cmp_le_i32_e64 s[6:7], v151, v234
	v_or_b32_e32 v151, 2, v150
	v_cmp_le_i32_e32 vcc, v150, v234
	v_cndmask_b32_e64 v33, v152, v33, s[6:7]
	v_cmp_le_i32_e64 s[6:7], v151, v234
	v_or_b32_e32 v151, 34, v150
	v_cmp_le_i32_e64 s[8:9], v151, v234
	v_or_b32_e32 v151, 3, v150
	v_cndmask_b32_e64 v32, v152, v32, s[0:1]
	v_cndmask_b32_e64 v34, v152, v34, s[8:9]
	v_cmp_le_i32_e64 s[8:9], v151, v234
	v_or_b32_e32 v151, 35, v150
	v_cmp_le_i32_e64 s[10:11], v151, v234
	v_or_b32_e32 v151, 8, v150
	v_cmp_lt_i32_e64 s[0:1], v150, v234
	v_cndmask_b32_e64 v35, v152, v35, s[10:11]
	v_cmp_le_i32_e64 s[10:11], v151, v234
	v_or_b32_e32 v151, 40, v150
	v_cmp_le_i32_e64 s[12:13], v151, v234
	v_or_b32_e32 v151, 9, v150
	s_nop 0
	v_cndmask_b32_e64 v36, v152, v36, s[12:13]
	v_cmp_le_i32_e64 s[12:13], v151, v234
	v_or_b32_e32 v151, 41, v150
	v_cmp_le_i32_e64 s[14:15], v151, v234
	v_or_b32_e32 v151, 10, v150
	s_nop 0
	v_cndmask_b32_e64 v37, v152, v37, s[14:15]
	v_cmp_le_i32_e64 s[14:15], v151, v234
	v_or_b32_e32 v151, 42, v150
	v_cmp_le_i32_e64 s[16:17], v151, v234
	v_or_b32_e32 v151, 11, v150
	s_nop 0
	v_cndmask_b32_e64 v38, v152, v38, s[16:17]
	v_cmp_le_i32_e64 s[16:17], v151, v234
	v_or_b32_e32 v151, 43, v150
	v_cmp_le_i32_e64 s[18:19], v151, v234
	v_or_b32_e32 v151, 16, v150
	s_nop 0
	v_cndmask_b32_e64 v39, v152, v39, s[18:19]
	v_cmp_le_i32_e64 s[18:19], v151, v234
	v_or_b32_e32 v151, 48, v150
	v_cmp_le_i32_e64 s[22:23], v151, v234
	v_or_b32_e32 v151, 17, v150
	s_nop 0
	v_cndmask_b32_e64 v40, v152, v40, s[22:23]
	v_cmp_le_i32_e64 s[22:23], v151, v234
	v_or_b32_e32 v151, 49, v150
	v_cmp_le_i32_e64 s[24:25], v151, v234
	v_or_b32_e32 v151, 18, v150
	s_nop 0
	v_cndmask_b32_e64 v41, v152, v41, s[24:25]
	v_cmp_le_i32_e64 s[24:25], v151, v234
	v_or_b32_e32 v151, 50, v150
	v_cmp_le_i32_e64 s[26:27], v151, v234
	v_or_b32_e32 v151, 19, v150
	s_nop 0
	v_cndmask_b32_e64 v42, v152, v42, s[26:27]
	v_cmp_le_i32_e64 s[26:27], v151, v234
	v_or_b32_e32 v151, 51, v150
	v_cmp_le_i32_e64 s[28:29], v151, v234
	v_or_b32_e32 v151, 24, v150
	s_nop 0
	v_cndmask_b32_e64 v43, v152, v43, s[28:29]
	v_cmp_le_i32_e64 s[28:29], v151, v234
	v_or_b32_e32 v151, 56, v150
	v_cmp_le_i32_e64 s[30:31], v151, v234
	v_or_b32_e32 v151, 25, v150
	s_nop 0
	v_cndmask_b32_e64 v44, v152, v44, s[30:31]
	v_cmp_le_i32_e64 s[30:31], v151, v234
	v_or_b32_e32 v151, 57, v150
	v_cmp_le_i32_e64 s[34:35], v151, v234
	v_or_b32_e32 v151, 26, v150
	s_nop 0
	v_cndmask_b32_e64 v45, v152, v45, s[34:35]
	v_cmp_le_i32_e64 s[34:35], v151, v234
	v_or_b32_e32 v151, 58, v150
	v_cmp_le_i32_e64 s[36:37], v151, v234
	v_or_b32_e32 v151, 27, v150
	v_or_b32_e32 v150, 59, v150
	v_cndmask_b32_e64 v46, v152, v46, s[36:37]
	v_cmp_le_i32_e64 s[36:37], v151, v234
	v_cmp_gt_i32_e64 s[40:41], v150, v234
	s_and_saveexec_b64 s[48:49], s[40:41]
	v_mov_b32_e32 v47, s65
	s_or_b64 exec, exec, s[48:49]
	v_accvgpr_write_b32 a79, v47
	v_accvgpr_write_b32 a78, v46
	v_accvgpr_write_b32 a77, v45
	v_accvgpr_write_b32 a76, v44
	v_accvgpr_write_b32 a75, v43
	v_accvgpr_write_b32 a74, v42
	v_accvgpr_write_b32 a73, v41
	v_accvgpr_write_b32 a72, v40
	v_accvgpr_write_b32 a71, v39
	v_accvgpr_write_b32 a70, v38
	v_accvgpr_write_b32 a69, v37
	v_accvgpr_write_b32 a68, v36
	v_accvgpr_write_b32 a67, v35
	v_accvgpr_write_b32 a66, v34
	v_accvgpr_write_b32 a65, v33
	v_accvgpr_write_b32 a64, v32
	v_mov_b32_e32 v32, 0xff800000
	v_cndmask_b32_e64 v1, v32, v1, s[0:1]
	v_cndmask_b32_e32 v0, v32, v0, vcc
	v_cndmask_b32_e64 v2, v32, v2, s[6:7]
	v_cndmask_b32_e64 v3, v32, v3, s[8:9]
	v_cndmask_b32_e64 v4, v32, v4, s[10:11]
	v_cndmask_b32_e64 v5, v32, v5, s[12:13]
	v_cndmask_b32_e64 v6, v32, v6, s[14:15]
	v_cndmask_b32_e64 v7, v32, v7, s[16:17]
	v_cndmask_b32_e64 v8, v32, v8, s[18:19]
	v_cndmask_b32_e64 v9, v32, v9, s[22:23]
	v_cndmask_b32_e64 v10, v32, v10, s[24:25]
	v_cndmask_b32_e64 v11, v32, v11, s[26:27]
	v_cndmask_b32_e64 v12, v32, v12, s[28:29]
	v_cndmask_b32_e64 v13, v32, v13, s[30:31]
	v_cndmask_b32_e64 v14, v32, v14, s[34:35]
	v_cndmask_b32_e64 v15, v32, v15, s[36:37]
	v_accvgpr_write_b32 a80, v0
	v_accvgpr_write_b32 a81, v1
	v_accvgpr_write_b32 a82, v2
	v_accvgpr_write_b32 a83, v3
	v_accvgpr_write_b32 a84, v4
	v_accvgpr_write_b32 a85, v5
	v_accvgpr_write_b32 a86, v6
	v_accvgpr_write_b32 a87, v7
	v_accvgpr_write_b32 a88, v8
	v_accvgpr_write_b32 a89, v9
	v_accvgpr_write_b32 a90, v10
	v_accvgpr_write_b32 a91, v11
	v_accvgpr_write_b32 a92, v12
	v_accvgpr_write_b32 a93, v13
	v_accvgpr_write_b32 a94, v14
	v_accvgpr_write_b32 a95, v15
	s_mov_b64 s[40:41], s[70:71]
; DI float ex2(float x) { return __builtin_amdgcn_exp2f(x); }
; template <int DQK>
; DI void attn_item_c(const u16* __restrict__ Qp, int ldq, const u16* __restrict__ Kp, const u16* __restrict__ Vtp, int ldv,
;                     int nkt, int q0, float c, u16* Yp, int ldy, char* smem, bool dry) {
;     ...
;     float mx = fmaxf(s0[0], s1[0]);
; #pragma unroll
;     for (int e = 1; e < 16; ++e) mx = fmaxf(fmaxf(mx, s0[e]), s1[e]);
;     mx = fmaxf(mx, __shfl_xor(mx, 32));
;     if (__builtin_amdgcn_ballot_w64((mx - m) * c > 8.f) != 0ull) {
;       const float mn = fmaxf(m, mx);
;       const float alpha = ex2((m - mn) * c);
;       m = mn;
;       l *= alpha;
; #pragma unroll
;       for (int dt = 0; dt < 4; ++dt)
; #pragma unroll
;         for (int e = 0; e < 16; ++e) o[dt][e] *= alpha;
;     }
;     ...
;     l += ps;
.LBB0_276:
	s_or_b64 exec, exec, s[46:47]
	v_add_f32_e32 v150, 0, v191
	v_add_f32_e32 v150, v192, v150
	v_add_f32_e32 v150, v193, v150
	v_add_f32_e32 v150, v198, v150
	v_add_f32_e32 v150, v199, v150
	v_add_f32_e32 v150, v200, v150
	v_add_f32_e32 v150, v201, v150
	v_add_f32_e32 v150, v202, v150
	v_add_f32_e32 v150, v203, v150
	v_add_f32_e32 v150, v204, v150
	v_add_f32_e32 v150, v205, v150
	v_add_f32_e32 v150, v206, v150
	v_add_f32_e32 v150, v207, v150
	v_add_f32_e32 v150, v208, v150
	v_add_f32_e32 v150, v209, v150
	v_add_f32_e32 v150, v248, v150
	v_add_f32_e32 v150, v213, v150
	v_add_f32_e32 v150, v214, v150
	v_add_f32_e32 v129, v129, v150
	v_add_f32_e32 v129, v215, v129
	v_add_f32_e32 v129, v227, v129
	v_add_f32_e32 v129, v228, v129
	v_add_f32_e32 v129, v229, v129
	v_accvgpr_read_b32 v0, a64
	v_accvgpr_read_b32 v32, a80
	v_add_f32_e32 v129, v230, v129
	v_add_f32_e32 v129, v149, v129
	v_max_f32_e32 v149, v0, v0
	v_max_f32_e32 v150, v32, v32
	v_accvgpr_read_b32 v1, a65
	v_accvgpr_read_b32 v33, a81
	v_max_f32_e32 v149, v150, v149
	v_accvgpr_read_b32 v2, a66
	v_accvgpr_read_b32 v34, a82
	v_max3_f32 v149, v149, v33, v1
	v_accvgpr_read_b32 v3, a67
	v_accvgpr_read_b32 v35, a83
	v_max3_f32 v149, v149, v34, v2
	v_accvgpr_read_b32 v4, a68
	v_accvgpr_read_b32 v36, a84
	v_max3_f32 v149, v149, v35, v3
	v_accvgpr_read_b32 v5, a69
	v_accvgpr_read_b32 v37, a85
	v_max3_f32 v149, v149, v36, v4
	v_accvgpr_read_b32 v6, a70
	v_accvgpr_read_b32 v38, a86
	v_max3_f32 v149, v149, v37, v5
	v_accvgpr_read_b32 v7, a71
	v_accvgpr_read_b32 v39, a87
	v_max3_f32 v149, v149, v38, v6
	v_accvgpr_read_b32 v8, a72
	v_accvgpr_read_b32 v40, a88
	v_max3_f32 v149, v149, v39, v7
	v_accvgpr_read_b32 v9, a73
	v_accvgpr_read_b32 v41, a89
	v_max3_f32 v149, v149, v40, v8
	v_accvgpr_read_b32 v10, a74
	v_accvgpr_read_b32 v42, a90
	v_max3_f32 v149, v149, v41, v9
	v_accvgpr_read_b32 v11, a75
	v_accvgpr_read_b32 v43, a91
	v_max3_f32 v149, v149, v42, v10
	v_accvgpr_read_b32 v12, a76
	v_accvgpr_read_b32 v44, a92
	v_max3_f32 v149, v149, v43, v11
	v_accvgpr_read_b32 v13, a77
	v_accvgpr_read_b32 v45, a93
	v_max3_f32 v149, v149, v44, v12
	v_accvgpr_read_b32 v14, a78
	v_accvgpr_read_b32 v46, a94
	v_max3_f32 v149, v149, v45, v13
	v_accvgpr_read_b32 v15, a79
	v_accvgpr_read_b32 v47, a95
	v_add_f32_e32 v129, v218, v129
	v_max3_f32 v149, v149, v46, v14
	v_add_f32_e32 v129, v231, v129
	v_max3_f32 v149, v149, v47, v15
	v_add_f32_e32 v129, v235, v129
	ds_bpermute_b32 v150, v232, v149
	v_add_f32_e32 v129, v244, v129
	v_add_f32_e32 v129, v146, v129
	v_add_f32_e32 v129, v147, v129
	v_add_f32_e32 v129, v148, v129
	v_add_f32_e32 v146, v190, v129
	s_waitcnt lgkmcnt(0)
	v_max_f32_e32 v129, v150, v150
	v_max_f32_e32 v129, v149, v129
	v_sub_f32_e32 v147, v129, v216
	v_mul_f32_e32 v147, 0x3dd53b94, v147
	v_cmp_lt_f32_e32 vcc, s33, v147
	s_cbranch_vccz .LBB0_278
	v_accvgpr_read_b32 v16, a48
	v_accvgpr_read_b32 v63, a47
	v_accvgpr_read_b32 v79, a31
	v_accvgpr_read_b32 v95, a15
	v_accvgpr_read_b32 v17, a49
	v_accvgpr_read_b32 v18, a50
	v_accvgpr_read_b32 v19, a51
	v_accvgpr_read_b32 v20, a52
	v_accvgpr_read_b32 v21, a53
	v_accvgpr_read_b32 v22, a54
	v_accvgpr_read_b32 v23, a55
	v_accvgpr_read_b32 v24, a56
	v_accvgpr_read_b32 v25, a57
	v_accvgpr_read_b32 v26, a58
	v_accvgpr_read_b32 v27, a59
	v_accvgpr_read_b32 v28, a60
	v_accvgpr_read_b32 v29, a61
	v_accvgpr_read_b32 v30, a62
	v_accvgpr_read_b32 v31, a63
	v_accvgpr_read_b32 v62, a46
	v_accvgpr_read_b32 v61, a45
	v_accvgpr_read_b32 v60, a44
	v_accvgpr_read_b32 v59, a43
	v_accvgpr_read_b32 v58, a42
	v_accvgpr_read_b32 v57, a41
	v_accvgpr_read_b32 v56, a40
	v_accvgpr_read_b32 v55, a39
	v_accvgpr_read_b32 v54, a38
	v_accvgpr_read_b32 v53, a37
	v_accvgpr_read_b32 v52, a36
	v_accvgpr_read_b32 v51, a35
	v_accvgpr_read_b32 v50, a34
	v_accvgpr_read_b32 v49, a33
	v_accvgpr_read_b32 v48, a32
	v_accvgpr_read_b32 v78, a30
	v_accvgpr_read_b32 v77, a29
	v_accvgpr_read_b32 v76, a28
	v_accvgpr_read_b32 v75, a27
	v_accvgpr_read_b32 v74, a26
	v_accvgpr_read_b32 v73, a25
	v_accvgpr_read_b32 v72, a24
	v_accvgpr_read_b32 v71, a23
	v_accvgpr_read_b32 v70, a22
	v_accvgpr_read_b32 v69, a21
	v_accvgpr_read_b32 v68, a20
	v_accvgpr_read_b32 v67, a19
	v_accvgpr_read_b32 v66, a18
	v_accvgpr_read_b32 v65, a17
	v_accvgpr_read_b32 v64, a16
	v_accvgpr_read_b32 v94, a14
	v_accvgpr_read_b32 v93, a13
	v_accvgpr_read_b32 v92, a12
	v_accvgpr_read_b32 v91, a11
	v_accvgpr_read_b32 v90, a10
	v_accvgpr_read_b32 v89, a9
	v_accvgpr_read_b32 v88, a8
	v_accvgpr_read_b32 v87, a7
	v_accvgpr_read_b32 v86, a6
	v_accvgpr_read_b32 v85, a5
	v_accvgpr_read_b32 v84, a4
	v_accvgpr_read_b32 v83, a3
	v_accvgpr_read_b32 v82, a2
	v_accvgpr_read_b32 v81, a1
	v_accvgpr_read_b32 v80, a0
	v_max_f32_e32 v129, v129, v129
	v_max_f32_e32 v147, v216, v216
	v_max_f32_e32 v147, v147, v129
	v_sub_f32_e32 v129, v216, v147
	v_mul_f32_e32 v129, 0x3dd53b94, v129
	v_exp_f32_e32 v216, v129
	s_nop 0
	v_pk_mul_f32 v[80:81], v[80:81], v[216:217] op_sel_hi:[1,0]
	v_pk_mul_f32 v[64:65], v[64:65], v[216:217] op_sel_hi:[1,0]
	v_pk_mul_f32 v[48:49], v[48:49], v[216:217] op_sel_hi:[1,0]
	v_pk_mul_f32 v[30:31], v[30:31], v[216:217] op_sel_hi:[1,0]
	v_pk_mul_f32 v[94:95], v[94:95], v[216:217] op_sel_hi:[1,0]
	v_pk_mul_f32 v[92:93], v[92:93], v[216:217] op_sel_hi:[1,0]
	v_pk_mul_f32 v[90:91], v[90:91], v[216:217] op_sel_hi:[1,0]
	v_pk_mul_f32 v[88:89], v[88:89], v[216:217] op_sel_hi:[1,0]
	v_pk_mul_f32 v[86:87], v[86:87], v[216:217] op_sel_hi:[1,0]
	v_pk_mul_f32 v[84:85], v[84:85], v[216:217] op_sel_hi:[1,0]
	v_pk_mul_f32 v[82:83], v[82:83], v[216:217] op_sel_hi:[1,0]
	v_pk_mul_f32 v[78:79], v[78:79], v[216:217] op_sel_hi:[1,0]
	v_accvgpr_write_b32 a0, v80
; #define MFMA32(a, b, c) __builtin_amdgcn_mfma_f32_32x32x16_bf16((a), (b), (c), 0, 0, 0)
; DI float ex2(float x) { return __builtin_amdgcn_exp2f(x); }
; template <int DQK>
; DI void attn_item_c(const u16* __restrict__ Qp, int ldq, const u16* __restrict__ Kp, const u16* __restrict__ Vtp, int ldv,
;                     int nkt, int q0, float c, u16* Yp, int ldy, char* smem, bool dry) {
;     ...
; #pragma unroll
;       for (int dt = 0; dt < 4; ++dt)
; #pragma unroll
;         for (int e = 0; e < 16; ++e) o[dt][e] *= alpha;
;     }
;     const float mc = m * c;
; #pragma unroll
;     for (int e = 0; e < 16; ++e) { n0[e] = 0.f; n1[e] = 0.f; }
;     const u16* k0 = Ks + r * KLD + 8 * h;
;     bf16x8 ka[3][2];
;     ka[0][0] = *(const bf16x8*)(k0); ka[0][1] = *(const bf16x8*)(k0 + 32 * KLD);
;     ka[1][0] = *(const bf16x8*)(k0 + 16); ka[1][1] = *(const bf16x8*)(k0 + 32 * KLD + 16);
;     bf16x8 pf[4];
;     u32x4 pk[4];
;     float ps = 0.f;
; #pragma unroll
;     for (int ks = 0; ks < NKS; ++ks) {
;       if (ks + 2 < NKS) {
;         ka[(ks + 2) % 3][0] = *(const bf16x8*)(k0 + 16 * (ks + 2));
;         ka[(ks + 2) % 3][1] = *(const bf16x8*)(k0 + 32 * KLD + 16 * (ks + 2));
;       }
;       __builtin_amdgcn_sched_barrier(0);
;       n0 = MFMA32(ka[ks % 3][0], qf[ks], n0); n1 = MFMA32(ka[ks % 3][1], qf[ks], n1);
;       {
;         constexpr int dummy0 = 0; (void)dummy0;
;         const int e_lo = (32 * ks) / NKS, e_hi = (32 * (ks + 1)) / NKS;
; #pragma unroll
;         for (int q = 0; q < 3; ++q) {
;           const int e = e_lo + q;
;           if (e < e_hi) {
;             if (e < 16) { s0[e & 15] = ex2(fmaf(s0[e & 15], c, -mc)); ps += s0[e & 15]; }
;             else        { s1[e & 15] = ex2(fmaf(s1[e & 15], c, -mc)); ps += s1[e & 15]; }
;           }
;         }
;       }
	v_pk_mul_f32 v[76:77], v[76:77], v[216:217] op_sel_hi:[1,0]
	v_pk_mul_f32 v[74:75], v[74:75], v[216:217] op_sel_hi:[1,0]
	v_pk_mul_f32 v[72:73], v[72:73], v[216:217] op_sel_hi:[1,0]
	v_pk_mul_f32 v[70:71], v[70:71], v[216:217] op_sel_hi:[1,0]
	v_pk_mul_f32 v[68:69], v[68:69], v[216:217] op_sel_hi:[1,0]
	v_pk_mul_f32 v[66:67], v[66:67], v[216:217] op_sel_hi:[1,0]
	v_pk_mul_f32 v[62:63], v[62:63], v[216:217] op_sel_hi:[1,0]
	v_accvgpr_write_b32 a16, v64
	v_pk_mul_f32 v[60:61], v[60:61], v[216:217] op_sel_hi:[1,0]
	v_pk_mul_f32 v[58:59], v[58:59], v[216:217] op_sel_hi:[1,0]
	v_pk_mul_f32 v[56:57], v[56:57], v[216:217] op_sel_hi:[1,0]
	v_pk_mul_f32 v[54:55], v[54:55], v[216:217] op_sel_hi:[1,0]
	v_pk_mul_f32 v[52:53], v[52:53], v[216:217] op_sel_hi:[1,0]
	v_pk_mul_f32 v[50:51], v[50:51], v[216:217] op_sel_hi:[1,0]
	v_pk_mul_f32 v[28:29], v[28:29], v[216:217] op_sel_hi:[1,0]
	v_accvgpr_write_b32 a32, v48
	v_pk_mul_f32 v[26:27], v[26:27], v[216:217] op_sel_hi:[1,0]
	v_pk_mul_f32 v[24:25], v[24:25], v[216:217] op_sel_hi:[1,0]
	v_pk_mul_f32 v[22:23], v[22:23], v[216:217] op_sel_hi:[1,0]
	v_pk_mul_f32 v[20:21], v[20:21], v[216:217] op_sel_hi:[1,0]
	v_pk_mul_f32 v[18:19], v[18:19], v[216:217] op_sel_hi:[1,0]
	v_pk_mul_f32 v[16:17], v[16:17], v[216:217] op_sel_hi:[1,0]
	v_pk_mul_f32 v[248:249], v[146:147], v[216:217]
	v_accvgpr_write_b32 a63, v31
	v_accvgpr_write_b32 a1, v81
	v_accvgpr_write_b32 a2, v82
	v_accvgpr_write_b32 a3, v83
	v_accvgpr_write_b32 a4, v84
	v_accvgpr_write_b32 a5, v85
	v_accvgpr_write_b32 a6, v86
	v_accvgpr_write_b32 a7, v87
	v_accvgpr_write_b32 a8, v88
	v_accvgpr_write_b32 a9, v89
	v_accvgpr_write_b32 a10, v90
	v_accvgpr_write_b32 a11, v91
	v_accvgpr_write_b32 a12, v92
	v_accvgpr_write_b32 a13, v93
	v_accvgpr_write_b32 a14, v94
	v_accvgpr_write_b32 a15, v95
	v_accvgpr_write_b32 a17, v65
	v_accvgpr_write_b32 a18, v66
	v_accvgpr_write_b32 a19, v67
	v_accvgpr_write_b32 a20, v68
	v_accvgpr_write_b32 a21, v69
	v_accvgpr_write_b32 a22, v70
	v_accvgpr_write_b32 a23, v71
	v_accvgpr_write_b32 a24, v72
	v_accvgpr_write_b32 a25, v73
	v_accvgpr_write_b32 a26, v74
	v_accvgpr_write_b32 a27, v75
	v_accvgpr_write_b32 a28, v76
	v_accvgpr_write_b32 a29, v77
	v_accvgpr_write_b32 a30, v78
	v_accvgpr_write_b32 a31, v79
	v_accvgpr_write_b32 a33, v49
	v_accvgpr_write_b32 a34, v50
	v_accvgpr_write_b32 a35, v51
	v_accvgpr_write_b32 a36, v52
	v_accvgpr_write_b32 a37, v53
	v_accvgpr_write_b32 a38, v54
	v_accvgpr_write_b32 a39, v55
	v_accvgpr_write_b32 a40, v56
	v_accvgpr_write_b32 a41, v57
	v_accvgpr_write_b32 a42, v58
	v_accvgpr_write_b32 a43, v59
	v_accvgpr_write_b32 a44, v60
	v_accvgpr_write_b32 a45, v61
	v_accvgpr_write_b32 a46, v62
	v_accvgpr_write_b32 a47, v63
	v_accvgpr_write_b32 a62, v30
	v_accvgpr_write_b32 a61, v29
	v_accvgpr_write_b32 a60, v28
	v_accvgpr_write_b32 a59, v27
	v_accvgpr_write_b32 a58, v26
	v_accvgpr_write_b32 a57, v25
	v_accvgpr_write_b32 a56, v24
	v_accvgpr_write_b32 a55, v23
	v_accvgpr_write_b32 a54, v22
	v_accvgpr_write_b32 a53, v21
	v_accvgpr_write_b32 a52, v20
	v_accvgpr_write_b32 a51, v19
	v_accvgpr_write_b32 a50, v18
	v_accvgpr_write_b32 a49, v17
	v_accvgpr_write_b32 a48, v16
	v_mov_b32_e32 v216, v147
	v_mov_b32_e32 v146, v248
.LBB0_278:
	ds_read_b128 v[18:21], v219 offset:44032
	ds_read_b128 v[22:25], v219 offset:44064
	ds_read_b128 v[26:29], v219 offset:56832
	ds_read_b128 v[48:51], v219 offset:44096
	ds_read_b128 v[52:55], v219 offset:56864
	ds_read_b128 v[56:59], v219 offset:56896
	v_accvgpr_read_b32 v17, a238
	v_mov_b32_e32 v16, v249
	v_cmp_le_i32_e32 vcc, s20, v17
	s_waitcnt lgkmcnt(5)
	v_mfma_f32_32x32x16_bf16 a[80:95], v[18:21], v[96:99], 0
	v_fmamk_f32 v17, v32, 0x3dd53b94, v16
	v_exp_f32_e32 v147, v17
	v_fmamk_f32 v17, v33, 0x3dd53b94, v16
	v_exp_f32_e32 v148, v17
	s_waitcnt lgkmcnt(3)
	v_mfma_f32_32x32x16_bf16 a[64:79], v[26:29], v[96:99], 0
	ds_read_b128 v[18:21], v219 offset:44128
	ds_read_b128 v[26:29], v219 offset:56928
	v_mfma_f32_32x32x16_bf16 a[80:95], v[22:25], v[100:103], a[80:95]
	v_fmamk_f32 v17, v34, 0x3dd53b94, v16
	v_exp_f32_e32 v149, v17
	v_fmamk_f32 v17, v35, 0x3dd53b94, v16
	v_exp_f32_e32 v150, v17
	v_fmamk_f32 v17, v36, 0x3dd53b94, v16
	v_exp_f32_e32 v151, v17
	s_waitcnt lgkmcnt(3)
	v_mfma_f32_32x32x16_bf16 a[64:79], v[52:55], v[100:103], a[64:79]
	ds_read_b128 v[22:25], v219 offset:44160
	ds_read_b128 v[30:33], v219 offset:56960
	v_mfma_f32_32x32x16_bf16 a[80:95], v[48:51], v[104:107], a[80:95]
	v_fmamk_f32 v17, v37, 0x3dd53b94, v16
	v_exp_f32_e32 v152, v17
	v_fmamk_f32 v17, v38, 0x3dd53b94, v16
	v_exp_f32_e32 v153, v17
	v_fmamk_f32 v17, v39, 0x3dd53b94, v16
	v_exp_f32_e32 v154, v17
	s_waitcnt lgkmcnt(4)
	v_mfma_f32_32x32x16_bf16 a[64:79], v[56:59], v[104:107], a[64:79]
	ds_read_b128 v[34:37], v219 offset:44192
	ds_read_b128 v[48:51], v219 offset:56992
	s_waitcnt lgkmcnt(5)
	v_mfma_f32_32x32x16_bf16 a[80:95], v[18:21], v[108:111], a[80:95]
	v_fmamk_f32 v17, v40, 0x3dd53b94, v16
	v_exp_f32_e32 v155, v17
	v_fmamk_f32 v17, v41, 0x3dd53b94, v16
	v_exp_f32_e32 v156, v17
	s_waitcnt lgkmcnt(4)
	v_mfma_f32_32x32x16_bf16 a[64:79], v[26:29], v[108:111], a[64:79]
	ds_read_b128 v[18:21], v219 offset:44224
	ds_read_b128 v[26:29], v219 offset:57024
	s_waitcnt lgkmcnt(5)
	v_mfma_f32_32x32x16_bf16 a[80:95], v[22:25], v[112:115], a[80:95]
	v_fmamk_f32 v17, v42, 0x3dd53b94, v16
	v_exp_f32_e32 v157, v17
	v_fmamk_f32 v17, v43, 0x3dd53b94, v16
	v_exp_f32_e32 v158, v17
	v_fmamk_f32 v17, v44, 0x3dd53b94, v16
	v_exp_f32_e32 v159, v17
	s_waitcnt lgkmcnt(4)
	v_mfma_f32_32x32x16_bf16 a[64:79], v[30:33], v[112:115], a[64:79]
	ds_read_b128 v[22:25], v219 offset:44256
	ds_read_b128 v[30:33], v219 offset:57056
	s_waitcnt lgkmcnt(5)
; #define MFMA32(a, b, c) __builtin_amdgcn_mfma_f32_32x32x16_bf16((a), (b), (c), 0, 0, 0)
; DI unsigned pack2(float a, float b) { f2_t v = {a, b}; bf2_t r = __builtin_convertvector(v, bf2_t); return __builtin_bit_cast(unsigned, r); }
; DI float ex2(float x) { return __builtin_amdgcn_exp2f(x); }
; template <int DQK>
; DI void attn_item_c(const u16* __restrict__ Qp, int ldq, const u16* __restrict__ Kp, const u16* __restrict__ Vtp, int ldv,
;                     int nkt, int q0, float c, u16* Yp, int ldy, char* smem, bool dry) {
;     ...
; #pragma unroll
;     for (int ks = 0; ks < NKS; ++ks) {
;       if (ks + 2 < NKS) {
;         ka[(ks + 2) % 3][0] = *(const bf16x8*)(k0 + 16 * (ks + 2));
;         ka[(ks + 2) % 3][1] = *(const bf16x8*)(k0 + 32 * KLD + 16 * (ks + 2));
;       }
;       __builtin_amdgcn_sched_barrier(0);
;       n0 = MFMA32(ka[ks % 3][0], qf[ks], n0); n1 = MFMA32(ka[ks % 3][1], qf[ks], n1);
;       {
;         constexpr int dummy0 = 0; (void)dummy0;
;         const int e_lo = (32 * ks) / NKS, e_hi = (32 * (ks + 1)) / NKS;
; #pragma unroll
;         for (int q = 0; q < 3; ++q) {
;           const int e = e_lo + q;
;           if (e < e_hi) {
;             if (e < 16) { s0[e & 15] = ex2(fmaf(s0[e & 15], c, -mc)); ps += s0[e & 15]; }
;             else        { s1[e & 15] = ex2(fmaf(s1[e & 15], c, -mc)); ps += s1[e & 15]; }
;           }
;         }
;       }
;       if (ks == 3)  { pk[0].x = pack2(s0[0], s0[1]);  pk[0].y = pack2(s0[2], s0[3]);   pk[0].z = pack2(s0[4], s0[5]);   pk[0].w = pack2(s0[6], s0[7]); }
;       if (ks == 6)  { pk[1].x = pack2(s0[8], s0[9]);  pk[1].y = pack2(s0[10], s0[11]); pk[1].z = pack2(s0[12], s0[13]); pk[1].w = pack2(s0[14], s0[15]); }
;       if (ks == 9)  { pk[2].x = pack2(s1[0], s1[1]);  pk[2].y = pack2(s1[2], s1[3]);   pk[2].z = pack2(s1[4], s1[5]);   pk[2].w = pack2(s1[6], s1[7]); }
;       if (ks == NKS - 1) { pk[3].x = pack2(s1[8], s1[9]);  pk[3].y = pack2(s1[10], s1[11]); pk[3].z = pack2(s1[12], s1[13]); pk[3].w = pack2(s1[14], s1[15]); }
;       __builtin_amdgcn_sched_barrier(0);
;     }
;     l += ps;
; #pragma unroll
;     for (int i = 0; i < 4; ++i) pf[i] = __builtin_bit_cast(bf16x8, pk[i]);
;     if (active) {
	v_mfma_f32_32x32x16_bf16 a[80:95], v[34:37], v[116:119], a[80:95]
	v_fmamk_f32 v17, v45, 0x3dd53b94, v16
	v_exp_f32_e32 v160, v17
	v_fmamk_f32 v17, v46, 0x3dd53b94, v16
	v_exp_f32_e32 v161, v17
	v_fmamk_f32 v17, v47, 0x3dd53b94, v16
	v_exp_f32_e32 v248, v17
	s_waitcnt lgkmcnt(4)
	v_mfma_f32_32x32x16_bf16 a[64:79], v[48:51], v[116:119], a[64:79]
	ds_read_b128 v[34:37], v219 offset:44288
	ds_read_b128 v[38:41], v219 offset:57088
	s_waitcnt lgkmcnt(5)
	v_mfma_f32_32x32x16_bf16 a[80:95], v[18:21], v[120:123], a[80:95]
	v_fmamk_f32 v0, v0, 0x3dd53b94, v16
	v_exp_f32_e32 v213, v0
	v_fmamk_f32 v0, v1, 0x3dd53b94, v16
	v_exp_f32_e32 v214, v0
	s_waitcnt lgkmcnt(4)
	v_mfma_f32_32x32x16_bf16 a[64:79], v[26:29], v[120:123], a[64:79]
	ds_read_b128 v[18:21], v219 offset:44320
	ds_read_b128 v[26:29], v219 offset:57120
	s_waitcnt lgkmcnt(5)
	v_mfma_f32_32x32x16_bf16 a[80:95], v[22:25], v[124:127], a[80:95]
	v_fmamk_f32 v0, v2, 0x3dd53b94, v16
	v_exp_f32_e32 v129, v0
	v_fmamk_f32 v0, v3, 0x3dd53b94, v16
	v_exp_f32_e32 v215, v0
	v_fmamk_f32 v0, v4, 0x3dd53b94, v16
	v_exp_f32_e32 v227, v0
	s_waitcnt lgkmcnt(4)
	v_mfma_f32_32x32x16_bf16 a[64:79], v[30:33], v[124:127], a[64:79]
	ds_read_b128 v[0:3], v219 offset:44352
	ds_read_b128 v[22:25], v219 offset:57152
	s_waitcnt lgkmcnt(5)
	v_mfma_f32_32x32x16_bf16 a[80:95], v[34:37], v[130:133], a[80:95]
	v_fmamk_f32 v4, v5, 0x3dd53b94, v16
	v_exp_f32_e32 v228, v4
	v_fmamk_f32 v4, v6, 0x3dd53b94, v16
	v_exp_f32_e32 v229, v4
	v_fmamk_f32 v4, v7, 0x3dd53b94, v16
	v_exp_f32_e32 v230, v4
	s_waitcnt lgkmcnt(4)
	v_mfma_f32_32x32x16_bf16 a[64:79], v[38:41], v[130:133], a[64:79]
	ds_read_b128 v[4:7], v219 offset:44384
	ds_read_b128 v[30:33], v219 offset:57184
	s_waitcnt lgkmcnt(5)
	v_mfma_f32_32x32x16_bf16 a[80:95], v[18:21], v[134:137], a[80:95]
	v_fmamk_f32 v8, v8, 0x3dd53b94, v16
	v_exp_f32_e32 v244, v8
	v_fmamk_f32 v8, v9, 0x3dd53b94, v16
	v_exp_f32_e32 v245, v8
	s_waitcnt lgkmcnt(4)
	v_mfma_f32_32x32x16_bf16 a[64:79], v[26:29], v[134:137], a[64:79]
	s_waitcnt lgkmcnt(3)
	v_mfma_f32_32x32x16_bf16 a[80:95], v[0:3], v[138:141], a[80:95]
	v_fmamk_f32 v0, v10, 0x3dd53b94, v16
	v_exp_f32_e32 v246, v0
	v_fmamk_f32 v0, v11, 0x3dd53b94, v16
	v_exp_f32_e32 v247, v0
	v_fmamk_f32 v0, v12, 0x3dd53b94, v16
	v_exp_f32_e32 v162, v0
	s_waitcnt lgkmcnt(2)
	v_mfma_f32_32x32x16_bf16 a[64:79], v[22:25], v[138:141], a[64:79]
	s_waitcnt lgkmcnt(1)
	v_mfma_f32_32x32x16_bf16 a[80:95], v[4:7], v[142:145], a[80:95]
	v_fmamk_f32 v0, v13, 0x3dd53b94, v16
	v_exp_f32_e32 v231, v0
	v_fmamk_f32 v0, v14, 0x3dd53b94, v16
	v_fmac_f32_e32 v16, 0x3dd53b94, v15
	v_exp_f32_e32 v235, v0
	v_exp_f32_e32 v218, v16
	s_waitcnt lgkmcnt(0)
	v_mfma_f32_32x32x16_bf16 a[64:79], v[30:33], v[142:145], a[64:79]
	s_and_saveexec_b64 s[0:1], vcc
	s_xor_b64 s[0:1], exec, s[0:1]
	s_cbranch_execz .LBB0_280
; #define MFMA32(a, b, c) __builtin_amdgcn_mfma_f32_32x32x16_bf16((a), (b), (c), 0, 0, 0)
; template <int DQK>
; DI void attn_item_c(const u16* __restrict__ Qp, int ldq, const u16* __restrict__ Kp, const u16* __restrict__ Vtp, int ldv,
;                     int nkt, int q0, float c, u16* Yp, int ldy, char* smem, bool dry) {
;     ...
;   auto gloadK = [&](u32x4* ks_, int j) {
;     const u16* kg = Kp + (size_t)(j + 1) * 64 * DQK;
; #pragma unroll
;     for (int i = 0; i < NKC; ++i) ks_[i] = *(const u32x4*)(kg + (size_t)(tid + 256 * i) * 8);
;   };
;   auto gloadV = [&](u32x4* vs_, int j) {
; #pragma unroll
;     for (int i = 0; i < 4; ++i) vs_[i] = *(const u32x4*)(Vtp + (size_t)j * 8192 + (size_t)(tid + 256 * i) * 8);
;   };
;   auto lstoreK = [&](const u32x4* ks_, u16* Lb) {
; #pragma unroll
;     for (int i = 0; i < NKC; ++i) *(u32x4*)(Lb + kso[i]) = ks_[i];
;   };
;   auto lstoreV = [&](const u32x4* vs_, u16* Lb) {
; #pragma unroll
;     for (int i = 0; i < 4; ++i) {
;       u16* dst = Lb + vso + (32 * i) * 72;
;       u32x2 lo = {vs_[i].x, vs_[i].y}, hi = {vs_[i].z, vs_[i].w};
;       *(u32x2*)dst = lo; *(u32x2*)(dst + 8) = hi;
;     }
;   };
;     ...
;     for (int i = 0; i < 4; ++i) pf[i] = __builtin_bit_cast(bf16x8, pk[i]);
;     if (active) {
;       const u16* v0 = Vs + r * 72 + 8 * h;
;       bf16x8 va[2][4];
; #pragma unroll
;       for (int dt = 0; dt < 4; ++dt) va[0][dt] = *(const bf16x8*)(v0 + (32 * dt) * 72);
; #pragma unroll
;       for (int kk = 0; kk < 4; ++kk) {
;         if (kk < 3) {
; #pragma unroll
;           for (int dt = 0; dt < 4; ++dt) va[(kk + 1) & 1][dt] = *(const bf16x8*)(v0 + (32 * dt) * 72 + 16 * (kk + 1));
;         }
;         __builtin_amdgcn_sched_barrier(0);
; #pragma unroll
;         for (int dt = 0; dt < 4; ++dt) o[dt] = MFMA32(va[kk & 1][dt], pf[kk], o[dt]);
;         if (kk == 0) lstoreK(wk, Ln);
;         if (kk == 1) lstoreV(wv, Ln);
;         if (kk == 2) gloadK(wk, kt + 3);
;         if (kk == 3) gloadV(wv, kt + 3);
;         __builtin_amdgcn_sched_barrier(0);
;       }
	ds_read_b128 v[16:19], v250
	ds_read_b128 v[20:23], v250 offset:32
	ds_read_b128 v[24:27], v250 offset:4608
	ds_read_b128 v[28:31], v250 offset:4640
	ds_read_b128 v[32:35], v250 offset:9216
	ds_read_b128 v[36:39], v250 offset:9248
	ds_read_b128 v[40:43], v250 offset:13824
	ds_read_b128 v[44:47], v250 offset:13856
	s_add_i32 s20, s44, 4
	s_add_i32 s8, s44, 5
	v_cvt_pk_bf16_f32 v0, v244, v245
	v_cvt_pk_bf16_f32 v1, v246, v247
	v_cvt_pk_bf16_f32 v2, v162, v231
	v_cvt_pk_bf16_f32 v3, v235, v218
	v_cvt_pk_bf16_f32 v4, v213, v214
	v_cvt_pk_bf16_f32 v5, v129, v215
	v_cvt_pk_bf16_f32 v6, v227, v228
	v_cvt_pk_bf16_f32 v7, v229, v230
	v_cvt_pk_bf16_f32 v8, v155, v156
	v_cvt_pk_bf16_f32 v9, v157, v158
	v_cvt_pk_bf16_f32 v10, v159, v160
	v_cvt_pk_bf16_f32 v11, v161, v248
	v_cvt_pk_bf16_f32 v12, v147, v148
	v_cvt_pk_bf16_f32 v13, v149, v150
	v_cvt_pk_bf16_f32 v14, v151, v152
	v_cvt_pk_bf16_f32 v15, v153, v154
	s_lshl_b64 s[6:7], s[20:21], 14
	s_mul_hi_u32 s9, s8, 0x6000
	s_mulk_i32 s8, 0x6000
	s_waitcnt lgkmcnt(7)
	v_mfma_f32_32x32x16_bf16 a[0:15], v[16:19], v[12:15], a[0:15]
	s_waitcnt vmcnt(10)
	ds_write_b128 v221, a[120:123]
	ds_write_b128 v222, a[124:127]
	ds_write_b128 v223, a[132:135]
	ds_write_b128 v224, a[136:139]
	ds_write_b128 v225, a[140:143]
	ds_write_b128 v226, a[144:147]
	s_waitcnt lgkmcnt(11)
	v_mfma_f32_32x32x16_bf16 a[16:31], v[24:27], v[12:15], a[16:31]
	s_waitcnt lgkmcnt(9)
	v_mfma_f32_32x32x16_bf16 a[32:47], v[32:35], v[12:15], a[32:47]
	s_waitcnt lgkmcnt(7)
	v_mfma_f32_32x32x16_bf16 a[48:63], v[40:43], v[12:15], a[48:63]
	ds_read_b128 v[12:15], v250 offset:64
	ds_read_b128 v[16:19], v250 offset:4672
	ds_read_b128 v[24:27], v250 offset:9280
	ds_read_b128 v[32:35], v250 offset:13888
	v_mfma_f32_32x32x16_bf16 a[0:15], v[20:23], v[8:11], a[0:15]
	v_accvgpr_read_b32 v20, a229
	v_mfma_f32_32x32x16_bf16 a[16:31], v[28:31], v[8:11], a[16:31]
	v_accvgpr_read_b32 v28, a244
	v_accvgpr_read_b32 v29, a245
	v_accvgpr_read_b32 v30, a246
	v_accvgpr_read_b32 v31, a247
	ds_write2_b64 v20, v[28:29], v[30:31] offset0:128 offset1:130
	v_accvgpr_read_b32 v20, a234
	ds_write2_b64 v20, v[170:171], v[172:173] offset0:192 offset1:194
	v_mfma_f32_32x32x16_bf16 a[32:47], v[36:39], v[8:11], a[32:47]
	v_accvgpr_read_b32 v20, a235
	ds_write2_b64 v20, v[166:167], v[168:169] offset1:2
	v_accvgpr_read_b32 v20, a236
	ds_write2_b64 v20, v[174:175], v[176:177] offset0:64 offset1:66
	s_waitcnt lgkmcnt(14)
	v_mfma_f32_32x32x16_bf16 a[48:63], v[44:47], v[8:11], a[48:63]
	ds_read_b128 v[8:11], v250 offset:96
	ds_read_b128 v[20:23], v250 offset:4704
	ds_read_b128 v[28:31], v250 offset:9312
	ds_read_b128 v[36:39], v250 offset:13920
	s_add_u32 s8, s94, s8
	s_addc_u32 s9, s95, s9
	s_waitcnt lgkmcnt(11)
	v_mfma_f32_32x32x16_bf16 a[0:15], v[12:15], v[4:7], a[0:15]
	v_lshl_add_u64 v[12:13], s[8:9], 0, v[236:237]
	v_lshl_add_u64 v[14:15], s[8:9], 0, v[238:239]
	global_load_dwordx4 a[156:159], v[12:13], off
	global_load_dwordx4 a[164:167], v[14:15], off
	v_lshl_add_u64 v[12:13], s[8:9], 0, v[240:241]
	v_lshl_add_u64 v[14:15], s[8:9], 0, v[242:243]
	global_load_dwordx4 a[172:175], v[12:13], off
	global_load_dwordx4 a[180:183], v[14:15], off
	v_accvgpr_read_b32 v12, a230
	v_accvgpr_read_b32 v13, a231
	v_accvgpr_read_b32 v14, a232
	v_lshl_add_u64 v[12:13], s[8:9], 0, v[12:13]
	v_accvgpr_read_b32 v15, a233
	v_lshl_add_u64 v[14:15], s[8:9], 0, v[14:15]
	global_load_dwordx4 a[188:191], v[12:13], off
	global_load_dwordx4 a[192:195], v[14:15], off
	s_waitcnt lgkmcnt(10)
	v_mfma_f32_32x32x16_bf16 a[16:31], v[16:19], v[4:7], a[16:31]
	s_waitcnt lgkmcnt(9)
	v_mfma_f32_32x32x16_bf16 a[32:47], v[24:27], v[4:7], a[32:47]
	s_waitcnt lgkmcnt(8)
	v_mfma_f32_32x32x16_bf16 a[48:63], v[32:35], v[4:7], a[48:63]
	s_add_u32 s6, s60, s6
	s_addc_u32 s7, s61, s7
	s_waitcnt lgkmcnt(3)
	v_mfma_f32_32x32x16_bf16 a[0:15], v[8:11], v[0:3], a[0:15]
	s_waitcnt lgkmcnt(2)
	v_mfma_f32_32x32x16_bf16 a[16:31], v[20:23], v[0:3], a[16:31]
	s_waitcnt lgkmcnt(1)
	v_mfma_f32_32x32x16_bf16 a[32:47], v[28:31], v[0:3], a[32:47]
	s_waitcnt lgkmcnt(0)
	v_mfma_f32_32x32x16_bf16 a[48:63], v[36:39], v[0:3], a[48:63]
	v_lshl_add_u64 v[0:1], s[6:7], 0, v[236:237]
	global_load_dwordx4 v[190:193], v[0:1], off
	v_lshl_add_u64 v[0:1], s[6:7], 0, v[238:239]
	global_load_dwordx4 v[202:205], v[0:1], off
	v_lshl_add_u64 v[0:1], s[6:7], 0, v[240:241]
	global_load_dwordx4 v[198:201], v[0:1], off
	v_lshl_add_u64 v[0:1], s[6:7], 0, v[242:243]
	global_load_dwordx4 v[206:209], v[0:1], off

; DI int crow(int reg, int h) { return (reg & 3) + 8 * (reg >> 2) + 4 * h; }
; template <int DQK>
; DI void attn_item_c(const u16* __restrict__ Qp, int ldq, const u16* __restrict__ Kp, const u16* __restrict__ Vtp, int ldv,
;                     int nkt, int q0, float c, u16* Yp, int ldy, char* smem, bool dry) {
;     ...
;   auto body = [&](int kt, u32x4* wk, u32x4* wv, f32x16& s0, f32x16& s1, f32x16& n0, f32x16& n1) {
;     const u16* Ks = L0 + (kt & 1) * BUFE;
;     const u16* Vs = Ks + 64 * KLD;
;     u16* Ln = L0 + ((kt + 1) & 1) * BUFE;
;     const bool active = !(kt * 64 > qmin + 31);
;     if (kt * 64 + 63 > qmin) {
; #pragma unroll
;       for (int e = 0; e < 16; ++e) {
;         int key = kt * 64 + crow(e, h);
;         if (key > qi) s0[e] = -INFINITY;
;         if (key + 32 > qi) s1[e] = -INFINITY;
;       }
;     }
;     ...
;     __syncthreads();
.LBB0_282:
	s_or_b64 exec, exec, s[0:1]
	s_nop 0
	s_or_b32 s0, s45, 0xbf
	s_or_b32 s20, s45, 0x80
	v_cmp_gt_i32_e32 vcc, s0, v233
	s_waitcnt lgkmcnt(0)
	s_barrier
	s_and_saveexec_b64 s[46:47], vcc
	s_cbranch_execz .LBB0_286
	v_accvgpr_read_b32 v0, a80
	v_accvgpr_read_b32 v32, a64
	v_accvgpr_read_b32 v1, a81
	v_accvgpr_read_b32 v2, a82
	v_accvgpr_read_b32 v3, a83
	v_accvgpr_read_b32 v4, a84
	v_accvgpr_read_b32 v5, a85
	v_accvgpr_read_b32 v6, a86
	v_accvgpr_read_b32 v7, a87
	v_accvgpr_read_b32 v8, a88
	v_accvgpr_read_b32 v9, a89
	v_accvgpr_read_b32 v10, a90
	v_accvgpr_read_b32 v11, a91
	v_accvgpr_read_b32 v12, a92
	v_accvgpr_read_b32 v13, a93
	v_accvgpr_read_b32 v14, a94
	v_accvgpr_read_b32 v15, a95
	v_accvgpr_read_b32 v33, a65
	v_accvgpr_read_b32 v34, a66
	v_accvgpr_read_b32 v35, a67
	v_accvgpr_read_b32 v36, a68
	v_accvgpr_read_b32 v37, a69
	v_accvgpr_read_b32 v38, a70
	v_accvgpr_read_b32 v39, a71
	v_accvgpr_read_b32 v40, a72
	v_accvgpr_read_b32 v41, a73
	v_accvgpr_read_b32 v42, a74
	v_accvgpr_read_b32 v43, a75
	v_accvgpr_read_b32 v44, a76
	v_accvgpr_read_b32 v45, a77
	v_accvgpr_read_b32 v46, a78
	v_accvgpr_read_b32 v47, a79
	v_accvgpr_read_b32 v163, a237
	v_or_b32_e32 v163, s20, v163
	v_or_b32_e32 v164, 32, v163
	v_cmp_le_i32_e64 s[0:1], v164, v234
	v_or_b32_e32 v164, 33, v163
	v_mov_b32_e32 v165, 0xff800000
	v_cmp_le_i32_e64 s[6:7], v164, v234
	v_or_b32_e32 v164, 2, v163
	v_cmp_le_i32_e32 vcc, v163, v234
	v_cndmask_b32_e64 v33, v165, v33, s[6:7]
	v_cmp_le_i32_e64 s[6:7], v164, v234
	v_or_b32_e32 v164, 34, v163
	v_cmp_le_i32_e64 s[8:9], v164, v234
	v_or_b32_e32 v164, 3, v163
	v_cndmask_b32_e64 v32, v165, v32, s[0:1]
	v_cndmask_b32_e64 v34, v165, v34, s[8:9]
	v_cmp_le_i32_e64 s[8:9], v164, v234
	v_or_b32_e32 v164, 35, v163
	v_cmp_le_i32_e64 s[10:11], v164, v234
	v_or_b32_e32 v164, 8, v163
	v_cmp_lt_i32_e64 s[0:1], v163, v234
	v_cndmask_b32_e64 v35, v165, v35, s[10:11]
	v_cmp_le_i32_e64 s[10:11], v164, v234
	v_or_b32_e32 v164, 40, v163
	v_cmp_le_i32_e64 s[12:13], v164, v234
	v_or_b32_e32 v164, 9, v163
	s_nop 0
	v_cndmask_b32_e64 v36, v165, v36, s[12:13]
	v_cmp_le_i32_e64 s[12:13], v164, v234
	v_or_b32_e32 v164, 41, v163
	v_cmp_le_i32_e64 s[14:15], v164, v234
	v_or_b32_e32 v164, 10, v163
	s_nop 0
	v_cndmask_b32_e64 v37, v165, v37, s[14:15]
	v_cmp_le_i32_e64 s[14:15], v164, v234
	v_or_b32_e32 v164, 42, v163
	v_cmp_le_i32_e64 s[16:17], v164, v234
	v_or_b32_e32 v164, 11, v163
	s_nop 0
	v_cndmask_b32_e64 v38, v165, v38, s[16:17]
	v_cmp_le_i32_e64 s[16:17], v164, v234
	v_or_b32_e32 v164, 43, v163
	v_cmp_le_i32_e64 s[18:19], v164, v234
	v_or_b32_e32 v164, 16, v163
	s_nop 0
	v_cndmask_b32_e64 v39, v165, v39, s[18:19]
	v_cmp_le_i32_e64 s[18:19], v164, v234
	v_or_b32_e32 v164, 48, v163
	v_cmp_le_i32_e64 s[22:23], v164, v234
	v_or_b32_e32 v164, 17, v163
	s_nop 0
	v_cndmask_b32_e64 v40, v165, v40, s[22:23]
	v_cmp_le_i32_e64 s[22:23], v164, v234
	v_or_b32_e32 v164, 49, v163
	v_cmp_le_i32_e64 s[24:25], v164, v234
	v_or_b32_e32 v164, 18, v163
	s_nop 0
	v_cndmask_b32_e64 v41, v165, v41, s[24:25]
	v_cmp_le_i32_e64 s[24:25], v164, v234
	v_or_b32_e32 v164, 50, v163
	v_cmp_le_i32_e64 s[26:27], v164, v234
	v_or_b32_e32 v164, 19, v163
	s_nop 0
	v_cndmask_b32_e64 v42, v165, v42, s[26:27]
	v_cmp_le_i32_e64 s[26:27], v164, v234
	v_or_b32_e32 v164, 51, v163
	v_cmp_le_i32_e64 s[28:29], v164, v234
	v_or_b32_e32 v164, 24, v163
	s_nop 0
	v_cndmask_b32_e64 v43, v165, v43, s[28:29]
	v_cmp_le_i32_e64 s[28:29], v164, v234
	v_or_b32_e32 v164, 56, v163
	v_cmp_le_i32_e64 s[30:31], v164, v234
	v_or_b32_e32 v164, 25, v163
	s_nop 0
	v_cndmask_b32_e64 v44, v165, v44, s[30:31]
	v_cmp_le_i32_e64 s[30:31], v164, v234
	v_or_b32_e32 v164, 57, v163
	v_cmp_le_i32_e64 s[34:35], v164, v234
	v_or_b32_e32 v164, 26, v163
	s_nop 0
	v_cndmask_b32_e64 v45, v165, v45, s[34:35]
	v_cmp_le_i32_e64 s[34:35], v164, v234
	v_or_b32_e32 v164, 58, v163
	v_cmp_le_i32_e64 s[36:37], v164, v234
	v_or_b32_e32 v164, 27, v163
	v_or_b32_e32 v163, 59, v163
	v_cndmask_b32_e64 v46, v165, v46, s[36:37]
	v_cmp_le_i32_e64 s[36:37], v164, v234
	v_cmp_gt_i32_e64 s[40:41], v163, v234
	s_and_saveexec_b64 s[48:49], s[40:41]
	v_mov_b32_e32 v47, s65
	s_or_b64 exec, exec, s[48:49]
	v_accvgpr_write_b32 a79, v47
	v_accvgpr_write_b32 a78, v46
	v_accvgpr_write_b32 a77, v45
	v_accvgpr_write_b32 a76, v44
	v_accvgpr_write_b32 a75, v43
	v_accvgpr_write_b32 a74, v42
	v_accvgpr_write_b32 a73, v41
	v_accvgpr_write_b32 a72, v40
	v_accvgpr_write_b32 a71, v39
	v_accvgpr_write_b32 a70, v38
	v_accvgpr_write_b32 a69, v37
	v_accvgpr_write_b32 a68, v36
	v_accvgpr_write_b32 a67, v35
	v_accvgpr_write_b32 a66, v34
	v_accvgpr_write_b32 a65, v33
	v_accvgpr_write_b32 a64, v32
	v_mov_b32_e32 v32, 0xff800000
	v_cndmask_b32_e64 v1, v32, v1, s[0:1]
	v_cndmask_b32_e32 v0, v32, v0, vcc
	v_cndmask_b32_e64 v2, v32, v2, s[6:7]
	v_cndmask_b32_e64 v3, v32, v3, s[8:9]
	v_cndmask_b32_e64 v4, v32, v4, s[10:11]
	v_cndmask_b32_e64 v5, v32, v5, s[12:13]
	v_cndmask_b32_e64 v6, v32, v6, s[14:15]
	v_cndmask_b32_e64 v7, v32, v7, s[16:17]
	v_cndmask_b32_e64 v8, v32, v8, s[18:19]
	v_cndmask_b32_e64 v9, v32, v9, s[22:23]
	v_cndmask_b32_e64 v10, v32, v10, s[24:25]
	v_cndmask_b32_e64 v11, v32, v11, s[26:27]
	v_cndmask_b32_e64 v12, v32, v12, s[28:29]
	v_cndmask_b32_e64 v13, v32, v13, s[30:31]
	v_cndmask_b32_e64 v14, v32, v14, s[34:35]
	v_cndmask_b32_e64 v15, v32, v15, s[36:37]
	v_accvgpr_write_b32 a80, v0
	v_accvgpr_write_b32 a81, v1
	v_accvgpr_write_b32 a82, v2
	v_accvgpr_write_b32 a83, v3
	v_accvgpr_write_b32 a84, v4
	v_accvgpr_write_b32 a85, v5
	v_accvgpr_write_b32 a86, v6
	v_accvgpr_write_b32 a87, v7
	v_accvgpr_write_b32 a88, v8
	v_accvgpr_write_b32 a89, v9
	v_accvgpr_write_b32 a90, v10
	v_accvgpr_write_b32 a91, v11
	v_accvgpr_write_b32 a92, v12
	v_accvgpr_write_b32 a93, v13
	v_accvgpr_write_b32 a94, v14
	v_accvgpr_write_b32 a95, v15
	s_mov_b64 s[40:41], s[70:71]
; DI float ex2(float x) { return __builtin_amdgcn_exp2f(x); }
; template <int DQK>
; DI void attn_item_c(const u16* __restrict__ Qp, int ldq, const u16* __restrict__ Kp, const u16* __restrict__ Vtp, int ldv,
;                     int nkt, int q0, float c, u16* Yp, int ldy, char* smem, bool dry) {
;     ...
;     float mx = fmaxf(s0[0], s1[0]);
; #pragma unroll
;     for (int e = 1; e < 16; ++e) mx = fmaxf(fmaxf(mx, s0[e]), s1[e]);
;     mx = fmaxf(mx, __shfl_xor(mx, 32));
;     if (__builtin_amdgcn_ballot_w64((mx - m) * c > 8.f) != 0ull) {
;       const float mn = fmaxf(m, mx);
;       const float alpha = ex2((m - mn) * c);
;       m = mn;
;       l *= alpha;
; #pragma unroll
;       for (int dt = 0; dt < 4; ++dt)
; #pragma unroll
;         for (int e = 0; e < 16; ++e) o[dt][e] *= alpha;
;     }
;     ...
;     l += ps;
.LBB0_286:
	s_or_b64 exec, exec, s[46:47]
	v_add_f32_e32 v147, 0, v147
	v_add_f32_e32 v147, v148, v147
	v_add_f32_e32 v147, v149, v147
	v_add_f32_e32 v147, v150, v147
	v_add_f32_e32 v147, v151, v147
	v_add_f32_e32 v147, v152, v147
	v_add_f32_e32 v147, v153, v147
	v_add_f32_e32 v147, v154, v147
	v_add_f32_e32 v147, v155, v147
	v_add_f32_e32 v147, v156, v147
	v_add_f32_e32 v147, v157, v147
	v_add_f32_e32 v147, v158, v147
	v_add_f32_e32 v147, v159, v147
	v_add_f32_e32 v147, v160, v147
	v_add_f32_e32 v147, v161, v147
	v_add_f32_e32 v147, v248, v147
	v_add_f32_e32 v147, v213, v147
	v_accvgpr_read_b32 v32, a80
	v_accvgpr_read_b32 v0, a64
	v_add_f32_e32 v147, v214, v147
	v_add_f32_e32 v129, v129, v147
	v_max_f32_e32 v147, v0, v0
	v_max_f32_e32 v148, v32, v32
	v_accvgpr_read_b32 v33, a81
	v_accvgpr_read_b32 v1, a65
	v_max_f32_e32 v147, v148, v147
	v_accvgpr_read_b32 v34, a82
	v_accvgpr_read_b32 v2, a66
	v_max3_f32 v147, v147, v33, v1
	v_accvgpr_read_b32 v35, a83
	v_accvgpr_read_b32 v3, a67
	v_max3_f32 v147, v147, v34, v2
	v_accvgpr_read_b32 v36, a84
	v_accvgpr_read_b32 v4, a68
	v_max3_f32 v147, v147, v35, v3
	v_accvgpr_read_b32 v37, a85
	v_accvgpr_read_b32 v5, a69
	v_max3_f32 v147, v147, v36, v4
	v_accvgpr_read_b32 v38, a86
	v_accvgpr_read_b32 v6, a70
	v_max3_f32 v147, v147, v37, v5
	v_accvgpr_read_b32 v39, a87
	v_accvgpr_read_b32 v7, a71
	v_max3_f32 v147, v147, v38, v6
	v_accvgpr_read_b32 v40, a88
	v_accvgpr_read_b32 v8, a72
	v_max3_f32 v147, v147, v39, v7
	v_accvgpr_read_b32 v41, a89
	v_accvgpr_read_b32 v9, a73
	v_add_f32_e32 v129, v215, v129
	v_max3_f32 v147, v147, v40, v8
	v_accvgpr_read_b32 v42, a90
	v_accvgpr_read_b32 v10, a74
	v_add_f32_e32 v129, v227, v129
	v_max3_f32 v147, v147, v41, v9
	v_accvgpr_read_b32 v43, a91
	v_accvgpr_read_b32 v11, a75
	v_add_f32_e32 v129, v228, v129
	v_max3_f32 v147, v147, v42, v10
	v_accvgpr_read_b32 v44, a92
	v_accvgpr_read_b32 v12, a76
	v_add_f32_e32 v129, v229, v129
	v_max3_f32 v147, v147, v43, v11
	v_accvgpr_read_b32 v45, a93
	v_accvgpr_read_b32 v13, a77
	v_add_f32_e32 v129, v230, v129
	v_max3_f32 v147, v147, v44, v12
	v_accvgpr_read_b32 v46, a94
	v_accvgpr_read_b32 v14, a78
	v_add_f32_e32 v129, v244, v129
	v_max3_f32 v147, v147, v45, v13
	v_accvgpr_read_b32 v47, a95
	v_accvgpr_read_b32 v15, a79
	v_add_f32_e32 v129, v245, v129
	v_max3_f32 v147, v147, v46, v14
	v_add_f32_e32 v129, v246, v129
	v_max3_f32 v147, v147, v47, v15
	v_add_f32_e32 v129, v247, v129
	ds_bpermute_b32 v148, v232, v147
	v_add_f32_e32 v129, v162, v129
	v_add_f32_e32 v129, v231, v129
	v_add_f32_e32 v129, v235, v129
	v_add_f32_e32 v129, v218, v129
	v_add_f32_e32 v248, v146, v129
	s_waitcnt lgkmcnt(0)
	v_max_f32_e32 v129, v148, v148
	v_max_f32_e32 v129, v147, v129
	v_sub_f32_e32 v146, v129, v216
	v_mul_f32_e32 v146, 0x3dd53b94, v146
	v_cmp_lt_f32_e32 vcc, s33, v146
	s_cbranch_vccz .LBB0_288
	v_accvgpr_read_b32 v16, a48
	v_accvgpr_read_b32 v63, a47
	v_accvgpr_read_b32 v79, a31
	v_accvgpr_read_b32 v95, a15
	v_accvgpr_read_b32 v17, a49
	v_accvgpr_read_b32 v18, a50
	v_accvgpr_read_b32 v19, a51
	v_accvgpr_read_b32 v20, a52
	v_accvgpr_read_b32 v21, a53
	v_accvgpr_read_b32 v22, a54
	v_accvgpr_read_b32 v23, a55
	v_accvgpr_read_b32 v24, a56
	v_accvgpr_read_b32 v25, a57
	v_accvgpr_read_b32 v26, a58
	v_accvgpr_read_b32 v27, a59
	v_accvgpr_read_b32 v28, a60
	v_accvgpr_read_b32 v29, a61
	v_accvgpr_read_b32 v30, a62
	v_accvgpr_read_b32 v31, a63
	v_accvgpr_read_b32 v62, a46
	v_accvgpr_read_b32 v61, a45
	v_accvgpr_read_b32 v60, a44
	v_accvgpr_read_b32 v59, a43
	v_accvgpr_read_b32 v58, a42
	v_accvgpr_read_b32 v57, a41
	v_accvgpr_read_b32 v56, a40
	v_accvgpr_read_b32 v55, a39
	v_accvgpr_read_b32 v54, a38
	v_accvgpr_read_b32 v53, a37
	v_accvgpr_read_b32 v52, a36
	v_accvgpr_read_b32 v51, a35
	v_accvgpr_read_b32 v50, a34
	v_accvgpr_read_b32 v49, a33
	v_accvgpr_read_b32 v48, a32
	v_accvgpr_read_b32 v78, a30
	v_accvgpr_read_b32 v77, a29
	v_accvgpr_read_b32 v76, a28
	v_accvgpr_read_b32 v75, a27
	v_accvgpr_read_b32 v74, a26
	v_accvgpr_read_b32 v73, a25
	v_accvgpr_read_b32 v72, a24
	v_accvgpr_read_b32 v71, a23
	v_accvgpr_read_b32 v70, a22
	v_accvgpr_read_b32 v69, a21
	v_accvgpr_read_b32 v68, a20
	v_accvgpr_read_b32 v67, a19
	v_accvgpr_read_b32 v66, a18
	v_accvgpr_read_b32 v65, a17
	v_accvgpr_read_b32 v64, a16
	v_accvgpr_read_b32 v94, a14
	v_accvgpr_read_b32 v93, a13
	v_accvgpr_read_b32 v92, a12
	v_accvgpr_read_b32 v91, a11
	v_accvgpr_read_b32 v90, a10
	v_accvgpr_read_b32 v89, a9
	v_accvgpr_read_b32 v88, a8
	v_accvgpr_read_b32 v87, a7
	v_accvgpr_read_b32 v86, a6
	v_accvgpr_read_b32 v85, a5
	v_accvgpr_read_b32 v84, a4
	v_accvgpr_read_b32 v83, a3
	v_accvgpr_read_b32 v82, a2
	v_accvgpr_read_b32 v81, a1
	v_accvgpr_read_b32 v80, a0
	v_max_f32_e32 v129, v129, v129
	v_max_f32_e32 v146, v216, v216
	v_max_f32_e32 v249, v146, v129
	v_sub_f32_e32 v129, v216, v249
	v_mul_f32_e32 v129, 0x3dd53b94, v129
	v_exp_f32_e32 v216, v129
	s_nop 0
	v_pk_mul_f32 v[30:31], v[30:31], v[216:217] op_sel_hi:[1,0]
	v_pk_mul_f32 v[80:81], v[80:81], v[216:217] op_sel_hi:[1,0]
	v_pk_mul_f32 v[64:65], v[64:65], v[216:217] op_sel_hi:[1,0]
	v_pk_mul_f32 v[48:49], v[48:49], v[216:217] op_sel_hi:[1,0]
	v_pk_mul_f32 v[28:29], v[28:29], v[216:217] op_sel_hi:[1,0]
	v_pk_mul_f32 v[26:27], v[26:27], v[216:217] op_sel_hi:[1,0]
	v_pk_mul_f32 v[24:25], v[24:25], v[216:217] op_sel_hi:[1,0]
	v_pk_mul_f32 v[22:23], v[22:23], v[216:217] op_sel_hi:[1,0]
	v_pk_mul_f32 v[20:21], v[20:21], v[216:217] op_sel_hi:[1,0]
	v_pk_mul_f32 v[18:19], v[18:19], v[216:217] op_sel_hi:[1,0]
	v_pk_mul_f32 v[16:17], v[16:17], v[216:217] op_sel_hi:[1,0]
	v_pk_mul_f32 v[94:95], v[94:95], v[216:217] op_sel_hi:[1,0]
	v_accvgpr_write_b32 a63, v31
; #define MFMA32(a, b, c) __builtin_amdgcn_mfma_f32_32x32x16_bf16((a), (b), (c), 0, 0, 0)
; DI float ex2(float x) { return __builtin_amdgcn_exp2f(x); }
; template <int DQK>
; DI void attn_item_c(const u16* __restrict__ Qp, int ldq, const u16* __restrict__ Kp, const u16* __restrict__ Vtp, int ldv,
;                     int nkt, int q0, float c, u16* Yp, int ldy, char* smem, bool dry) {
;     ...
; #pragma unroll
;       for (int dt = 0; dt < 4; ++dt)
; #pragma unroll
;         for (int e = 0; e < 16; ++e) o[dt][e] *= alpha;
;     }
;     const float mc = m * c;
; #pragma unroll
;     for (int e = 0; e < 16; ++e) { n0[e] = 0.f; n1[e] = 0.f; }
;     const u16* k0 = Ks + r * KLD + 8 * h;
;     bf16x8 ka[3][2];
;     ka[0][0] = *(const bf16x8*)(k0); ka[0][1] = *(const bf16x8*)(k0 + 32 * KLD);
;     ka[1][0] = *(const bf16x8*)(k0 + 16); ka[1][1] = *(const bf16x8*)(k0 + 32 * KLD + 16);
;     bf16x8 pf[4];
;     u32x4 pk[4];
;     float ps = 0.f;
; #pragma unroll
;     for (int ks = 0; ks < NKS; ++ks) {
;       if (ks + 2 < NKS) {
;         ka[(ks + 2) % 3][0] = *(const bf16x8*)(k0 + 16 * (ks + 2));
;         ka[(ks + 2) % 3][1] = *(const bf16x8*)(k0 + 32 * KLD + 16 * (ks + 2));
;       }
;       __builtin_amdgcn_sched_barrier(0);
;       n0 = MFMA32(ka[ks % 3][0], qf[ks], n0); n1 = MFMA32(ka[ks % 3][1], qf[ks], n1);
;       {
;         constexpr int dummy0 = 0; (void)dummy0;
;         const int e_lo = (32 * ks) / NKS, e_hi = (32 * (ks + 1)) / NKS;
; #pragma unroll
;         for (int q = 0; q < 3; ++q) {
;           const int e = e_lo + q;
;           if (e < e_hi) {
;             if (e < 16) { s0[e & 15] = ex2(fmaf(s0[e & 15], c, -mc)); ps += s0[e & 15]; }
;             else        { s1[e & 15] = ex2(fmaf(s1[e & 15], c, -mc)); ps += s1[e & 15]; }
;           }
;         }
;       }
	v_pk_mul_f32 v[92:93], v[92:93], v[216:217] op_sel_hi:[1,0]
	v_pk_mul_f32 v[90:91], v[90:91], v[216:217] op_sel_hi:[1,0]
	v_pk_mul_f32 v[88:89], v[88:89], v[216:217] op_sel_hi:[1,0]
	v_pk_mul_f32 v[86:87], v[86:87], v[216:217] op_sel_hi:[1,0]
	v_pk_mul_f32 v[84:85], v[84:85], v[216:217] op_sel_hi:[1,0]
	v_pk_mul_f32 v[82:83], v[82:83], v[216:217] op_sel_hi:[1,0]
	v_pk_mul_f32 v[78:79], v[78:79], v[216:217] op_sel_hi:[1,0]
	v_accvgpr_write_b32 a0, v80
	v_pk_mul_f32 v[76:77], v[76:77], v[216:217] op_sel_hi:[1,0]
	v_pk_mul_f32 v[74:75], v[74:75], v[216:217] op_sel_hi:[1,0]
	v_pk_mul_f32 v[72:73], v[72:73], v[216:217] op_sel_hi:[1,0]
	v_pk_mul_f32 v[70:71], v[70:71], v[216:217] op_sel_hi:[1,0]
	v_pk_mul_f32 v[68:69], v[68:69], v[216:217] op_sel_hi:[1,0]
	v_pk_mul_f32 v[66:67], v[66:67], v[216:217] op_sel_hi:[1,0]
	v_pk_mul_f32 v[62:63], v[62:63], v[216:217] op_sel_hi:[1,0]
	v_accvgpr_write_b32 a16, v64
	v_pk_mul_f32 v[60:61], v[60:61], v[216:217] op_sel_hi:[1,0]
	v_pk_mul_f32 v[58:59], v[58:59], v[216:217] op_sel_hi:[1,0]
	v_pk_mul_f32 v[56:57], v[56:57], v[216:217] op_sel_hi:[1,0]
	v_pk_mul_f32 v[54:55], v[54:55], v[216:217] op_sel_hi:[1,0]
	v_pk_mul_f32 v[52:53], v[52:53], v[216:217] op_sel_hi:[1,0]
	v_pk_mul_f32 v[50:51], v[50:51], v[216:217] op_sel_hi:[1,0]
	v_accvgpr_write_b32 a62, v30
	v_accvgpr_write_b32 a32, v48
	v_accvgpr_write_b32 a61, v29
	v_accvgpr_write_b32 a60, v28
	v_accvgpr_write_b32 a59, v27
	v_accvgpr_write_b32 a58, v26
	v_accvgpr_write_b32 a57, v25
	v_accvgpr_write_b32 a56, v24
	v_accvgpr_write_b32 a55, v23
	v_accvgpr_write_b32 a54, v22
	v_accvgpr_write_b32 a53, v21
	v_accvgpr_write_b32 a52, v20
	v_accvgpr_write_b32 a51, v19
	v_accvgpr_write_b32 a50, v18
	v_accvgpr_write_b32 a49, v17
	v_accvgpr_write_b32 a48, v16
	v_pk_mul_f32 v[16:17], v[248:249], v[216:217]
	v_accvgpr_write_b32 a1, v81
	v_accvgpr_write_b32 a2, v82
	v_accvgpr_write_b32 a3, v83
	v_accvgpr_write_b32 a4, v84
	v_accvgpr_write_b32 a5, v85
	v_accvgpr_write_b32 a6, v86
	v_accvgpr_write_b32 a7, v87
	v_accvgpr_write_b32 a8, v88
	v_accvgpr_write_b32 a9, v89
	v_accvgpr_write_b32 a10, v90
	v_accvgpr_write_b32 a11, v91
	v_accvgpr_write_b32 a12, v92
	v_accvgpr_write_b32 a13, v93
	v_accvgpr_write_b32 a14, v94
	v_accvgpr_write_b32 a15, v95
	v_accvgpr_write_b32 a17, v65
	v_accvgpr_write_b32 a18, v66
	v_accvgpr_write_b32 a19, v67
	v_accvgpr_write_b32 a20, v68
	v_accvgpr_write_b32 a21, v69
	v_accvgpr_write_b32 a22, v70
	v_accvgpr_write_b32 a23, v71
	v_accvgpr_write_b32 a24, v72
	v_accvgpr_write_b32 a25, v73
	v_accvgpr_write_b32 a26, v74
	v_accvgpr_write_b32 a27, v75
	v_accvgpr_write_b32 a28, v76
	v_accvgpr_write_b32 a29, v77
	v_accvgpr_write_b32 a30, v78
	v_accvgpr_write_b32 a31, v79
	v_accvgpr_write_b32 a33, v49
	v_accvgpr_write_b32 a34, v50
	v_accvgpr_write_b32 a35, v51
	v_accvgpr_write_b32 a36, v52
	v_accvgpr_write_b32 a37, v53
	v_accvgpr_write_b32 a38, v54
	v_accvgpr_write_b32 a39, v55
	v_accvgpr_write_b32 a40, v56
	v_accvgpr_write_b32 a41, v57
	v_accvgpr_write_b32 a42, v58
	v_accvgpr_write_b32 a43, v59
	v_accvgpr_write_b32 a44, v60
	v_accvgpr_write_b32 a45, v61
	v_accvgpr_write_b32 a46, v62
	v_accvgpr_write_b32 a47, v63
	v_mov_b32_e32 v216, v249
	v_mov_b64_e32 v[248:249], v[16:17]
.LBB0_288:
	ds_read_b128 v[16:19], v212
	ds_read_b128 v[20:23], v212 offset:32
	ds_read_b128 v[24:27], v212 offset:12800
	ds_read_b128 v[28:31], v212 offset:64
	ds_read_b128 v[48:51], v212 offset:12832
	ds_read_b128 v[52:55], v212 offset:12864
	v_accvgpr_read_b32 v56, a238
	v_cmp_le_i32_e32 vcc, s20, v56
	s_waitcnt lgkmcnt(5)
	v_mfma_f32_32x32x16_bf16 a[80:95], v[16:19], v[96:99], 0
	v_fmamk_f32 v16, v32, 0x3dd53b94, v249
	v_exp_f32_e32 v162, v16
	v_fmamk_f32 v16, v33, 0x3dd53b94, v249
	v_exp_f32_e32 v163, v16
	s_waitcnt lgkmcnt(3)
	v_mfma_f32_32x32x16_bf16 a[64:79], v[24:27], v[96:99], 0
	ds_read_b128 v[16:19], v212 offset:96
	ds_read_b128 v[24:27], v212 offset:12896
	v_mfma_f32_32x32x16_bf16 a[80:95], v[20:23], v[100:103], a[80:95]
	v_fmamk_f32 v20, v34, 0x3dd53b94, v249
	v_exp_f32_e32 v164, v20
	v_fmamk_f32 v20, v35, 0x3dd53b94, v249
	v_exp_f32_e32 v165, v20
	v_fmamk_f32 v20, v36, 0x3dd53b94, v249
	v_exp_f32_e32 v166, v20
	s_waitcnt lgkmcnt(3)
	v_mfma_f32_32x32x16_bf16 a[64:79], v[48:51], v[100:103], a[64:79]
	ds_read_b128 v[20:23], v212 offset:128
	ds_read_b128 v[32:35], v212 offset:12928
	v_mfma_f32_32x32x16_bf16 a[80:95], v[28:31], v[104:107], a[80:95]
	v_fmamk_f32 v28, v37, 0x3dd53b94, v249
	v_exp_f32_e32 v167, v28
	v_fmamk_f32 v28, v38, 0x3dd53b94, v249
	v_exp_f32_e32 v168, v28
	v_fmamk_f32 v28, v39, 0x3dd53b94, v249
	v_exp_f32_e32 v169, v28
	s_waitcnt lgkmcnt(4)
	v_mfma_f32_32x32x16_bf16 a[64:79], v[52:55], v[104:107], a[64:79]
	ds_read_b128 v[28:31], v212 offset:160
	ds_read_b128 v[36:39], v212 offset:12960
	s_waitcnt lgkmcnt(5)
	v_mfma_f32_32x32x16_bf16 a[80:95], v[16:19], v[108:111], a[80:95]
	v_fmamk_f32 v16, v40, 0x3dd53b94, v249
	v_exp_f32_e32 v170, v16
	v_fmamk_f32 v16, v41, 0x3dd53b94, v249
	v_exp_f32_e32 v171, v16
	s_waitcnt lgkmcnt(4)
	v_mfma_f32_32x32x16_bf16 a[64:79], v[24:27], v[108:111], a[64:79]
	ds_read_b128 v[16:19], v212 offset:192
	ds_read_b128 v[24:27], v212 offset:12992
	s_waitcnt lgkmcnt(5)
	v_mfma_f32_32x32x16_bf16 a[80:95], v[20:23], v[112:115], a[80:95]
	v_fmamk_f32 v20, v42, 0x3dd53b94, v249
	v_exp_f32_e32 v172, v20
	v_fmamk_f32 v20, v43, 0x3dd53b94, v249
	v_exp_f32_e32 v173, v20
	v_fmamk_f32 v20, v44, 0x3dd53b94, v249
	v_exp_f32_e32 v174, v20
	s_waitcnt lgkmcnt(4)
	v_mfma_f32_32x32x16_bf16 a[64:79], v[32:35], v[112:115], a[64:79]
	ds_read_b128 v[20:23], v212 offset:224
	ds_read_b128 v[32:35], v212 offset:13024
	s_waitcnt lgkmcnt(5)
; #define MFMA32(a, b, c) __builtin_amdgcn_mfma_f32_32x32x16_bf16((a), (b), (c), 0, 0, 0)
; DI unsigned pack2(float a, float b) { f2_t v = {a, b}; bf2_t r = __builtin_convertvector(v, bf2_t); return __builtin_bit_cast(unsigned, r); }
; DI float ex2(float x) { return __builtin_amdgcn_exp2f(x); }
; template <int DQK>
; DI void attn_item_c(const u16* __restrict__ Qp, int ldq, const u16* __restrict__ Kp, const u16* __restrict__ Vtp, int ldv,
;                     int nkt, int q0, float c, u16* Yp, int ldy, char* smem, bool dry) {
;     ...
; #pragma unroll
;     for (int ks = 0; ks < NKS; ++ks) {
;       if (ks + 2 < NKS) {
;         ka[(ks + 2) % 3][0] = *(const bf16x8*)(k0 + 16 * (ks + 2));
;         ka[(ks + 2) % 3][1] = *(const bf16x8*)(k0 + 32 * KLD + 16 * (ks + 2));
;       }
;       __builtin_amdgcn_sched_barrier(0);
;       n0 = MFMA32(ka[ks % 3][0], qf[ks], n0); n1 = MFMA32(ka[ks % 3][1], qf[ks], n1);
;       {
;         constexpr int dummy0 = 0; (void)dummy0;
;         const int e_lo = (32 * ks) / NKS, e_hi = (32 * (ks + 1)) / NKS;
; #pragma unroll
;         for (int q = 0; q < 3; ++q) {
;           const int e = e_lo + q;
;           if (e < e_hi) {
;             if (e < 16) { s0[e & 15] = ex2(fmaf(s0[e & 15], c, -mc)); ps += s0[e & 15]; }
;             else        { s1[e & 15] = ex2(fmaf(s1[e & 15], c, -mc)); ps += s1[e & 15]; }
;           }
;         }
;       }
;       if (ks == 3)  { pk[0].x = pack2(s0[0], s0[1]);  pk[0].y = pack2(s0[2], s0[3]);   pk[0].z = pack2(s0[4], s0[5]);   pk[0].w = pack2(s0[6], s0[7]); }
;       if (ks == 6)  { pk[1].x = pack2(s0[8], s0[9]);  pk[1].y = pack2(s0[10], s0[11]); pk[1].z = pack2(s0[12], s0[13]); pk[1].w = pack2(s0[14], s0[15]); }
;       if (ks == 9)  { pk[2].x = pack2(s1[0], s1[1]);  pk[2].y = pack2(s1[2], s1[3]);   pk[2].z = pack2(s1[4], s1[5]);   pk[2].w = pack2(s1[6], s1[7]); }
;       if (ks == NKS - 1) { pk[3].x = pack2(s1[8], s1[9]);  pk[3].y = pack2(s1[10], s1[11]); pk[3].z = pack2(s1[12], s1[13]); pk[3].w = pack2(s1[14], s1[15]); }
;       __builtin_amdgcn_sched_barrier(0);
;     }
;     l += ps;
; #pragma unroll
;     for (int i = 0; i < 4; ++i) pf[i] = __builtin_bit_cast(bf16x8, pk[i]);
;     if (active) {
	v_mfma_f32_32x32x16_bf16 a[80:95], v[28:31], v[116:119], a[80:95]
	v_fmamk_f32 v28, v45, 0x3dd53b94, v249
	v_exp_f32_e32 v175, v28
	v_fmamk_f32 v28, v46, 0x3dd53b94, v249
	v_exp_f32_e32 v176, v28
	v_fmamk_f32 v28, v47, 0x3dd53b94, v249
	v_exp_f32_e32 v177, v28
	s_waitcnt lgkmcnt(4)
	v_mfma_f32_32x32x16_bf16 a[64:79], v[36:39], v[116:119], a[64:79]
	ds_read_b128 v[28:31], v212 offset:256
	ds_read_b128 v[36:39], v212 offset:13056
	s_waitcnt lgkmcnt(5)
	v_mfma_f32_32x32x16_bf16 a[80:95], v[16:19], v[120:123], a[80:95]
	v_fmamk_f32 v0, v0, 0x3dd53b94, v249
	v_exp_f32_e32 v213, v0
	v_fmamk_f32 v0, v1, 0x3dd53b94, v249
	v_exp_f32_e32 v214, v0
	s_waitcnt lgkmcnt(4)
	v_mfma_f32_32x32x16_bf16 a[64:79], v[24:27], v[120:123], a[64:79]
	ds_read_b128 v[16:19], v212 offset:288
	ds_read_b128 v[24:27], v212 offset:13088
	s_waitcnt lgkmcnt(5)
	v_mfma_f32_32x32x16_bf16 a[80:95], v[20:23], v[124:127], a[80:95]
	v_fmamk_f32 v0, v2, 0x3dd53b94, v249
	v_exp_f32_e32 v215, v0
	v_fmamk_f32 v0, v3, 0x3dd53b94, v249
	v_exp_f32_e32 v129, v0
	v_fmamk_f32 v0, v4, 0x3dd53b94, v249
	v_exp_f32_e32 v227, v0
	s_waitcnt lgkmcnt(4)
	v_mfma_f32_32x32x16_bf16 a[64:79], v[32:35], v[124:127], a[64:79]
	ds_read_b128 v[0:3], v212 offset:320
	ds_read_b128 v[20:23], v212 offset:13120
	s_waitcnt lgkmcnt(5)
	v_mfma_f32_32x32x16_bf16 a[80:95], v[28:31], v[130:133], a[80:95]
	v_fmamk_f32 v4, v5, 0x3dd53b94, v249
	v_exp_f32_e32 v228, v4
	v_fmamk_f32 v4, v6, 0x3dd53b94, v249
	v_exp_f32_e32 v229, v4
	v_fmamk_f32 v4, v7, 0x3dd53b94, v249
	v_exp_f32_e32 v230, v4
	s_waitcnt lgkmcnt(4)
	v_mfma_f32_32x32x16_bf16 a[64:79], v[36:39], v[130:133], a[64:79]
	ds_read_b128 v[4:7], v212 offset:352
	ds_read_b128 v[28:31], v212 offset:13152
	s_waitcnt lgkmcnt(5)
	v_mfma_f32_32x32x16_bf16 a[80:95], v[16:19], v[134:137], a[80:95]
	v_fmamk_f32 v8, v8, 0x3dd53b94, v249
	v_exp_f32_e32 v147, v8
	v_fmamk_f32 v8, v9, 0x3dd53b94, v249
	v_exp_f32_e32 v148, v8
	s_waitcnt lgkmcnt(4)
	v_mfma_f32_32x32x16_bf16 a[64:79], v[24:27], v[134:137], a[64:79]
	s_waitcnt lgkmcnt(3)
	v_mfma_f32_32x32x16_bf16 a[80:95], v[0:3], v[138:141], a[80:95]
	v_fmamk_f32 v0, v10, 0x3dd53b94, v249
	v_exp_f32_e32 v149, v0
	v_fmamk_f32 v0, v11, 0x3dd53b94, v249
	v_exp_f32_e32 v218, v0
	v_fmamk_f32 v0, v12, 0x3dd53b94, v249
	v_exp_f32_e32 v244, v0
	s_waitcnt lgkmcnt(2)
	v_mfma_f32_32x32x16_bf16 a[64:79], v[20:23], v[138:141], a[64:79]
	s_waitcnt lgkmcnt(1)
	v_mfma_f32_32x32x16_bf16 a[80:95], v[4:7], v[142:145], a[80:95]
	v_fmamk_f32 v0, v13, 0x3dd53b94, v249
	v_exp_f32_e32 v231, v0
	v_fmamk_f32 v0, v14, 0x3dd53b94, v249
	v_exp_f32_e32 v235, v0
	v_fmamk_f32 v0, v15, 0x3dd53b94, v249
	v_exp_f32_e32 v146, v0
	s_waitcnt lgkmcnt(0)
	v_mfma_f32_32x32x16_bf16 a[64:79], v[28:31], v[142:145], a[64:79]
	s_and_saveexec_b64 s[0:1], vcc
	s_xor_b64 s[0:1], exec, s[0:1]
	s_cbranch_execz .LBB0_290
; #define MFMA32(a, b, c) __builtin_amdgcn_mfma_f32_32x32x16_bf16((a), (b), (c), 0, 0, 0)
; template <int DQK>
; DI void attn_item_c(const u16* __restrict__ Qp, int ldq, const u16* __restrict__ Kp, const u16* __restrict__ Vtp, int ldv,
;                     int nkt, int q0, float c, u16* Yp, int ldy, char* smem, bool dry) {
;     ...
;   auto gloadK = [&](u32x4* ks_, int j) {
;     const u16* kg = Kp + (size_t)(j + 1) * 64 * DQK;
; #pragma unroll
;     for (int i = 0; i < NKC; ++i) ks_[i] = *(const u32x4*)(kg + (size_t)(tid + 256 * i) * 8);
;   };
;   auto gloadV = [&](u32x4* vs_, int j) {
; #pragma unroll
;     for (int i = 0; i < 4; ++i) vs_[i] = *(const u32x4*)(Vtp + (size_t)j * 8192 + (size_t)(tid + 256 * i) * 8);
;   };
;   auto lstoreK = [&](const u32x4* ks_, u16* Lb) {
; #pragma unroll
;     for (int i = 0; i < NKC; ++i) *(u32x4*)(Lb + kso[i]) = ks_[i];
;   };
;   auto lstoreV = [&](const u32x4* vs_, u16* Lb) {
; #pragma unroll
;     for (int i = 0; i < 4; ++i) {
;       u16* dst = Lb + vso + (32 * i) * 72;
;       u32x2 lo = {vs_[i].x, vs_[i].y}, hi = {vs_[i].z, vs_[i].w};
;       *(u32x2*)dst = lo; *(u32x2*)(dst + 8) = hi;
;     }
;   };
;     ...
;     for (int i = 0; i < 4; ++i) pf[i] = __builtin_bit_cast(bf16x8, pk[i]);
;     if (active) {
;       const u16* v0 = Vs + r * 72 + 8 * h;
;       bf16x8 va[2][4];
; #pragma unroll
;       for (int dt = 0; dt < 4; ++dt) va[0][dt] = *(const bf16x8*)(v0 + (32 * dt) * 72);
; #pragma unroll
;       for (int kk = 0; kk < 4; ++kk) {
;         if (kk < 3) {
; #pragma unroll
;           for (int dt = 0; dt < 4; ++dt) va[(kk + 1) & 1][dt] = *(const bf16x8*)(v0 + (32 * dt) * 72 + 16 * (kk + 1));
;         }
;         __builtin_amdgcn_sched_barrier(0);
; #pragma unroll
;         for (int dt = 0; dt < 4; ++dt) o[dt] = MFMA32(va[kk & 1][dt], pf[kk], o[dt]);
;         if (kk == 0) lstoreK(wk, Ln);
;         if (kk == 1) lstoreV(wv, Ln);
;         if (kk == 2) gloadK(wk, kt + 3);
;         if (kk == 3) gloadV(wv, kt + 3);
;         __builtin_amdgcn_sched_barrier(0);
;       }
	ds_read_b128 v[16:19], v128 offset:25600
	ds_read_b128 v[20:23], v128 offset:25632
	ds_read_b128 v[24:27], v128 offset:30208
	ds_read_b128 v[28:31], v128 offset:30240
	ds_read_b128 v[32:35], v128 offset:34816
	ds_read_b128 v[36:39], v128 offset:34848
	ds_read_b128 v[40:43], v128 offset:39424
	ds_read_b128 v[44:47], v128 offset:39456
	s_add_i32 s20, s44, 5
	s_add_i32 s8, s44, 6
	v_cvt_pk_bf16_f32 v0, v147, v148
	v_cvt_pk_bf16_f32 v1, v149, v218
	v_cvt_pk_bf16_f32 v2, v244, v231
	v_cvt_pk_bf16_f32 v3, v235, v146
	v_cvt_pk_bf16_f32 v4, v213, v214
	v_cvt_pk_bf16_f32 v5, v215, v129
	v_cvt_pk_bf16_f32 v6, v227, v228
	v_cvt_pk_bf16_f32 v7, v229, v230
	v_cvt_pk_bf16_f32 v8, v170, v171
	v_cvt_pk_bf16_f32 v9, v172, v173
	v_cvt_pk_bf16_f32 v10, v174, v175
	v_cvt_pk_bf16_f32 v11, v176, v177
	v_cvt_pk_bf16_f32 v12, v162, v163
	v_cvt_pk_bf16_f32 v13, v164, v165
	v_cvt_pk_bf16_f32 v14, v166, v167
	v_cvt_pk_bf16_f32 v15, v168, v169
	s_lshl_b64 s[6:7], s[20:21], 14
	s_mul_hi_u32 s9, s8, 0x6000
	s_mulk_i32 s8, 0x6000
	s_waitcnt lgkmcnt(7)
	v_mfma_f32_32x32x16_bf16 a[0:15], v[16:19], v[12:15], a[0:15]
	s_waitcnt vmcnt(10)
	ds_write_b128 v221, a[148:151] offset:44032
	ds_write_b128 v222, a[152:155] offset:44032
	ds_write_b128 v223, a[160:163] offset:44032
	ds_write_b128 v224, a[168:171] offset:44032
	ds_write_b128 v225, a[176:179] offset:44032
	ds_write_b128 v226, a[184:187] offset:44032
	s_waitcnt lgkmcnt(11)
	v_mfma_f32_32x32x16_bf16 a[16:31], v[24:27], v[12:15], a[16:31]
	s_waitcnt lgkmcnt(9)
	v_mfma_f32_32x32x16_bf16 a[32:47], v[32:35], v[12:15], a[32:47]
	s_waitcnt lgkmcnt(7)
	v_mfma_f32_32x32x16_bf16 a[48:63], v[40:43], v[12:15], a[48:63]
	ds_read_b128 v[12:15], v128 offset:25664
	ds_read_b128 v[16:19], v128 offset:30272
	ds_read_b128 v[24:27], v128 offset:34880
	ds_read_b128 v[32:35], v128 offset:39488
	v_mfma_f32_32x32x16_bf16 a[0:15], v[20:23], v[8:11], a[0:15]
	ds_write2_b64 v220, v[178:179], v[180:181] offset1:2
	ds_write2_b64 v211, v[186:187], v[188:189] offset0:64 offset1:66
	ds_write2_b64 v251, v[182:183], v[184:185] offset0:128 offset1:130
	ds_write2_b64 v210, v[194:195], v[196:197] offset0:192 offset1:194
	v_mfma_f32_32x32x16_bf16 a[16:31], v[28:31], v[8:11], a[16:31]
	v_mfma_f32_32x32x16_bf16 a[32:47], v[36:39], v[8:11], a[32:47]
	s_waitcnt lgkmcnt(14)
	v_mfma_f32_32x32x16_bf16 a[48:63], v[44:47], v[8:11], a[48:63]
	ds_read_b128 v[8:11], v128 offset:25696
	ds_read_b128 v[20:23], v128 offset:30304
	ds_read_b128 v[28:31], v128 offset:34912
	ds_read_b128 v[36:39], v128 offset:39520
	s_add_u32 s8, s94, s8
	s_addc_u32 s9, s95, s9
	s_waitcnt lgkmcnt(11)
	v_mfma_f32_32x32x16_bf16 a[0:15], v[12:15], v[4:7], a[0:15]
	v_lshl_add_u64 v[12:13], s[8:9], 0, v[236:237]
	v_lshl_add_u64 v[14:15], s[8:9], 0, v[238:239]
	global_load_dwordx4 a[96:99], v[12:13], off
	global_load_dwordx4 a[100:103], v[14:15], off
	v_lshl_add_u64 v[12:13], s[8:9], 0, v[240:241]
	v_lshl_add_u64 v[14:15], s[8:9], 0, v[242:243]
	global_load_dwordx4 a[104:107], v[12:13], off
	global_load_dwordx4 a[108:111], v[14:15], off
	v_accvgpr_read_b32 v12, a230
	v_accvgpr_read_b32 v13, a231
	v_accvgpr_read_b32 v14, a232
	v_lshl_add_u64 v[12:13], s[8:9], 0, v[12:13]
	v_accvgpr_read_b32 v15, a233
	v_lshl_add_u64 v[14:15], s[8:9], 0, v[14:15]
	global_load_dwordx4 a[112:115], v[12:13], off
	global_load_dwordx4 a[116:119], v[14:15], off
	s_waitcnt lgkmcnt(10)
	v_mfma_f32_32x32x16_bf16 a[16:31], v[16:19], v[4:7], a[16:31]
	s_waitcnt lgkmcnt(9)
	v_mfma_f32_32x32x16_bf16 a[32:47], v[24:27], v[4:7], a[32:47]
	s_waitcnt lgkmcnt(8)
	v_mfma_f32_32x32x16_bf16 a[48:63], v[32:35], v[4:7], a[48:63]
	s_add_u32 s6, s60, s6
	s_addc_u32 s7, s61, s7
	s_waitcnt lgkmcnt(3)
	v_mfma_f32_32x32x16_bf16 a[0:15], v[8:11], v[0:3], a[0:15]
	s_waitcnt lgkmcnt(2)
	v_mfma_f32_32x32x16_bf16 a[16:31], v[20:23], v[0:3], a[16:31]
	s_waitcnt lgkmcnt(1)
	v_mfma_f32_32x32x16_bf16 a[32:47], v[28:31], v[0:3], a[32:47]
	s_waitcnt lgkmcnt(0)
	v_mfma_f32_32x32x16_bf16 a[48:63], v[36:39], v[0:3], a[48:63]
	v_lshl_add_u64 v[0:1], s[6:7], 0, v[236:237]
	global_load_dwordx4 a[240:243], v[0:1], off
	v_lshl_add_u64 v[0:1], s[6:7], 0, v[238:239]
	global_load_dwordx4 v[150:153], v[0:1], off
	v_lshl_add_u64 v[0:1], s[6:7], 0, v[240:241]
	global_load_dwordx4 v[154:157], v[0:1], off
	v_lshl_add_u64 v[0:1], s[6:7], 0, v[242:243]
	global_load_dwordx4 v[158:161], v[0:1], off

; DI int crow(int reg, int h) { return (reg & 3) + 8 * (reg >> 2) + 4 * h; }
; template <int DQK>
; DI void attn_item_c(const u16* __restrict__ Qp, int ldq, const u16* __restrict__ Kp, const u16* __restrict__ Vtp, int ldv,
;                     int nkt, int q0, float c, u16* Yp, int ldy, char* smem, bool dry) {
;     ...
;   auto body = [&](int kt, u32x4* wk, u32x4* wv, f32x16& s0, f32x16& s1, f32x16& n0, f32x16& n1) {
;     const u16* Ks = L0 + (kt & 1) * BUFE;
;     const u16* Vs = Ks + 64 * KLD;
;     u16* Ln = L0 + ((kt + 1) & 1) * BUFE;
;     const bool active = !(kt * 64 > qmin + 31);
;     if (kt * 64 + 63 > qmin) {
; #pragma unroll
;       for (int e = 0; e < 16; ++e) {
;         int key = kt * 64 + crow(e, h);
;         if (key > qi) s0[e] = -INFINITY;
;         if (key + 32 > qi) s1[e] = -INFINITY;
;       }
;     }
;     ...
;     __syncthreads();
.LBB0_292:
	s_or_b64 exec, exec, s[0:1]
	s_nop 0
	s_or_b32 s0, s45, 0xff
	s_or_b32 s20, s45, 0xc0
	v_cmp_gt_i32_e32 vcc, s0, v233
	s_waitcnt lgkmcnt(0)
	s_barrier
	s_and_saveexec_b64 s[46:47], vcc
	s_cbranch_execz .LBB0_296
	v_accvgpr_read_b32 v0, a80
	v_accvgpr_read_b32 v32, a64
	v_accvgpr_read_b32 v1, a81
	v_accvgpr_read_b32 v2, a82
	v_accvgpr_read_b32 v3, a83
	v_accvgpr_read_b32 v4, a84
	v_accvgpr_read_b32 v5, a85
	v_accvgpr_read_b32 v6, a86
	v_accvgpr_read_b32 v7, a87
	v_accvgpr_read_b32 v8, a88
	v_accvgpr_read_b32 v9, a89
	v_accvgpr_read_b32 v10, a90
	v_accvgpr_read_b32 v11, a91
	v_accvgpr_read_b32 v12, a92
	v_accvgpr_read_b32 v13, a93
	v_accvgpr_read_b32 v14, a94
	v_accvgpr_read_b32 v15, a95
	v_accvgpr_read_b32 v33, a65
	v_accvgpr_read_b32 v34, a66
	v_accvgpr_read_b32 v35, a67
	v_accvgpr_read_b32 v36, a68
	v_accvgpr_read_b32 v37, a69
	v_accvgpr_read_b32 v38, a70
	v_accvgpr_read_b32 v39, a71
	v_accvgpr_read_b32 v40, a72
	v_accvgpr_read_b32 v41, a73
	v_accvgpr_read_b32 v42, a74
	v_accvgpr_read_b32 v43, a75
	v_accvgpr_read_b32 v44, a76
	v_accvgpr_read_b32 v45, a77
	v_accvgpr_read_b32 v46, a78
	v_accvgpr_read_b32 v47, a79
	v_accvgpr_read_b32 v178, a237
	v_or_b32_e32 v178, s20, v178
	v_or_b32_e32 v179, 32, v178
	v_cmp_le_i32_e64 s[0:1], v179, v234
	v_or_b32_e32 v179, 33, v178
	v_mov_b32_e32 v180, 0xff800000
	v_cmp_le_i32_e64 s[6:7], v179, v234
	v_or_b32_e32 v179, 2, v178
	v_cmp_le_i32_e32 vcc, v178, v234
	v_cndmask_b32_e64 v33, v180, v33, s[6:7]
	v_cmp_le_i32_e64 s[6:7], v179, v234
	v_or_b32_e32 v179, 34, v178
	v_cmp_le_i32_e64 s[8:9], v179, v234
	v_or_b32_e32 v179, 3, v178
	v_cndmask_b32_e64 v32, v180, v32, s[0:1]
	v_cndmask_b32_e64 v34, v180, v34, s[8:9]
	v_cmp_le_i32_e64 s[8:9], v179, v234
	v_or_b32_e32 v179, 35, v178
	v_cmp_le_i32_e64 s[10:11], v179, v234
	v_or_b32_e32 v179, 8, v178
	v_cmp_lt_i32_e64 s[0:1], v178, v234
	v_cndmask_b32_e64 v35, v180, v35, s[10:11]
	v_cmp_le_i32_e64 s[10:11], v179, v234
	v_or_b32_e32 v179, 40, v178
	v_cmp_le_i32_e64 s[12:13], v179, v234
	v_or_b32_e32 v179, 9, v178
	s_nop 0
	v_cndmask_b32_e64 v36, v180, v36, s[12:13]
	v_cmp_le_i32_e64 s[12:13], v179, v234
	v_or_b32_e32 v179, 41, v178
	v_cmp_le_i32_e64 s[14:15], v179, v234
	v_or_b32_e32 v179, 10, v178
	s_nop 0
	v_cndmask_b32_e64 v37, v180, v37, s[14:15]
	v_cmp_le_i32_e64 s[14:15], v179, v234
	v_or_b32_e32 v179, 42, v178
	v_cmp_le_i32_e64 s[16:17], v179, v234
	v_or_b32_e32 v179, 11, v178
	s_nop 0
	v_cndmask_b32_e64 v38, v180, v38, s[16:17]
	v_cmp_le_i32_e64 s[16:17], v179, v234
	v_or_b32_e32 v179, 43, v178
	v_cmp_le_i32_e64 s[18:19], v179, v234
	v_or_b32_e32 v179, 16, v178
	s_nop 0
	v_cndmask_b32_e64 v39, v180, v39, s[18:19]
	v_cmp_le_i32_e64 s[18:19], v179, v234
	v_or_b32_e32 v179, 48, v178
	v_cmp_le_i32_e64 s[22:23], v179, v234
	v_or_b32_e32 v179, 17, v178
	s_nop 0
	v_cndmask_b32_e64 v40, v180, v40, s[22:23]
	v_cmp_le_i32_e64 s[22:23], v179, v234
	v_or_b32_e32 v179, 49, v178
	v_cmp_le_i32_e64 s[24:25], v179, v234
	v_or_b32_e32 v179, 18, v178
	s_nop 0
	v_cndmask_b32_e64 v41, v180, v41, s[24:25]
	v_cmp_le_i32_e64 s[24:25], v179, v234
	v_or_b32_e32 v179, 50, v178
	v_cmp_le_i32_e64 s[26:27], v179, v234
	v_or_b32_e32 v179, 19, v178
	s_nop 0
	v_cndmask_b32_e64 v42, v180, v42, s[26:27]
	v_cmp_le_i32_e64 s[26:27], v179, v234
	v_or_b32_e32 v179, 51, v178
	v_cmp_le_i32_e64 s[28:29], v179, v234
	v_or_b32_e32 v179, 24, v178
	s_nop 0
	v_cndmask_b32_e64 v43, v180, v43, s[28:29]
	v_cmp_le_i32_e64 s[28:29], v179, v234
	v_or_b32_e32 v179, 56, v178
	v_cmp_le_i32_e64 s[30:31], v179, v234
	v_or_b32_e32 v179, 25, v178
	s_nop 0
	v_cndmask_b32_e64 v44, v180, v44, s[30:31]
	v_cmp_le_i32_e64 s[30:31], v179, v234
	v_or_b32_e32 v179, 57, v178
	v_cmp_le_i32_e64 s[34:35], v179, v234
	v_or_b32_e32 v179, 26, v178
	s_nop 0
	v_cndmask_b32_e64 v45, v180, v45, s[34:35]
	v_cmp_le_i32_e64 s[34:35], v179, v234
	v_or_b32_e32 v179, 58, v178
	v_cmp_le_i32_e64 s[36:37], v179, v234
	v_or_b32_e32 v179, 27, v178
	v_or_b32_e32 v178, 59, v178
	v_cndmask_b32_e64 v46, v180, v46, s[36:37]
	v_cmp_le_i32_e64 s[36:37], v179, v234
	v_cmp_gt_i32_e64 s[40:41], v178, v234
	s_and_saveexec_b64 s[48:49], s[40:41]
	v_mov_b32_e32 v47, s65
	s_or_b64 exec, exec, s[48:49]
	v_accvgpr_write_b32 a79, v47
	v_accvgpr_write_b32 a78, v46
	v_accvgpr_write_b32 a77, v45
	v_accvgpr_write_b32 a76, v44
	v_accvgpr_write_b32 a75, v43
	v_accvgpr_write_b32 a74, v42
	v_accvgpr_write_b32 a73, v41
	v_accvgpr_write_b32 a72, v40
	v_accvgpr_write_b32 a71, v39
	v_accvgpr_write_b32 a70, v38
	v_accvgpr_write_b32 a69, v37
	v_accvgpr_write_b32 a68, v36
	v_accvgpr_write_b32 a67, v35
	v_accvgpr_write_b32 a66, v34
	v_accvgpr_write_b32 a65, v33
	v_accvgpr_write_b32 a64, v32
	v_mov_b32_e32 v32, 0xff800000
	v_cndmask_b32_e64 v1, v32, v1, s[0:1]
	v_cndmask_b32_e32 v0, v32, v0, vcc
	v_cndmask_b32_e64 v2, v32, v2, s[6:7]
	v_cndmask_b32_e64 v3, v32, v3, s[8:9]
	v_cndmask_b32_e64 v4, v32, v4, s[10:11]
	v_cndmask_b32_e64 v5, v32, v5, s[12:13]
	v_cndmask_b32_e64 v6, v32, v6, s[14:15]
	v_cndmask_b32_e64 v7, v32, v7, s[16:17]
	v_cndmask_b32_e64 v8, v32, v8, s[18:19]
	v_cndmask_b32_e64 v9, v32, v9, s[22:23]
	v_cndmask_b32_e64 v10, v32, v10, s[24:25]
	v_cndmask_b32_e64 v11, v32, v11, s[26:27]
	v_cndmask_b32_e64 v12, v32, v12, s[28:29]
	v_cndmask_b32_e64 v13, v32, v13, s[30:31]
	v_cndmask_b32_e64 v14, v32, v14, s[34:35]
	v_cndmask_b32_e64 v15, v32, v15, s[36:37]
	v_accvgpr_write_b32 a80, v0
	v_accvgpr_write_b32 a81, v1
	v_accvgpr_write_b32 a82, v2
	v_accvgpr_write_b32 a83, v3
	v_accvgpr_write_b32 a84, v4
	v_accvgpr_write_b32 a85, v5
	v_accvgpr_write_b32 a86, v6
	v_accvgpr_write_b32 a87, v7
	v_accvgpr_write_b32 a88, v8
	v_accvgpr_write_b32 a89, v9
	v_accvgpr_write_b32 a90, v10
	v_accvgpr_write_b32 a91, v11
	v_accvgpr_write_b32 a92, v12
	v_accvgpr_write_b32 a93, v13
	v_accvgpr_write_b32 a94, v14
	v_accvgpr_write_b32 a95, v15
	s_mov_b64 s[40:41], s[70:71]
; DI float ex2(float x) { return __builtin_amdgcn_exp2f(x); }
; template <int DQK>
; DI void attn_item_c(const u16* __restrict__ Qp, int ldq, const u16* __restrict__ Kp, const u16* __restrict__ Vtp, int ldv,
;                     int nkt, int q0, float c, u16* Yp, int ldy, char* smem, bool dry) {
;     ...
;     float mx = fmaxf(s0[0], s1[0]);
; #pragma unroll
;     for (int e = 1; e < 16; ++e) mx = fmaxf(fmaxf(mx, s0[e]), s1[e]);
;     mx = fmaxf(mx, __shfl_xor(mx, 32));
;     if (__builtin_amdgcn_ballot_w64((mx - m) * c > 8.f) != 0ull) {
;       const float mn = fmaxf(m, mx);
;       const float alpha = ex2((m - mn) * c);
;       m = mn;
;       l *= alpha;
; #pragma unroll
;       for (int dt = 0; dt < 4; ++dt)
; #pragma unroll
;         for (int e = 0; e < 16; ++e) o[dt][e] *= alpha;
;     }
;     ...
;     l += ps;
.LBB0_296:
	s_or_b64 exec, exec, s[46:47]
	v_add_f32_e32 v162, 0, v162
	v_add_f32_e32 v162, v163, v162
	v_add_f32_e32 v162, v164, v162
	v_add_f32_e32 v162, v165, v162
	v_add_f32_e32 v162, v166, v162
	v_add_f32_e32 v162, v167, v162
	v_add_f32_e32 v162, v168, v162
	v_add_f32_e32 v162, v169, v162
	v_add_f32_e32 v162, v170, v162
	v_add_f32_e32 v162, v171, v162
	v_add_f32_e32 v162, v172, v162
	v_add_f32_e32 v162, v173, v162
	v_add_f32_e32 v162, v174, v162
	v_add_f32_e32 v162, v175, v162
	v_add_f32_e32 v162, v176, v162
	v_add_f32_e32 v162, v177, v162
	v_add_f32_e32 v162, v213, v162
	v_add_f32_e32 v162, v214, v162
	v_add_f32_e32 v162, v215, v162
	v_add_f32_e32 v129, v129, v162
	v_add_f32_e32 v129, v227, v129
	v_add_f32_e32 v129, v228, v129
	v_add_f32_e32 v129, v229, v129
	v_add_f32_e32 v129, v230, v129
	v_accvgpr_read_b32 v0, a64
	v_accvgpr_read_b32 v32, a80
	v_add_f32_e32 v129, v147, v129
	v_add_f32_e32 v129, v148, v129
	v_max_f32_e32 v147, v0, v0
	v_max_f32_e32 v148, v32, v32
	v_accvgpr_read_b32 v1, a65
	v_accvgpr_read_b32 v33, a81
	v_max_f32_e32 v147, v148, v147
	v_accvgpr_read_b32 v2, a66
	v_accvgpr_read_b32 v34, a82
	v_max3_f32 v147, v147, v33, v1
	v_accvgpr_read_b32 v3, a67
	v_accvgpr_read_b32 v35, a83
	v_max3_f32 v147, v147, v34, v2
	v_accvgpr_read_b32 v4, a68
	v_accvgpr_read_b32 v36, a84
	v_max3_f32 v147, v147, v35, v3
	v_accvgpr_read_b32 v5, a69
	v_accvgpr_read_b32 v37, a85
	v_max3_f32 v147, v147, v36, v4
	v_accvgpr_read_b32 v6, a70
	v_accvgpr_read_b32 v38, a86
	v_max3_f32 v147, v147, v37, v5
	v_accvgpr_read_b32 v7, a71
	v_accvgpr_read_b32 v39, a87
	v_max3_f32 v147, v147, v38, v6
	v_accvgpr_read_b32 v8, a72
	v_accvgpr_read_b32 v40, a88
	v_max3_f32 v147, v147, v39, v7
	v_accvgpr_read_b32 v9, a73
	v_accvgpr_read_b32 v41, a89
	v_max3_f32 v147, v147, v40, v8
	v_accvgpr_read_b32 v10, a74
	v_accvgpr_read_b32 v42, a90
	v_max3_f32 v147, v147, v41, v9
	v_accvgpr_read_b32 v11, a75
	v_accvgpr_read_b32 v43, a91
	v_max3_f32 v147, v147, v42, v10
	v_accvgpr_read_b32 v12, a76
	v_accvgpr_read_b32 v44, a92
	v_max3_f32 v147, v147, v43, v11
	v_accvgpr_read_b32 v13, a77
	v_accvgpr_read_b32 v45, a93
	v_max3_f32 v147, v147, v44, v12
	v_accvgpr_read_b32 v14, a78
	v_accvgpr_read_b32 v46, a94
	v_max3_f32 v147, v147, v45, v13
	v_accvgpr_read_b32 v15, a79
	v_accvgpr_read_b32 v47, a95
	v_max3_f32 v147, v147, v46, v14
	v_add_f32_e32 v129, v149, v129
	v_max3_f32 v147, v147, v47, v15
	v_add_f32_e32 v129, v218, v129
	ds_bpermute_b32 v148, v232, v147
	v_add_f32_e32 v129, v244, v129
	v_add_f32_e32 v129, v231, v129
	v_add_f32_e32 v129, v235, v129
	v_add_f32_e32 v129, v146, v129
	v_add_f32_e32 v248, v248, v129
	s_waitcnt lgkmcnt(0)
	v_max_f32_e32 v129, v148, v148
	v_max_f32_e32 v129, v147, v129
	v_sub_f32_e32 v146, v129, v216
	v_mul_f32_e32 v146, 0x3dd53b94, v146
	v_cmp_lt_f32_e32 vcc, s33, v146
	s_cbranch_vccz .LBB0_298
	v_accvgpr_read_b32 v16, a48
	v_accvgpr_read_b32 v63, a47
	v_accvgpr_read_b32 v79, a31
	v_accvgpr_read_b32 v95, a15
	v_accvgpr_read_b32 v17, a49
	v_accvgpr_read_b32 v18, a50
	v_accvgpr_read_b32 v19, a51
	v_accvgpr_read_b32 v20, a52
	v_accvgpr_read_b32 v21, a53
	v_accvgpr_read_b32 v22, a54
	v_accvgpr_read_b32 v23, a55
	v_accvgpr_read_b32 v24, a56
	v_accvgpr_read_b32 v25, a57
	v_accvgpr_read_b32 v26, a58
	v_accvgpr_read_b32 v27, a59
	v_accvgpr_read_b32 v28, a60
	v_accvgpr_read_b32 v29, a61
	v_accvgpr_read_b32 v30, a62
	v_accvgpr_read_b32 v31, a63
	v_accvgpr_read_b32 v62, a46
	v_accvgpr_read_b32 v61, a45
	v_accvgpr_read_b32 v60, a44
	v_accvgpr_read_b32 v59, a43
	v_accvgpr_read_b32 v58, a42
	v_accvgpr_read_b32 v57, a41
	v_accvgpr_read_b32 v56, a40
	v_accvgpr_read_b32 v55, a39
	v_accvgpr_read_b32 v54, a38
	v_accvgpr_read_b32 v53, a37
	v_accvgpr_read_b32 v52, a36
	v_accvgpr_read_b32 v51, a35
	v_accvgpr_read_b32 v50, a34
	v_accvgpr_read_b32 v49, a33
	v_accvgpr_read_b32 v48, a32
	v_accvgpr_read_b32 v78, a30
	v_accvgpr_read_b32 v77, a29
	v_accvgpr_read_b32 v76, a28
	v_accvgpr_read_b32 v75, a27
	v_accvgpr_read_b32 v74, a26
	v_accvgpr_read_b32 v73, a25
	v_accvgpr_read_b32 v72, a24
	v_accvgpr_read_b32 v71, a23
	v_accvgpr_read_b32 v70, a22
	v_accvgpr_read_b32 v69, a21
	v_accvgpr_read_b32 v68, a20
	v_accvgpr_read_b32 v67, a19
	v_accvgpr_read_b32 v66, a18
	v_accvgpr_read_b32 v65, a17
	v_accvgpr_read_b32 v64, a16
	v_accvgpr_read_b32 v94, a14
	v_accvgpr_read_b32 v93, a13
	v_accvgpr_read_b32 v92, a12
	v_accvgpr_read_b32 v91, a11
	v_accvgpr_read_b32 v90, a10
	v_accvgpr_read_b32 v89, a9
	v_accvgpr_read_b32 v88, a8
	v_accvgpr_read_b32 v87, a7
	v_accvgpr_read_b32 v86, a6
	v_accvgpr_read_b32 v85, a5
	v_accvgpr_read_b32 v84, a4
	v_accvgpr_read_b32 v83, a3
	v_accvgpr_read_b32 v82, a2
	v_accvgpr_read_b32 v81, a1
	v_accvgpr_read_b32 v80, a0
	v_max_f32_e32 v129, v129, v129
	v_max_f32_e32 v146, v216, v216
	v_max_f32_e32 v249, v146, v129
	v_sub_f32_e32 v129, v216, v249
	v_mul_f32_e32 v129, 0x3dd53b94, v129
	v_exp_f32_e32 v216, v129
	s_nop 0
	v_pk_mul_f32 v[30:31], v[30:31], v[216:217] op_sel_hi:[1,0]
	v_pk_mul_f32 v[80:81], v[80:81], v[216:217] op_sel_hi:[1,0]
	v_pk_mul_f32 v[64:65], v[64:65], v[216:217] op_sel_hi:[1,0]
	v_pk_mul_f32 v[48:49], v[48:49], v[216:217] op_sel_hi:[1,0]
	v_pk_mul_f32 v[28:29], v[28:29], v[216:217] op_sel_hi:[1,0]
	v_pk_mul_f32 v[26:27], v[26:27], v[216:217] op_sel_hi:[1,0]
	v_pk_mul_f32 v[24:25], v[24:25], v[216:217] op_sel_hi:[1,0]
	v_pk_mul_f32 v[22:23], v[22:23], v[216:217] op_sel_hi:[1,0]
	v_pk_mul_f32 v[20:21], v[20:21], v[216:217] op_sel_hi:[1,0]
	v_pk_mul_f32 v[18:19], v[18:19], v[216:217] op_sel_hi:[1,0]
	v_pk_mul_f32 v[16:17], v[16:17], v[216:217] op_sel_hi:[1,0]
	v_pk_mul_f32 v[94:95], v[94:95], v[216:217] op_sel_hi:[1,0]
	v_accvgpr_write_b32 a63, v31
; #define MFMA32(a, b, c) __builtin_amdgcn_mfma_f32_32x32x16_bf16((a), (b), (c), 0, 0, 0)
; DI float ex2(float x) { return __builtin_amdgcn_exp2f(x); }
; template <int DQK>
; DI void attn_item_c(const u16* __restrict__ Qp, int ldq, const u16* __restrict__ Kp, const u16* __restrict__ Vtp, int ldv,
;                     int nkt, int q0, float c, u16* Yp, int ldy, char* smem, bool dry) {
;     ...
; #pragma unroll
;       for (int dt = 0; dt < 4; ++dt)
; #pragma unroll
;         for (int e = 0; e < 16; ++e) o[dt][e] *= alpha;
;     }
;     const float mc = m * c;
; #pragma unroll
;     for (int e = 0; e < 16; ++e) { n0[e] = 0.f; n1[e] = 0.f; }
;     const u16* k0 = Ks + r * KLD + 8 * h;
;     bf16x8 ka[3][2];
;     ka[0][0] = *(const bf16x8*)(k0); ka[0][1] = *(const bf16x8*)(k0 + 32 * KLD);
;     ka[1][0] = *(const bf16x8*)(k0 + 16); ka[1][1] = *(const bf16x8*)(k0 + 32 * KLD + 16);
;     bf16x8 pf[4];
;     u32x4 pk[4];
;     float ps = 0.f;
; #pragma unroll
;     for (int ks = 0; ks < NKS; ++ks) {
;       if (ks + 2 < NKS) {
;         ka[(ks + 2) % 3][0] = *(const bf16x8*)(k0 + 16 * (ks + 2));
;         ka[(ks + 2) % 3][1] = *(const bf16x8*)(k0 + 32 * KLD + 16 * (ks + 2));
;       }
;       __builtin_amdgcn_sched_barrier(0);
;       n0 = MFMA32(ka[ks % 3][0], qf[ks], n0); n1 = MFMA32(ka[ks % 3][1], qf[ks], n1);
;       {
;         constexpr int dummy0 = 0; (void)dummy0;
;         const int e_lo = (32 * ks) / NKS, e_hi = (32 * (ks + 1)) / NKS;
; #pragma unroll
;         for (int q = 0; q < 3; ++q) {
;           const int e = e_lo + q;
;           if (e < e_hi) {
;             if (e < 16) { s0[e & 15] = ex2(fmaf(s0[e & 15], c, -mc)); ps += s0[e & 15]; }
;             else        { s1[e & 15] = ex2(fmaf(s1[e & 15], c, -mc)); ps += s1[e & 15]; }
;           }
;         }
;       }
	v_pk_mul_f32 v[92:93], v[92:93], v[216:217] op_sel_hi:[1,0]
	v_pk_mul_f32 v[90:91], v[90:91], v[216:217] op_sel_hi:[1,0]
	v_pk_mul_f32 v[88:89], v[88:89], v[216:217] op_sel_hi:[1,0]
	v_pk_mul_f32 v[86:87], v[86:87], v[216:217] op_sel_hi:[1,0]
	v_pk_mul_f32 v[84:85], v[84:85], v[216:217] op_sel_hi:[1,0]
	v_pk_mul_f32 v[82:83], v[82:83], v[216:217] op_sel_hi:[1,0]
	v_pk_mul_f32 v[78:79], v[78:79], v[216:217] op_sel_hi:[1,0]
	v_accvgpr_write_b32 a0, v80
	v_pk_mul_f32 v[76:77], v[76:77], v[216:217] op_sel_hi:[1,0]
	v_pk_mul_f32 v[74:75], v[74:75], v[216:217] op_sel_hi:[1,0]
	v_pk_mul_f32 v[72:73], v[72:73], v[216:217] op_sel_hi:[1,0]
	v_pk_mul_f32 v[70:71], v[70:71], v[216:217] op_sel_hi:[1,0]
	v_pk_mul_f32 v[68:69], v[68:69], v[216:217] op_sel_hi:[1,0]
	v_pk_mul_f32 v[66:67], v[66:67], v[216:217] op_sel_hi:[1,0]
	v_pk_mul_f32 v[62:63], v[62:63], v[216:217] op_sel_hi:[1,0]
	v_accvgpr_write_b32 a16, v64
	v_pk_mul_f32 v[60:61], v[60:61], v[216:217] op_sel_hi:[1,0]
	v_pk_mul_f32 v[58:59], v[58:59], v[216:217] op_sel_hi:[1,0]
	v_pk_mul_f32 v[56:57], v[56:57], v[216:217] op_sel_hi:[1,0]
	v_pk_mul_f32 v[54:55], v[54:55], v[216:217] op_sel_hi:[1,0]
	v_pk_mul_f32 v[52:53], v[52:53], v[216:217] op_sel_hi:[1,0]
	v_pk_mul_f32 v[50:51], v[50:51], v[216:217] op_sel_hi:[1,0]
	v_accvgpr_write_b32 a62, v30
	v_accvgpr_write_b32 a32, v48
	v_accvgpr_write_b32 a61, v29
	v_accvgpr_write_b32 a60, v28
	v_accvgpr_write_b32 a59, v27
	v_accvgpr_write_b32 a58, v26
	v_accvgpr_write_b32 a57, v25
	v_accvgpr_write_b32 a56, v24
	v_accvgpr_write_b32 a55, v23
	v_accvgpr_write_b32 a54, v22
	v_accvgpr_write_b32 a53, v21
	v_accvgpr_write_b32 a52, v20
	v_accvgpr_write_b32 a51, v19
	v_accvgpr_write_b32 a50, v18
	v_accvgpr_write_b32 a49, v17
	v_accvgpr_write_b32 a48, v16
	v_pk_mul_f32 v[16:17], v[248:249], v[216:217]
	v_accvgpr_write_b32 a1, v81
	v_accvgpr_write_b32 a2, v82
	v_accvgpr_write_b32 a3, v83
	v_accvgpr_write_b32 a4, v84
	v_accvgpr_write_b32 a5, v85
	v_accvgpr_write_b32 a6, v86
	v_accvgpr_write_b32 a7, v87
	v_accvgpr_write_b32 a8, v88
	v_accvgpr_write_b32 a9, v89
	v_accvgpr_write_b32 a10, v90
	v_accvgpr_write_b32 a11, v91
	v_accvgpr_write_b32 a12, v92
	v_accvgpr_write_b32 a13, v93
	v_accvgpr_write_b32 a14, v94
	v_accvgpr_write_b32 a15, v95
	v_accvgpr_write_b32 a17, v65
	v_accvgpr_write_b32 a18, v66
	v_accvgpr_write_b32 a19, v67
	v_accvgpr_write_b32 a20, v68
	v_accvgpr_write_b32 a21, v69
	v_accvgpr_write_b32 a22, v70
	v_accvgpr_write_b32 a23, v71
	v_accvgpr_write_b32 a24, v72
	v_accvgpr_write_b32 a25, v73
	v_accvgpr_write_b32 a26, v74
	v_accvgpr_write_b32 a27, v75
	v_accvgpr_write_b32 a28, v76
	v_accvgpr_write_b32 a29, v77
	v_accvgpr_write_b32 a30, v78
	v_accvgpr_write_b32 a31, v79
	v_accvgpr_write_b32 a33, v49
	v_accvgpr_write_b32 a34, v50
	v_accvgpr_write_b32 a35, v51
	v_accvgpr_write_b32 a36, v52
	v_accvgpr_write_b32 a37, v53
	v_accvgpr_write_b32 a38, v54
	v_accvgpr_write_b32 a39, v55
	v_accvgpr_write_b32 a40, v56
	v_accvgpr_write_b32 a41, v57
	v_accvgpr_write_b32 a42, v58
	v_accvgpr_write_b32 a43, v59
	v_accvgpr_write_b32 a44, v60
	v_accvgpr_write_b32 a45, v61
	v_accvgpr_write_b32 a46, v62
	v_accvgpr_write_b32 a47, v63
	v_mov_b32_e32 v216, v249
	v_mov_b64_e32 v[248:249], v[16:17]
.LBB0_298:
	ds_read_b128 v[16:19], v219 offset:44032
	ds_read_b128 v[20:23], v219 offset:44064
	ds_read_b128 v[24:27], v219 offset:56832
	ds_read_b128 v[28:31], v219 offset:44096
	ds_read_b128 v[48:51], v219 offset:56864
	ds_read_b128 v[52:55], v219 offset:56896
	v_accvgpr_read_b32 v56, a238
	v_cmp_le_i32_e32 vcc, s20, v56
	s_waitcnt lgkmcnt(5)
	v_mfma_f32_32x32x16_bf16 a[80:95], v[16:19], v[96:99], 0
	v_fmamk_f32 v16, v32, 0x3dd53b94, v249
	v_fmamk_f32 v17, v33, 0x3dd53b94, v249
	v_exp_f32_e32 v16, v16
	v_exp_f32_e32 v17, v17
	s_waitcnt lgkmcnt(3)
	v_mfma_f32_32x32x16_bf16 a[64:79], v[24:27], v[96:99], 0
	ds_read_b128 v[24:27], v219 offset:44128
	ds_read_b128 v[56:59], v219 offset:56928
	v_mfma_f32_32x32x16_bf16 a[80:95], v[20:23], v[100:103], a[80:95]
	v_fmamk_f32 v18, v34, 0x3dd53b94, v249
	v_fmamk_f32 v19, v35, 0x3dd53b94, v249
	v_fmamk_f32 v20, v36, 0x3dd53b94, v249
	v_exp_f32_e32 v18, v18
	v_exp_f32_e32 v19, v19
	v_exp_f32_e32 v20, v20
	s_waitcnt lgkmcnt(3)
	v_mfma_f32_32x32x16_bf16 a[64:79], v[48:51], v[100:103], a[64:79]
	ds_read_b128 v[32:35], v219 offset:44160
	ds_read_b128 v[48:51], v219 offset:56960
	v_mfma_f32_32x32x16_bf16 a[80:95], v[28:31], v[104:107], a[80:95]
	v_fmamk_f32 v21, v37, 0x3dd53b94, v249
	v_fmamk_f32 v22, v38, 0x3dd53b94, v249
	v_fmamk_f32 v23, v39, 0x3dd53b94, v249
	v_exp_f32_e32 v21, v21
	v_exp_f32_e32 v22, v22
	v_exp_f32_e32 v23, v23
	s_waitcnt lgkmcnt(4)
	v_mfma_f32_32x32x16_bf16 a[64:79], v[52:55], v[104:107], a[64:79]
	ds_read_b128 v[36:39], v219 offset:44192
	ds_read_b128 v[52:55], v219 offset:56992
	s_waitcnt lgkmcnt(5)
	v_mfma_f32_32x32x16_bf16 a[80:95], v[24:27], v[108:111], a[80:95]
	v_fmamk_f32 v24, v40, 0x3dd53b94, v249
	v_fmamk_f32 v25, v41, 0x3dd53b94, v249
	v_exp_f32_e32 v24, v24
	v_exp_f32_e32 v25, v25
	s_waitcnt lgkmcnt(4)
	v_mfma_f32_32x32x16_bf16 a[64:79], v[56:59], v[108:111], a[64:79]
	ds_read_b128 v[56:59], v219 offset:44224
	ds_read_b128 v[60:63], v219 offset:57024
	s_waitcnt lgkmcnt(5)
	v_mfma_f32_32x32x16_bf16 a[80:95], v[32:35], v[112:115], a[80:95]
	v_fmamk_f32 v26, v42, 0x3dd53b94, v249
	v_fmamk_f32 v27, v43, 0x3dd53b94, v249
	v_fmamk_f32 v28, v44, 0x3dd53b94, v249
	v_exp_f32_e32 v26, v26
	v_exp_f32_e32 v27, v27
	v_exp_f32_e32 v28, v28
	s_waitcnt lgkmcnt(4)
	v_mfma_f32_32x32x16_bf16 a[64:79], v[48:51], v[112:115], a[64:79]
	ds_read_b128 v[32:35], v219 offset:44256
	ds_read_b128 v[40:43], v219 offset:57056
	s_waitcnt lgkmcnt(5)
; #define MFMA32(a, b, c) __builtin_amdgcn_mfma_f32_32x32x16_bf16((a), (b), (c), 0, 0, 0)
; DI unsigned pack2(float a, float b) { f2_t v = {a, b}; bf2_t r = __builtin_convertvector(v, bf2_t); return __builtin_bit_cast(unsigned, r); }
; DI float ex2(float x) { return __builtin_amdgcn_exp2f(x); }
; template <int DQK>
; DI void attn_item_c(const u16* __restrict__ Qp, int ldq, const u16* __restrict__ Kp, const u16* __restrict__ Vtp, int ldv,
;                     int nkt, int q0, float c, u16* Yp, int ldy, char* smem, bool dry) {
;     ...
; #pragma unroll
;     for (int ks = 0; ks < NKS; ++ks) {
;       if (ks + 2 < NKS) {
;         ka[(ks + 2) % 3][0] = *(const bf16x8*)(k0 + 16 * (ks + 2));
;         ka[(ks + 2) % 3][1] = *(const bf16x8*)(k0 + 32 * KLD + 16 * (ks + 2));
;       }
;       __builtin_amdgcn_sched_barrier(0);
;       n0 = MFMA32(ka[ks % 3][0], qf[ks], n0); n1 = MFMA32(ka[ks % 3][1], qf[ks], n1);
;       {
;         constexpr int dummy0 = 0; (void)dummy0;
;         const int e_lo = (32 * ks) / NKS, e_hi = (32 * (ks + 1)) / NKS;
; #pragma unroll
;         for (int q = 0; q < 3; ++q) {
;           const int e = e_lo + q;
;           if (e < e_hi) {
;             if (e < 16) { s0[e & 15] = ex2(fmaf(s0[e & 15], c, -mc)); ps += s0[e & 15]; }
;             else        { s1[e & 15] = ex2(fmaf(s1[e & 15], c, -mc)); ps += s1[e & 15]; }
;           }
;         }
;       }
;       if (ks == 3)  { pk[0].x = pack2(s0[0], s0[1]);  pk[0].y = pack2(s0[2], s0[3]);   pk[0].z = pack2(s0[4], s0[5]);   pk[0].w = pack2(s0[6], s0[7]); }
;       if (ks == 6)  { pk[1].x = pack2(s0[8], s0[9]);  pk[1].y = pack2(s0[10], s0[11]); pk[1].z = pack2(s0[12], s0[13]); pk[1].w = pack2(s0[14], s0[15]); }
;       if (ks == 9)  { pk[2].x = pack2(s1[0], s1[1]);  pk[2].y = pack2(s1[2], s1[3]);   pk[2].z = pack2(s1[4], s1[5]);   pk[2].w = pack2(s1[6], s1[7]); }
;       if (ks == NKS - 1) { pk[3].x = pack2(s1[8], s1[9]);  pk[3].y = pack2(s1[10], s1[11]); pk[3].z = pack2(s1[12], s1[13]); pk[3].w = pack2(s1[14], s1[15]); }
;       __builtin_amdgcn_sched_barrier(0);
;     }
;     l += ps;
; #pragma unroll
;     for (int i = 0; i < 4; ++i) pf[i] = __builtin_bit_cast(bf16x8, pk[i]);
;     if (active) {
	v_mfma_f32_32x32x16_bf16 a[80:95], v[36:39], v[116:119], a[80:95]
	v_fmamk_f32 v29, v45, 0x3dd53b94, v249
	v_fmamk_f32 v30, v46, 0x3dd53b94, v249
	v_fmamk_f32 v31, v47, 0x3dd53b94, v249
	v_exp_f32_e32 v29, v29
	v_exp_f32_e32 v30, v30
	v_exp_f32_e32 v31, v31
	s_waitcnt lgkmcnt(4)
	v_mfma_f32_32x32x16_bf16 a[64:79], v[52:55], v[116:119], a[64:79]
	ds_read_b128 v[36:39], v219 offset:44288
	ds_read_b128 v[44:47], v219 offset:57088
	s_waitcnt lgkmcnt(5)
	v_mfma_f32_32x32x16_bf16 a[80:95], v[56:59], v[120:123], a[80:95]
	v_fmamk_f32 v0, v0, 0x3dd53b94, v249
	v_fmamk_f32 v1, v1, 0x3dd53b94, v249
	v_exp_f32_e32 v0, v0
	v_exp_f32_e32 v1, v1
	s_waitcnt lgkmcnt(4)
	v_mfma_f32_32x32x16_bf16 a[64:79], v[60:63], v[120:123], a[64:79]
	ds_read_b128 v[48:51], v219 offset:44320
	ds_read_b128 v[52:55], v219 offset:57120
	s_waitcnt lgkmcnt(5)
	v_mfma_f32_32x32x16_bf16 a[80:95], v[32:35], v[124:127], a[80:95]
	v_fmamk_f32 v2, v2, 0x3dd53b94, v249
	v_fmamk_f32 v3, v3, 0x3dd53b94, v249
	v_fmamk_f32 v4, v4, 0x3dd53b94, v249
	v_exp_f32_e32 v2, v2
	v_exp_f32_e32 v3, v3
	v_exp_f32_e32 v4, v4
	s_waitcnt lgkmcnt(4)
	v_mfma_f32_32x32x16_bf16 a[64:79], v[40:43], v[124:127], a[64:79]
	ds_read_b128 v[32:35], v219 offset:44352
	ds_read_b128 v[40:43], v219 offset:57152
	s_waitcnt lgkmcnt(5)
	v_mfma_f32_32x32x16_bf16 a[80:95], v[36:39], v[130:133], a[80:95]
	v_fmamk_f32 v5, v5, 0x3dd53b94, v249
	v_fmamk_f32 v6, v6, 0x3dd53b94, v249
	v_fmamk_f32 v7, v7, 0x3dd53b94, v249
	v_exp_f32_e32 v5, v5
	v_exp_f32_e32 v6, v6
	v_exp_f32_e32 v7, v7
	s_waitcnt lgkmcnt(4)
	v_mfma_f32_32x32x16_bf16 a[64:79], v[44:47], v[130:133], a[64:79]
	ds_read_b128 v[36:39], v219 offset:44384
	ds_read_b128 v[44:47], v219 offset:57184
	s_waitcnt lgkmcnt(5)
	v_mfma_f32_32x32x16_bf16 a[80:95], v[48:51], v[134:137], a[80:95]
	v_fmamk_f32 v8, v8, 0x3dd53b94, v249
	v_fmamk_f32 v9, v9, 0x3dd53b94, v249
	v_exp_f32_e32 v8, v8
	v_exp_f32_e32 v9, v9
	s_waitcnt lgkmcnt(4)
	v_mfma_f32_32x32x16_bf16 a[64:79], v[52:55], v[134:137], a[64:79]
	s_waitcnt lgkmcnt(3)
	v_mfma_f32_32x32x16_bf16 a[80:95], v[32:35], v[138:141], a[80:95]
	v_fmamk_f32 v10, v10, 0x3dd53b94, v249
	v_fmamk_f32 v11, v11, 0x3dd53b94, v249
	v_fmamk_f32 v12, v12, 0x3dd53b94, v249
	v_exp_f32_e32 v10, v10
	v_exp_f32_e32 v11, v11
	v_exp_f32_e32 v12, v12
	s_waitcnt lgkmcnt(2)
	v_mfma_f32_32x32x16_bf16 a[64:79], v[40:43], v[138:141], a[64:79]
	s_waitcnt lgkmcnt(1)
	v_mfma_f32_32x32x16_bf16 a[80:95], v[36:39], v[142:145], a[80:95]
	v_fmamk_f32 v13, v13, 0x3dd53b94, v249
	v_fmamk_f32 v14, v14, 0x3dd53b94, v249
	v_fmamk_f32 v15, v15, 0x3dd53b94, v249
	v_exp_f32_e32 v13, v13
	v_exp_f32_e32 v14, v14
	v_exp_f32_e32 v15, v15
	s_waitcnt lgkmcnt(0)
	v_mfma_f32_32x32x16_bf16 a[64:79], v[44:47], v[142:145], a[64:79]
	s_and_saveexec_b64 s[0:1], vcc
	s_xor_b64 s[0:1], exec, s[0:1]
	s_cbranch_execz .LBB0_300
; #define MFMA32(a, b, c) __builtin_amdgcn_mfma_f32_32x32x16_bf16((a), (b), (c), 0, 0, 0)
; template <int DQK>
; DI void attn_item_c(const u16* __restrict__ Qp, int ldq, const u16* __restrict__ Kp, const u16* __restrict__ Vtp, int ldv,
;                     int nkt, int q0, float c, u16* Yp, int ldy, char* smem, bool dry) {
;     ...
;   auto gloadK = [&](u32x4* ks_, int j) {
;     const u16* kg = Kp + (size_t)(j + 1) * 64 * DQK;
; #pragma unroll
;     for (int i = 0; i < NKC; ++i) ks_[i] = *(const u32x4*)(kg + (size_t)(tid + 256 * i) * 8);
;   };
;   auto gloadV = [&](u32x4* vs_, int j) {
; #pragma unroll
;     for (int i = 0; i < 4; ++i) vs_[i] = *(const u32x4*)(Vtp + (size_t)j * 8192 + (size_t)(tid + 256 * i) * 8);
;   };
;   auto lstoreK = [&](const u32x4* ks_, u16* Lb) {
; #pragma unroll
;     for (int i = 0; i < NKC; ++i) *(u32x4*)(Lb + kso[i]) = ks_[i];
;   };
;   auto lstoreV = [&](const u32x4* vs_, u16* Lb) {
; #pragma unroll
;     for (int i = 0; i < 4; ++i) {
;       u16* dst = Lb + vso + (32 * i) * 72;
;       u32x2 lo = {vs_[i].x, vs_[i].y}, hi = {vs_[i].z, vs_[i].w};
;       *(u32x2*)dst = lo; *(u32x2*)(dst + 8) = hi;
;     }
;   };
;     ...
;     for (int i = 0; i < 4; ++i) pf[i] = __builtin_bit_cast(bf16x8, pk[i]);
;     if (active) {
;       const u16* v0 = Vs + r * 72 + 8 * h;
;       bf16x8 va[2][4];
; #pragma unroll
;       for (int dt = 0; dt < 4; ++dt) va[0][dt] = *(const bf16x8*)(v0 + (32 * dt) * 72);
; #pragma unroll
;       for (int kk = 0; kk < 4; ++kk) {
;         if (kk < 3) {
; #pragma unroll
;           for (int dt = 0; dt < 4; ++dt) va[(kk + 1) & 1][dt] = *(const bf16x8*)(v0 + (32 * dt) * 72 + 16 * (kk + 1));
;         }
;         __builtin_amdgcn_sched_barrier(0);
; #pragma unroll
;         for (int dt = 0; dt < 4; ++dt) o[dt] = MFMA32(va[kk & 1][dt], pf[kk], o[dt]);
;         if (kk == 0) lstoreK(wk, Ln);
;         if (kk == 1) lstoreV(wv, Ln);
;         if (kk == 2) gloadK(wk, kt + 3);
;         if (kk == 3) gloadV(wv, kt + 3);
;         __builtin_amdgcn_sched_barrier(0);
;       }
	ds_read_b128 v[48:51], v250
	ds_read_b128 v[52:55], v250 offset:32
	ds_read_b128 v[56:59], v250 offset:4608
	ds_read_b128 v[60:63], v250 offset:4640
	ds_read_b128 v[64:67], v250 offset:9216
	ds_read_b128 v[68:71], v250 offset:9248
	ds_read_b128 v[72:75], v250 offset:13824
	ds_read_b128 v[76:79], v250 offset:13856
	s_add_i32 s20, s44, 6
	s_add_i32 s8, s44, 7
	v_cvt_pk_bf16_f32 v32, v8, v9
	v_cvt_pk_bf16_f32 v33, v10, v11
	v_cvt_pk_bf16_f32 v34, v12, v13
	v_cvt_pk_bf16_f32 v35, v14, v15
	v_cvt_pk_bf16_f32 v36, v0, v1
	v_cvt_pk_bf16_f32 v37, v2, v3
	v_cvt_pk_bf16_f32 v38, v4, v5
	v_cvt_pk_bf16_f32 v39, v6, v7
	v_cvt_pk_bf16_f32 v40, v24, v25
	v_cvt_pk_bf16_f32 v41, v26, v27
	v_cvt_pk_bf16_f32 v42, v28, v29
	v_cvt_pk_bf16_f32 v43, v30, v31
	v_cvt_pk_bf16_f32 v44, v16, v17
	v_cvt_pk_bf16_f32 v45, v18, v19
	v_cvt_pk_bf16_f32 v46, v20, v21
	v_cvt_pk_bf16_f32 v47, v22, v23
	s_lshl_b64 s[6:7], s[20:21], 14
	s_mul_hi_u32 s9, s8, 0x6000
	s_mulk_i32 s8, 0x6000
	s_waitcnt lgkmcnt(7)
	v_mfma_f32_32x32x16_bf16 a[0:15], v[48:51], v[44:47], a[0:15]
	s_waitcnt vmcnt(10)
	ds_write_b128 v221, a[156:159]
	ds_write_b128 v222, a[164:167]
	ds_write_b128 v223, a[172:175]
	ds_write_b128 v224, a[180:183]
	ds_write_b128 v225, a[188:191]
	ds_write_b128 v226, a[192:195]
	s_waitcnt lgkmcnt(11)
	v_mfma_f32_32x32x16_bf16 a[16:31], v[56:59], v[44:47], a[16:31]
	s_waitcnt lgkmcnt(9)
	v_mfma_f32_32x32x16_bf16 a[32:47], v[64:67], v[44:47], a[32:47]
	s_waitcnt lgkmcnt(7)
	v_mfma_f32_32x32x16_bf16 a[48:63], v[72:75], v[44:47], a[48:63]
	ds_read_b128 v[44:47], v250 offset:64
	ds_read_b128 v[48:51], v250 offset:4672
	ds_read_b128 v[56:59], v250 offset:9280
	ds_read_b128 v[64:67], v250 offset:13888
	v_mfma_f32_32x32x16_bf16 a[0:15], v[52:55], v[40:43], a[0:15]
	v_accvgpr_read_b32 v52, a229
	ds_write2_b64 v52, v[190:191], v[192:193] offset0:128 offset1:130
	v_accvgpr_read_b32 v52, a234
	ds_write2_b64 v52, v[202:203], v[204:205] offset0:192 offset1:194
	v_accvgpr_read_b32 v52, a235
	ds_write2_b64 v52, v[198:199], v[200:201] offset1:2
	v_accvgpr_read_b32 v52, a236
	v_mfma_f32_32x32x16_bf16 a[16:31], v[60:63], v[40:43], a[16:31]
	ds_write2_b64 v52, v[206:207], v[208:209] offset0:64 offset1:66
	v_mfma_f32_32x32x16_bf16 a[32:47], v[68:71], v[40:43], a[32:47]
	s_waitcnt lgkmcnt(14)
	v_mfma_f32_32x32x16_bf16 a[48:63], v[76:79], v[40:43], a[48:63]
	ds_read_b128 v[40:43], v250 offset:96
	ds_read_b128 v[52:55], v250 offset:4704
	ds_read_b128 v[60:63], v250 offset:9312
	ds_read_b128 v[68:71], v250 offset:13920
	s_add_u32 s8, s94, s8
	s_addc_u32 s9, s95, s9
	s_waitcnt lgkmcnt(11)
	v_mfma_f32_32x32x16_bf16 a[0:15], v[44:47], v[36:39], a[0:15]
	v_lshl_add_u64 v[44:45], s[8:9], 0, v[236:237]
	v_lshl_add_u64 v[46:47], s[8:9], 0, v[238:239]
	global_load_dwordx4 a[120:123], v[44:45], off
	global_load_dwordx4 a[124:127], v[46:47], off
	v_lshl_add_u64 v[44:45], s[8:9], 0, v[240:241]
	v_lshl_add_u64 v[46:47], s[8:9], 0, v[242:243]
	global_load_dwordx4 a[132:135], v[44:45], off
	global_load_dwordx4 a[136:139], v[46:47], off
	v_accvgpr_read_b32 v44, a230
	v_accvgpr_read_b32 v45, a231
	v_accvgpr_read_b32 v46, a232
	v_lshl_add_u64 v[44:45], s[8:9], 0, v[44:45]
	v_accvgpr_read_b32 v47, a233
	v_lshl_add_u64 v[46:47], s[8:9], 0, v[46:47]
	global_load_dwordx4 a[140:143], v[44:45], off
	global_load_dwordx4 a[144:147], v[46:47], off
	s_waitcnt lgkmcnt(10)
	v_mfma_f32_32x32x16_bf16 a[16:31], v[48:51], v[36:39], a[16:31]
	s_waitcnt lgkmcnt(9)
	v_mfma_f32_32x32x16_bf16 a[32:47], v[56:59], v[36:39], a[32:47]
	s_waitcnt lgkmcnt(8)
	v_mfma_f32_32x32x16_bf16 a[48:63], v[64:67], v[36:39], a[48:63]
	s_add_u32 s6, s60, s6
	s_addc_u32 s7, s61, s7
	s_waitcnt lgkmcnt(3)
	v_mfma_f32_32x32x16_bf16 a[0:15], v[40:43], v[32:35], a[0:15]
	s_waitcnt lgkmcnt(2)
	v_mfma_f32_32x32x16_bf16 a[16:31], v[52:55], v[32:35], a[16:31]
	s_waitcnt lgkmcnt(1)
	v_mfma_f32_32x32x16_bf16 a[32:47], v[60:63], v[32:35], a[32:47]
	s_waitcnt lgkmcnt(0)
	v_mfma_f32_32x32x16_bf16 a[48:63], v[68:71], v[32:35], a[48:63]
	v_lshl_add_u64 v[32:33], s[6:7], 0, v[236:237]
	global_load_dwordx4 a[244:247], v[32:33], off
	v_lshl_add_u64 v[32:33], s[6:7], 0, v[238:239]
	global_load_dwordx4 v[170:173], v[32:33], off
	v_lshl_add_u64 v[32:33], s[6:7], 0, v[240:241]
	global_load_dwordx4 v[166:169], v[32:33], off
	v_lshl_add_u64 v[32:33], s[6:7], 0, v[242:243]
	global_load_dwordx4 v[174:177], v[32:33], off
